# pooling phase rewritten by hand as a sliding-window pass: each lane walks 32 consecutive rows, adds the new row and subtracts the oldest (f32), instead of reloading and re-summing the whole trailing w
# speedup vs baseline: 1.0067x; 1.0035x over previous
; __device__ __forceinline__ float bf_lo(unsigned w) { return __uint_as_float(w << 16); }
; __device__ __forceinline__ float bf_hi(unsigned w) { return __uint_as_float(w & 0xffff0000u); }
; template <int W> __device__ __forceinline__ v4u pool_window(const bf16* up, int t) {
;     v4u q[W];
; #pragma unroll
;     for (int j = 0; j < W; ++j) q[j] = *(const v4u*)(up - (size_t)((j <= t) ? j : 0) * 512);
;     float acc[8];
; #pragma unroll
;     for (int e = 0; e < 8; ++e) acc[e] = 0.f;
; #pragma unroll
;     for (int j = 0; j < W; ++j) { const float wgt = (j <= t) ? 1.f : 0.f;
;         acc[0] += wgt * pg8::bf_lo(q[j].x); acc[1] += wgt * pg8::bf_hi(q[j].x); acc[2] += wgt * pg8::bf_lo(q[j].y); acc[3] += wgt * pg8::bf_hi(q[j].y);
;         acc[4] += wgt * pg8::bf_lo(q[j].z); acc[5] += wgt * pg8::bf_hi(q[j].z); acc[6] += wgt * pg8::bf_lo(q[j].w); acc[7] += wgt * pg8::bf_hi(q[j].w); }
; __global__ void __launch_bounds__(NWAVES * 64, 2) hybrid_fwd(Args a) {
;     ...
;         PHASE_IDS;
;         for (int wi = gw; wi < M; wi += NGW) {
;             const int rq = wi >> 2, gp = ((wi & 3) + (wi >> 11)) & 3;
;             const int row = 4 * rq + (lane >> 4), t = row & (SEQ - 1);
;             const bf16* up = Ub + (size_t)row * 512 + gp * 128 + (lane & 15) * 8;
;             v4u o;
;             if (gp == 0) o = pool_window<2>(up, t); else if (gp == 1) o = pool_window<4>(up, t); else if (gp == 2) o = pool_window<8>(up, t); else o = pool_window<16>(up, t);
.LBB0_266:
	v_writelane_b32 v255, s10, 4
	s_nop 1
	v_writelane_b32 v255, s11, 5
	s_or_b64 exec, exec, s[2:3]
	v_mov_b32_e32 v0, v190
	s_add_u32 s84, s74, 0x37000000
	s_barrier
	s_addc_u32 s85, s75, 0
	v_readfirstlane_b32 s0, v0
	s_ashr_i32 s0, s0, 6
	v_writelane_b32 v255, s98, 6
	s_add_i32 s0, s0, s87
	s_cmp_gt_i32 s0, 0xffff
	v_writelane_b32 v255, s99, 7
	v_and_b32_e32 v50, 63, v0
	s_cbranch_scc1 .LBB0_280
	s_and_b32 s5, s0, 3
	s_lshr_b32 s6, s0, 2
	s_lshl_b32 s6, s6, 7
	v_lshrrev_b32_e32 v2, 4, v50
	v_lshl_add_u32 v2, v2, 5, s6
	v_and_b32_e32 v3, 15, v50
	v_lshlrev_b32_e32 v3, 4, v3
	s_lshl_b32 s7, s5, 8
	v_lshl_add_u32 v0, v2, 10, v3
	v_add_u32_e32 v0, s7, v0
	s_lshl_b32 s7, s5, 24
	v_lshl_add_u32 v1, v2, 8, v3
	v_add_u32_e32 v1, s7, v1
	v_and_b32_e32 v2, 0xfff, v2
	v_mov_b32_e32 v5, 0
	s_cmp_eq_u32 s5, 0
	s_cbranch_scc1 .Lpool_w2
	s_cmp_eq_u32 s5, 1
	s_cbranch_scc1 .Lpool_w4
	s_cmp_eq_u32 s5, 2
	s_cbranch_scc1 .Lpool_w8
.Lpool_w16:
	s_mov_b32 s4, 0
.Lpool_pass_w16:
	v_mov_b32_e32 v64, 0
	v_mov_b32_e32 v65, 0
	v_mov_b32_e32 v66, 0
	v_mov_b32_e32 v67, 0
	v_mov_b32_e32 v68, 0
	v_mov_b32_e32 v69, 0
	v_mov_b32_e32 v70, 0
	v_mov_b32_e32 v71, 0
	v_mov_b32_e32 v72, 0
	v_mov_b32_e32 v73, 0
	v_mov_b32_e32 v74, 0
	v_mov_b32_e32 v75, 0
	v_mov_b32_e32 v76, 0
	v_mov_b32_e32 v77, 0
	v_mov_b32_e32 v78, 0
	v_mov_b32_e32 v79, 0
	v_mov_b32_e32 v80, 0
	v_mov_b32_e32 v81, 0
	v_mov_b32_e32 v82, 0
	v_mov_b32_e32 v83, 0
	v_mov_b32_e32 v84, 0
	v_mov_b32_e32 v85, 0
	v_mov_b32_e32 v86, 0
	v_mov_b32_e32 v87, 0
	v_mov_b32_e32 v88, 0
	v_mov_b32_e32 v89, 0
	v_mov_b32_e32 v90, 0
	v_mov_b32_e32 v91, 0
	v_mov_b32_e32 v92, 0
	v_mov_b32_e32 v93, 0
	v_mov_b32_e32 v94, 0
	v_mov_b32_e32 v95, 0
	v_mov_b32_e32 v96, 0
	v_mov_b32_e32 v97, 0
	v_mov_b32_e32 v98, 0
	v_mov_b32_e32 v99, 0
	v_mov_b32_e32 v100, 0
	v_mov_b32_e32 v101, 0
	v_mov_b32_e32 v102, 0
	v_mov_b32_e32 v103, 0
	v_mov_b32_e32 v104, 0
	v_mov_b32_e32 v105, 0
	v_mov_b32_e32 v106, 0
	v_mov_b32_e32 v107, 0
	v_mov_b32_e32 v108, 0
	v_mov_b32_e32 v109, 0
	v_mov_b32_e32 v110, 0
	v_mov_b32_e32 v111, 0
	v_mov_b32_e32 v112, 0
	v_mov_b32_e32 v113, 0
	v_mov_b32_e32 v114, 0
	v_mov_b32_e32 v115, 0
	v_mov_b32_e32 v116, 0
	v_mov_b32_e32 v117, 0
	v_mov_b32_e32 v118, 0
	v_mov_b32_e32 v119, 0
	v_mov_b32_e32 v120, 0
	v_mov_b32_e32 v121, 0
	v_mov_b32_e32 v122, 0
	v_mov_b32_e32 v123, 0
	v_cmp_ne_u32_e32 vcc, 0, v2
	s_and_saveexec_b64 s[2:3], vcc
	v_subrev_u32_e32 v3, 0x4000, v0
	global_load_dwordx4 v[64:67], v3, s[34:35] offset:1024
	global_load_dwordx4 v[68:71], v3, s[34:35] offset:2048
	global_load_dwordx4 v[72:75], v3, s[34:35] offset:3072
	v_subrev_u32_e32 v3, 0x3000, v0
	global_load_dwordx4 v[76:79], v3, s[34:35]
	global_load_dwordx4 v[80:83], v3, s[34:35] offset:1024
	global_load_dwordx4 v[84:87], v3, s[34:35] offset:2048
	global_load_dwordx4 v[88:91], v3, s[34:35] offset:3072
	v_subrev_u32_e32 v3, 0x2000, v0
	global_load_dwordx4 v[92:95], v3, s[34:35]
	global_load_dwordx4 v[96:99], v3, s[34:35] offset:1024
	global_load_dwordx4 v[100:103], v3, s[34:35] offset:2048
	global_load_dwordx4 v[104:107], v3, s[34:35] offset:3072
	v_subrev_u32_e32 v3, 0x1000, v0
	global_load_dwordx4 v[108:111], v3, s[34:35]
	global_load_dwordx4 v[112:115], v3, s[34:35] offset:1024
	global_load_dwordx4 v[116:119], v3, s[34:35] offset:2048
	global_load_dwordx4 v[120:123], v3, s[34:35] offset:3072
	s_mov_b64 exec, s[2:3]
	global_load_dwordx4 v[124:127], v0, s[34:35]
	global_load_dwordx4 v[128:131], v0, s[34:35] offset:1024
	global_load_dwordx4 v[132:135], v0, s[34:35] offset:2048
	global_load_dwordx4 v[136:139], v0, s[34:35] offset:3072
	v_add_u32_e32 v3, 0x1000, v0
	global_load_dwordx4 v[140:143], v3, s[34:35]
	global_load_dwordx4 v[144:147], v3, s[34:35] offset:1024
	global_load_dwordx4 v[148:151], v3, s[34:35] offset:2048
	global_load_dwordx4 v[152:155], v3, s[34:35] offset:3072
	v_add_u32_e32 v3, 0x2000, v0
	global_load_dwordx4 v[156:159], v3, s[34:35]
	global_load_dwordx4 v[160:163], v3, s[34:35] offset:1024
	global_load_dwordx4 v[164:167], v3, s[34:35] offset:2048
	global_load_dwordx4 v[168:171], v3, s[34:35] offset:3072
	v_add_u32_e32 v3, 0x3000, v0
	global_load_dwordx4 v[172:175], v3, s[34:35]
	global_load_dwordx4 v[176:179], v3, s[34:35] offset:1024
	global_load_dwordx4 v[180:183], v3, s[34:35] offset:2048
	global_load_dwordx4 v[184:187], v3, s[34:35] offset:3072
	v_mov_b32_e32 v8, 0
	v_mov_b32_e32 v9, 0
	v_mov_b32_e32 v10, 0
	v_mov_b32_e32 v11, 0
	v_mov_b32_e32 v12, 0
	v_mov_b32_e32 v13, 0
	v_mov_b32_e32 v14, 0
	v_mov_b32_e32 v15, 0
	s_waitcnt vmcnt(30)
	v_lshlrev_b32_e32 v16, 16, v64
	v_and_b32_e32 v17, 0xffff0000, v64
	v_lshlrev_b32_e32 v18, 16, v65
	v_and_b32_e32 v19, 0xffff0000, v65
	v_lshlrev_b32_e32 v20, 16, v66
	v_and_b32_e32 v21, 0xffff0000, v66
	v_lshlrev_b32_e32 v22, 16, v67
	v_and_b32_e32 v23, 0xffff0000, v67
	v_pk_add_f32 v[8:9], v[8:9], v[16:17]
	v_pk_add_f32 v[10:11], v[10:11], v[18:19]
	v_pk_add_f32 v[12:13], v[12:13], v[20:21]
	v_pk_add_f32 v[14:15], v[14:15], v[22:23]
	s_waitcnt vmcnt(29)
	v_lshlrev_b32_e32 v16, 16, v68
	v_and_b32_e32 v17, 0xffff0000, v68
	v_lshlrev_b32_e32 v18, 16, v69
	v_and_b32_e32 v19, 0xffff0000, v69
	v_lshlrev_b32_e32 v20, 16, v70
	v_and_b32_e32 v21, 0xffff0000, v70
	v_lshlrev_b32_e32 v22, 16, v71
	v_and_b32_e32 v23, 0xffff0000, v71
	v_pk_add_f32 v[8:9], v[8:9], v[16:17]
	v_pk_add_f32 v[10:11], v[10:11], v[18:19]
	v_pk_add_f32 v[12:13], v[12:13], v[20:21]
	v_pk_add_f32 v[14:15], v[14:15], v[22:23]
	s_waitcnt vmcnt(28)
; __device__ __forceinline__ float bf_lo(unsigned w) { return __uint_as_float(w << 16); }
; __device__ __forceinline__ float bf_hi(unsigned w) { return __uint_as_float(w & 0xffff0000u); }
; template <int W> __device__ __forceinline__ v4u pool_window(const bf16* up, int t) {
;     ...
;     for (int j = 0; j < W; ++j) { const float wgt = (j <= t) ? 1.f : 0.f;
;         acc[0] += wgt * pg8::bf_lo(q[j].x); acc[1] += wgt * pg8::bf_hi(q[j].x); acc[2] += wgt * pg8::bf_lo(q[j].y); acc[3] += wgt * pg8::bf_hi(q[j].y);
;         acc[4] += wgt * pg8::bf_lo(q[j].z); acc[5] += wgt * pg8::bf_hi(q[j].z); acc[6] += wgt * pg8::bf_lo(q[j].w); acc[7] += wgt * pg8::bf_hi(q[j].w); }
	v_lshlrev_b32_e32 v16, 16, v72
	v_and_b32_e32 v17, 0xffff0000, v72
	v_lshlrev_b32_e32 v18, 16, v73
	v_and_b32_e32 v19, 0xffff0000, v73
	v_lshlrev_b32_e32 v20, 16, v74
	v_and_b32_e32 v21, 0xffff0000, v74
	v_lshlrev_b32_e32 v22, 16, v75
	v_and_b32_e32 v23, 0xffff0000, v75
	v_pk_add_f32 v[8:9], v[8:9], v[16:17]
	v_pk_add_f32 v[10:11], v[10:11], v[18:19]
	v_pk_add_f32 v[12:13], v[12:13], v[20:21]
	v_pk_add_f32 v[14:15], v[14:15], v[22:23]
	s_waitcnt vmcnt(27)
	v_lshlrev_b32_e32 v16, 16, v76
	v_and_b32_e32 v17, 0xffff0000, v76
	v_lshlrev_b32_e32 v18, 16, v77
	v_and_b32_e32 v19, 0xffff0000, v77
	v_lshlrev_b32_e32 v20, 16, v78
	v_and_b32_e32 v21, 0xffff0000, v78
	v_lshlrev_b32_e32 v22, 16, v79
	v_and_b32_e32 v23, 0xffff0000, v79
	v_pk_add_f32 v[8:9], v[8:9], v[16:17]
	v_pk_add_f32 v[10:11], v[10:11], v[18:19]
	v_pk_add_f32 v[12:13], v[12:13], v[20:21]
	v_pk_add_f32 v[14:15], v[14:15], v[22:23]
	s_waitcnt vmcnt(26)
	v_lshlrev_b32_e32 v16, 16, v80
	v_and_b32_e32 v17, 0xffff0000, v80
	v_lshlrev_b32_e32 v18, 16, v81
	v_and_b32_e32 v19, 0xffff0000, v81
	v_lshlrev_b32_e32 v20, 16, v82
	v_and_b32_e32 v21, 0xffff0000, v82
	v_lshlrev_b32_e32 v22, 16, v83
	v_and_b32_e32 v23, 0xffff0000, v83
	v_pk_add_f32 v[8:9], v[8:9], v[16:17]
	v_pk_add_f32 v[10:11], v[10:11], v[18:19]
	v_pk_add_f32 v[12:13], v[12:13], v[20:21]
	v_pk_add_f32 v[14:15], v[14:15], v[22:23]
	s_waitcnt vmcnt(25)
	v_lshlrev_b32_e32 v16, 16, v84
	v_and_b32_e32 v17, 0xffff0000, v84
	v_lshlrev_b32_e32 v18, 16, v85
	v_and_b32_e32 v19, 0xffff0000, v85
	v_lshlrev_b32_e32 v20, 16, v86
	v_and_b32_e32 v21, 0xffff0000, v86
	v_lshlrev_b32_e32 v22, 16, v87
	v_and_b32_e32 v23, 0xffff0000, v87
	v_pk_add_f32 v[8:9], v[8:9], v[16:17]
	v_pk_add_f32 v[10:11], v[10:11], v[18:19]
	v_pk_add_f32 v[12:13], v[12:13], v[20:21]
	v_pk_add_f32 v[14:15], v[14:15], v[22:23]
	s_waitcnt vmcnt(24)
	v_lshlrev_b32_e32 v16, 16, v88
	v_and_b32_e32 v17, 0xffff0000, v88
	v_lshlrev_b32_e32 v18, 16, v89
	v_and_b32_e32 v19, 0xffff0000, v89
	v_lshlrev_b32_e32 v20, 16, v90
	v_and_b32_e32 v21, 0xffff0000, v90
	v_lshlrev_b32_e32 v22, 16, v91
	v_and_b32_e32 v23, 0xffff0000, v91
	v_pk_add_f32 v[8:9], v[8:9], v[16:17]
	v_pk_add_f32 v[10:11], v[10:11], v[18:19]
	v_pk_add_f32 v[12:13], v[12:13], v[20:21]
	v_pk_add_f32 v[14:15], v[14:15], v[22:23]
	s_waitcnt vmcnt(23)
	v_lshlrev_b32_e32 v16, 16, v92
	v_and_b32_e32 v17, 0xffff0000, v92
	v_lshlrev_b32_e32 v18, 16, v93
	v_and_b32_e32 v19, 0xffff0000, v93
	v_lshlrev_b32_e32 v20, 16, v94
	v_and_b32_e32 v21, 0xffff0000, v94
	v_lshlrev_b32_e32 v22, 16, v95
	v_and_b32_e32 v23, 0xffff0000, v95
	v_pk_add_f32 v[8:9], v[8:9], v[16:17]
	v_pk_add_f32 v[10:11], v[10:11], v[18:19]
	v_pk_add_f32 v[12:13], v[12:13], v[20:21]
	v_pk_add_f32 v[14:15], v[14:15], v[22:23]
	s_waitcnt vmcnt(22)
	v_lshlrev_b32_e32 v16, 16, v96
	v_and_b32_e32 v17, 0xffff0000, v96
	v_lshlrev_b32_e32 v18, 16, v97
	v_and_b32_e32 v19, 0xffff0000, v97
	v_lshlrev_b32_e32 v20, 16, v98
	v_and_b32_e32 v21, 0xffff0000, v98
	v_lshlrev_b32_e32 v22, 16, v99
	v_and_b32_e32 v23, 0xffff0000, v99
	v_pk_add_f32 v[8:9], v[8:9], v[16:17]
	v_pk_add_f32 v[10:11], v[10:11], v[18:19]
	v_pk_add_f32 v[12:13], v[12:13], v[20:21]
	v_pk_add_f32 v[14:15], v[14:15], v[22:23]
	s_waitcnt vmcnt(21)
	v_lshlrev_b32_e32 v16, 16, v100
	v_and_b32_e32 v17, 0xffff0000, v100
	v_lshlrev_b32_e32 v18, 16, v101
	v_and_b32_e32 v19, 0xffff0000, v101
	v_lshlrev_b32_e32 v20, 16, v102
	v_and_b32_e32 v21, 0xffff0000, v102
	v_lshlrev_b32_e32 v22, 16, v103
	v_and_b32_e32 v23, 0xffff0000, v103
	v_pk_add_f32 v[8:9], v[8:9], v[16:17]
	v_pk_add_f32 v[10:11], v[10:11], v[18:19]
	v_pk_add_f32 v[12:13], v[12:13], v[20:21]
	v_pk_add_f32 v[14:15], v[14:15], v[22:23]
	s_waitcnt vmcnt(20)
	v_lshlrev_b32_e32 v16, 16, v104
	v_and_b32_e32 v17, 0xffff0000, v104
	v_lshlrev_b32_e32 v18, 16, v105
	v_and_b32_e32 v19, 0xffff0000, v105
	v_lshlrev_b32_e32 v20, 16, v106
	v_and_b32_e32 v21, 0xffff0000, v106
	v_lshlrev_b32_e32 v22, 16, v107
	v_and_b32_e32 v23, 0xffff0000, v107
	v_pk_add_f32 v[8:9], v[8:9], v[16:17]
	v_pk_add_f32 v[10:11], v[10:11], v[18:19]
	v_pk_add_f32 v[12:13], v[12:13], v[20:21]
	v_pk_add_f32 v[14:15], v[14:15], v[22:23]
	s_waitcnt vmcnt(19)
	v_lshlrev_b32_e32 v16, 16, v108
	v_and_b32_e32 v17, 0xffff0000, v108
	v_lshlrev_b32_e32 v18, 16, v109
	v_and_b32_e32 v19, 0xffff0000, v109
	v_lshlrev_b32_e32 v20, 16, v110
	v_and_b32_e32 v21, 0xffff0000, v110
	v_lshlrev_b32_e32 v22, 16, v111
	v_and_b32_e32 v23, 0xffff0000, v111
	v_pk_add_f32 v[8:9], v[8:9], v[16:17]
	v_pk_add_f32 v[10:11], v[10:11], v[18:19]
	v_pk_add_f32 v[12:13], v[12:13], v[20:21]
	v_pk_add_f32 v[14:15], v[14:15], v[22:23]
	s_waitcnt vmcnt(18)
	v_lshlrev_b32_e32 v16, 16, v112
	v_and_b32_e32 v17, 0xffff0000, v112
	v_lshlrev_b32_e32 v18, 16, v113
	v_and_b32_e32 v19, 0xffff0000, v113
	v_lshlrev_b32_e32 v20, 16, v114
	v_and_b32_e32 v21, 0xffff0000, v114
	v_lshlrev_b32_e32 v22, 16, v115
	v_and_b32_e32 v23, 0xffff0000, v115
	v_pk_add_f32 v[8:9], v[8:9], v[16:17]
	v_pk_add_f32 v[10:11], v[10:11], v[18:19]
	v_pk_add_f32 v[12:13], v[12:13], v[20:21]
	v_pk_add_f32 v[14:15], v[14:15], v[22:23]
	s_waitcnt vmcnt(17)
	v_lshlrev_b32_e32 v16, 16, v116
	v_and_b32_e32 v17, 0xffff0000, v116
	v_lshlrev_b32_e32 v18, 16, v117
	v_and_b32_e32 v19, 0xffff0000, v117
	v_lshlrev_b32_e32 v20, 16, v118
	v_and_b32_e32 v21, 0xffff0000, v118
	v_lshlrev_b32_e32 v22, 16, v119
	v_and_b32_e32 v23, 0xffff0000, v119
	v_pk_add_f32 v[8:9], v[8:9], v[16:17]
	v_pk_add_f32 v[10:11], v[10:11], v[18:19]
	v_pk_add_f32 v[12:13], v[12:13], v[20:21]
	v_pk_add_f32 v[14:15], v[14:15], v[22:23]
	s_waitcnt vmcnt(16)
; __device__ __forceinline__ float bf_lo(unsigned w) { return __uint_as_float(w << 16); }
; __device__ __forceinline__ float bf_hi(unsigned w) { return __uint_as_float(w & 0xffff0000u); }
; __device__ __forceinline__ unsigned pk2(float lo, float hi) { return f2bf(lo) | (f2bf(hi) << 16); }
; template <int W> __device__ __forceinline__ v4u pool_window(const bf16* up, int t) {
;     ...
;     for (int j = 0; j < W; ++j) { const float wgt = (j <= t) ? 1.f : 0.f;
;         acc[0] += wgt * pg8::bf_lo(q[j].x); acc[1] += wgt * pg8::bf_hi(q[j].x); acc[2] += wgt * pg8::bf_lo(q[j].y); acc[3] += wgt * pg8::bf_hi(q[j].y);
;         acc[4] += wgt * pg8::bf_lo(q[j].z); acc[5] += wgt * pg8::bf_hi(q[j].z); acc[6] += wgt * pg8::bf_lo(q[j].w); acc[7] += wgt * pg8::bf_hi(q[j].w); }
;     const float inv = 1.0f / (float)((t + 1 < W) ? (t + 1) : W);
;     v4u o;
;     o.x = pk2(acc[0] * inv - pg8::bf_lo(q[0].x), acc[1] * inv - pg8::bf_hi(q[0].x)); o.y = pk2(acc[2] * inv - pg8::bf_lo(q[0].y), acc[3] * inv - pg8::bf_hi(q[0].y));
;     o.z = pk2(acc[4] * inv - pg8::bf_lo(q[0].z), acc[5] * inv - pg8::bf_hi(q[0].z)); o.w = pk2(acc[6] * inv - pg8::bf_lo(q[0].w), acc[7] * inv - pg8::bf_hi(q[0].w));
;     return o;
; __global__ void __launch_bounds__(NWAVES * 64, 2) hybrid_fwd(Args a) {
;     ...
;             *(v4u*)(Dp + ((size_t)gp * M + row) * 128 + (lane & 15) * 8) = o;
	v_lshlrev_b32_e32 v16, 16, v120
	v_and_b32_e32 v17, 0xffff0000, v120
	v_lshlrev_b32_e32 v18, 16, v121
	v_and_b32_e32 v19, 0xffff0000, v121
	v_lshlrev_b32_e32 v20, 16, v122
	v_and_b32_e32 v21, 0xffff0000, v122
	v_lshlrev_b32_e32 v22, 16, v123
	v_and_b32_e32 v23, 0xffff0000, v123
	v_pk_add_f32 v[8:9], v[8:9], v[16:17]
	v_pk_add_f32 v[10:11], v[10:11], v[18:19]
	v_pk_add_f32 v[12:13], v[12:13], v[20:21]
	v_pk_add_f32 v[14:15], v[14:15], v[22:23]
	v_add_u32_e32 v6, 1, v2
	v_min_u32_e32 v6, 16, v6
	v_cvt_f32_u32_e32 v6, v6
	v_rcp_f32_e32 v4, v6
	s_waitcnt vmcnt(15)
	v_lshlrev_b32_e32 v16, 16, v124
	v_and_b32_e32 v17, 0xffff0000, v124
	v_lshlrev_b32_e32 v18, 16, v125
	v_and_b32_e32 v19, 0xffff0000, v125
	v_lshlrev_b32_e32 v20, 16, v126
	v_and_b32_e32 v21, 0xffff0000, v126
	v_lshlrev_b32_e32 v22, 16, v127
	v_and_b32_e32 v23, 0xffff0000, v127
	v_pk_add_f32 v[8:9], v[8:9], v[16:17]
	v_pk_add_f32 v[10:11], v[10:11], v[18:19]
	v_pk_add_f32 v[12:13], v[12:13], v[20:21]
	v_pk_add_f32 v[14:15], v[14:15], v[22:23]
	v_pk_fma_f32 v[32:33], v[4:5], v[8:9], v[16:17] op_sel_hi:[0,1,1] neg_lo:[0,0,1] neg_hi:[0,0,1]
	v_pk_fma_f32 v[34:35], v[4:5], v[10:11], v[18:19] op_sel_hi:[0,1,1] neg_lo:[0,0,1] neg_hi:[0,0,1]
	v_pk_fma_f32 v[36:37], v[4:5], v[12:13], v[20:21] op_sel_hi:[0,1,1] neg_lo:[0,0,1] neg_hi:[0,0,1]
	v_pk_fma_f32 v[38:39], v[4:5], v[14:15], v[22:23] op_sel_hi:[0,1,1] neg_lo:[0,0,1] neg_hi:[0,0,1]
	v_lshlrev_b32_e32 v24, 16, v64
	v_and_b32_e32 v25, 0xffff0000, v64
	v_lshlrev_b32_e32 v26, 16, v65
	v_and_b32_e32 v27, 0xffff0000, v65
	v_lshlrev_b32_e32 v28, 16, v66
	v_and_b32_e32 v29, 0xffff0000, v66
	v_lshlrev_b32_e32 v30, 16, v67
	v_and_b32_e32 v31, 0xffff0000, v67
	v_cvt_pk_bf16_f32 v40, v32, v33
	v_cvt_pk_bf16_f32 v41, v34, v35
	v_cvt_pk_bf16_f32 v42, v36, v37
	v_cvt_pk_bf16_f32 v43, v38, v39
	v_pk_add_f32 v[8:9], v[8:9], v[24:25] neg_lo:[0,1] neg_hi:[0,1]
	v_pk_add_f32 v[10:11], v[10:11], v[26:27] neg_lo:[0,1] neg_hi:[0,1]
	v_pk_add_f32 v[12:13], v[12:13], v[28:29] neg_lo:[0,1] neg_hi:[0,1]
	v_pk_add_f32 v[14:15], v[14:15], v[30:31] neg_lo:[0,1] neg_hi:[0,1]
	global_store_dwordx4 v1, v[40:43], s[84:85]
	v_add_u32_e32 v6, 2, v2
	v_min_u32_e32 v6, 16, v6
	v_cvt_f32_u32_e32 v6, v6
	v_rcp_f32_e32 v4, v6
	s_waitcnt vmcnt(15)
	v_lshlrev_b32_e32 v16, 16, v128
	v_and_b32_e32 v17, 0xffff0000, v128
	v_lshlrev_b32_e32 v18, 16, v129
	v_and_b32_e32 v19, 0xffff0000, v129
	v_lshlrev_b32_e32 v20, 16, v130
	v_and_b32_e32 v21, 0xffff0000, v130
	v_lshlrev_b32_e32 v22, 16, v131
	v_and_b32_e32 v23, 0xffff0000, v131
	v_pk_add_f32 v[8:9], v[8:9], v[16:17]
	v_pk_add_f32 v[10:11], v[10:11], v[18:19]
	v_pk_add_f32 v[12:13], v[12:13], v[20:21]
	v_pk_add_f32 v[14:15], v[14:15], v[22:23]
	v_pk_fma_f32 v[32:33], v[4:5], v[8:9], v[16:17] op_sel_hi:[0,1,1] neg_lo:[0,0,1] neg_hi:[0,0,1]
	v_pk_fma_f32 v[34:35], v[4:5], v[10:11], v[18:19] op_sel_hi:[0,1,1] neg_lo:[0,0,1] neg_hi:[0,0,1]
	v_pk_fma_f32 v[36:37], v[4:5], v[12:13], v[20:21] op_sel_hi:[0,1,1] neg_lo:[0,0,1] neg_hi:[0,0,1]
	v_pk_fma_f32 v[38:39], v[4:5], v[14:15], v[22:23] op_sel_hi:[0,1,1] neg_lo:[0,0,1] neg_hi:[0,0,1]
	v_lshlrev_b32_e32 v24, 16, v68
	v_and_b32_e32 v25, 0xffff0000, v68
	v_lshlrev_b32_e32 v26, 16, v69
	v_and_b32_e32 v27, 0xffff0000, v69
	v_lshlrev_b32_e32 v28, 16, v70
	v_and_b32_e32 v29, 0xffff0000, v70
	v_lshlrev_b32_e32 v30, 16, v71
	v_and_b32_e32 v31, 0xffff0000, v71
	v_cvt_pk_bf16_f32 v44, v32, v33
	v_cvt_pk_bf16_f32 v45, v34, v35
	v_cvt_pk_bf16_f32 v46, v36, v37
	v_cvt_pk_bf16_f32 v47, v38, v39
	v_pk_add_f32 v[8:9], v[8:9], v[24:25] neg_lo:[0,1] neg_hi:[0,1]
	v_pk_add_f32 v[10:11], v[10:11], v[26:27] neg_lo:[0,1] neg_hi:[0,1]
	v_pk_add_f32 v[12:13], v[12:13], v[28:29] neg_lo:[0,1] neg_hi:[0,1]
	v_pk_add_f32 v[14:15], v[14:15], v[30:31] neg_lo:[0,1] neg_hi:[0,1]
	global_store_dwordx4 v1, v[44:47], s[84:85] offset:256
	v_add_u32_e32 v6, 3, v2
	v_min_u32_e32 v6, 16, v6
	v_cvt_f32_u32_e32 v6, v6
	v_rcp_f32_e32 v4, v6
	s_waitcnt vmcnt(15)
	v_lshlrev_b32_e32 v16, 16, v132
	v_and_b32_e32 v17, 0xffff0000, v132
	v_lshlrev_b32_e32 v18, 16, v133
	v_and_b32_e32 v19, 0xffff0000, v133
	v_lshlrev_b32_e32 v20, 16, v134
	v_and_b32_e32 v21, 0xffff0000, v134
	v_lshlrev_b32_e32 v22, 16, v135
	v_and_b32_e32 v23, 0xffff0000, v135
	v_pk_add_f32 v[8:9], v[8:9], v[16:17]
	v_pk_add_f32 v[10:11], v[10:11], v[18:19]
	v_pk_add_f32 v[12:13], v[12:13], v[20:21]
	v_pk_add_f32 v[14:15], v[14:15], v[22:23]
	v_pk_fma_f32 v[32:33], v[4:5], v[8:9], v[16:17] op_sel_hi:[0,1,1] neg_lo:[0,0,1] neg_hi:[0,0,1]
	v_pk_fma_f32 v[34:35], v[4:5], v[10:11], v[18:19] op_sel_hi:[0,1,1] neg_lo:[0,0,1] neg_hi:[0,0,1]
	v_pk_fma_f32 v[36:37], v[4:5], v[12:13], v[20:21] op_sel_hi:[0,1,1] neg_lo:[0,0,1] neg_hi:[0,0,1]
	v_pk_fma_f32 v[38:39], v[4:5], v[14:15], v[22:23] op_sel_hi:[0,1,1] neg_lo:[0,0,1] neg_hi:[0,0,1]
	v_lshlrev_b32_e32 v24, 16, v72
	v_and_b32_e32 v25, 0xffff0000, v72
	v_lshlrev_b32_e32 v26, 16, v73
	v_and_b32_e32 v27, 0xffff0000, v73
	v_lshlrev_b32_e32 v28, 16, v74
	v_and_b32_e32 v29, 0xffff0000, v74
	v_lshlrev_b32_e32 v30, 16, v75
	v_and_b32_e32 v31, 0xffff0000, v75
	v_cvt_pk_bf16_f32 v40, v32, v33
	v_cvt_pk_bf16_f32 v41, v34, v35
	v_cvt_pk_bf16_f32 v42, v36, v37
	v_cvt_pk_bf16_f32 v43, v38, v39
	v_pk_add_f32 v[8:9], v[8:9], v[24:25] neg_lo:[0,1] neg_hi:[0,1]
	v_pk_add_f32 v[10:11], v[10:11], v[26:27] neg_lo:[0,1] neg_hi:[0,1]
	v_pk_add_f32 v[12:13], v[12:13], v[28:29] neg_lo:[0,1] neg_hi:[0,1]
	v_pk_add_f32 v[14:15], v[14:15], v[30:31] neg_lo:[0,1] neg_hi:[0,1]
	global_store_dwordx4 v1, v[40:43], s[84:85] offset:512
	v_add_u32_e32 v6, 4, v2
	v_min_u32_e32 v6, 16, v6
	v_cvt_f32_u32_e32 v6, v6
	v_rcp_f32_e32 v4, v6
	s_waitcnt vmcnt(15)
; __device__ __forceinline__ float bf_lo(unsigned w) { return __uint_as_float(w << 16); }
; __device__ __forceinline__ float bf_hi(unsigned w) { return __uint_as_float(w & 0xffff0000u); }
; __device__ __forceinline__ unsigned pk2(float lo, float hi) { return f2bf(lo) | (f2bf(hi) << 16); }
; template <int W> __device__ __forceinline__ v4u pool_window(const bf16* up, int t) {
;     ...
;     for (int j = 0; j < W; ++j) { const float wgt = (j <= t) ? 1.f : 0.f;
;         acc[0] += wgt * pg8::bf_lo(q[j].x); acc[1] += wgt * pg8::bf_hi(q[j].x); acc[2] += wgt * pg8::bf_lo(q[j].y); acc[3] += wgt * pg8::bf_hi(q[j].y);
;         acc[4] += wgt * pg8::bf_lo(q[j].z); acc[5] += wgt * pg8::bf_hi(q[j].z); acc[6] += wgt * pg8::bf_lo(q[j].w); acc[7] += wgt * pg8::bf_hi(q[j].w); }
;     const float inv = 1.0f / (float)((t + 1 < W) ? (t + 1) : W);
;     v4u o;
;     o.x = pk2(acc[0] * inv - pg8::bf_lo(q[0].x), acc[1] * inv - pg8::bf_hi(q[0].x)); o.y = pk2(acc[2] * inv - pg8::bf_lo(q[0].y), acc[3] * inv - pg8::bf_hi(q[0].y));
;     o.z = pk2(acc[4] * inv - pg8::bf_lo(q[0].z), acc[5] * inv - pg8::bf_hi(q[0].z)); o.w = pk2(acc[6] * inv - pg8::bf_lo(q[0].w), acc[7] * inv - pg8::bf_hi(q[0].w));
;     return o;
; __global__ void __launch_bounds__(NWAVES * 64, 2) hybrid_fwd(Args a) {
;     ...
;             *(v4u*)(Dp + ((size_t)gp * M + row) * 128 + (lane & 15) * 8) = o;
	v_lshlrev_b32_e32 v16, 16, v136
	v_and_b32_e32 v17, 0xffff0000, v136
	v_lshlrev_b32_e32 v18, 16, v137
	v_and_b32_e32 v19, 0xffff0000, v137
	v_lshlrev_b32_e32 v20, 16, v138
	v_and_b32_e32 v21, 0xffff0000, v138
	v_lshlrev_b32_e32 v22, 16, v139
	v_and_b32_e32 v23, 0xffff0000, v139
	v_pk_add_f32 v[8:9], v[8:9], v[16:17]
	v_pk_add_f32 v[10:11], v[10:11], v[18:19]
	v_pk_add_f32 v[12:13], v[12:13], v[20:21]
	v_pk_add_f32 v[14:15], v[14:15], v[22:23]
	v_pk_fma_f32 v[32:33], v[4:5], v[8:9], v[16:17] op_sel_hi:[0,1,1] neg_lo:[0,0,1] neg_hi:[0,0,1]
	v_pk_fma_f32 v[34:35], v[4:5], v[10:11], v[18:19] op_sel_hi:[0,1,1] neg_lo:[0,0,1] neg_hi:[0,0,1]
	v_pk_fma_f32 v[36:37], v[4:5], v[12:13], v[20:21] op_sel_hi:[0,1,1] neg_lo:[0,0,1] neg_hi:[0,0,1]
	v_pk_fma_f32 v[38:39], v[4:5], v[14:15], v[22:23] op_sel_hi:[0,1,1] neg_lo:[0,0,1] neg_hi:[0,0,1]
	v_lshlrev_b32_e32 v24, 16, v76
	v_and_b32_e32 v25, 0xffff0000, v76
	v_lshlrev_b32_e32 v26, 16, v77
	v_and_b32_e32 v27, 0xffff0000, v77
	v_lshlrev_b32_e32 v28, 16, v78
	v_and_b32_e32 v29, 0xffff0000, v78
	v_lshlrev_b32_e32 v30, 16, v79
	v_and_b32_e32 v31, 0xffff0000, v79
	v_cvt_pk_bf16_f32 v44, v32, v33
	v_cvt_pk_bf16_f32 v45, v34, v35
	v_cvt_pk_bf16_f32 v46, v36, v37
	v_cvt_pk_bf16_f32 v47, v38, v39
	v_pk_add_f32 v[8:9], v[8:9], v[24:25] neg_lo:[0,1] neg_hi:[0,1]
	v_pk_add_f32 v[10:11], v[10:11], v[26:27] neg_lo:[0,1] neg_hi:[0,1]
	v_pk_add_f32 v[12:13], v[12:13], v[28:29] neg_lo:[0,1] neg_hi:[0,1]
	v_pk_add_f32 v[14:15], v[14:15], v[30:31] neg_lo:[0,1] neg_hi:[0,1]
	global_store_dwordx4 v1, v[44:47], s[84:85] offset:768
	v_add_u32_e32 v6, 5, v2
	v_min_u32_e32 v6, 16, v6
	v_cvt_f32_u32_e32 v6, v6
	v_rcp_f32_e32 v4, v6
	s_waitcnt vmcnt(15)
	v_lshlrev_b32_e32 v16, 16, v140
	v_and_b32_e32 v17, 0xffff0000, v140
	v_lshlrev_b32_e32 v18, 16, v141
	v_and_b32_e32 v19, 0xffff0000, v141
	v_lshlrev_b32_e32 v20, 16, v142
	v_and_b32_e32 v21, 0xffff0000, v142
	v_lshlrev_b32_e32 v22, 16, v143
	v_and_b32_e32 v23, 0xffff0000, v143
	v_pk_add_f32 v[8:9], v[8:9], v[16:17]
	v_pk_add_f32 v[10:11], v[10:11], v[18:19]
	v_pk_add_f32 v[12:13], v[12:13], v[20:21]
	v_pk_add_f32 v[14:15], v[14:15], v[22:23]
	v_pk_fma_f32 v[32:33], v[4:5], v[8:9], v[16:17] op_sel_hi:[0,1,1] neg_lo:[0,0,1] neg_hi:[0,0,1]
	v_pk_fma_f32 v[34:35], v[4:5], v[10:11], v[18:19] op_sel_hi:[0,1,1] neg_lo:[0,0,1] neg_hi:[0,0,1]
	v_pk_fma_f32 v[36:37], v[4:5], v[12:13], v[20:21] op_sel_hi:[0,1,1] neg_lo:[0,0,1] neg_hi:[0,0,1]
	v_pk_fma_f32 v[38:39], v[4:5], v[14:15], v[22:23] op_sel_hi:[0,1,1] neg_lo:[0,0,1] neg_hi:[0,0,1]
	v_lshlrev_b32_e32 v24, 16, v80
	v_and_b32_e32 v25, 0xffff0000, v80
	v_lshlrev_b32_e32 v26, 16, v81
	v_and_b32_e32 v27, 0xffff0000, v81
	v_lshlrev_b32_e32 v28, 16, v82
	v_and_b32_e32 v29, 0xffff0000, v82
	v_lshlrev_b32_e32 v30, 16, v83
	v_and_b32_e32 v31, 0xffff0000, v83
	v_cvt_pk_bf16_f32 v40, v32, v33
	v_cvt_pk_bf16_f32 v41, v34, v35
	v_cvt_pk_bf16_f32 v42, v36, v37
	v_cvt_pk_bf16_f32 v43, v38, v39
	v_pk_add_f32 v[8:9], v[8:9], v[24:25] neg_lo:[0,1] neg_hi:[0,1]
	v_pk_add_f32 v[10:11], v[10:11], v[26:27] neg_lo:[0,1] neg_hi:[0,1]
	v_pk_add_f32 v[12:13], v[12:13], v[28:29] neg_lo:[0,1] neg_hi:[0,1]
	v_pk_add_f32 v[14:15], v[14:15], v[30:31] neg_lo:[0,1] neg_hi:[0,1]
	global_store_dwordx4 v1, v[40:43], s[84:85] offset:1024
	v_add_u32_e32 v6, 6, v2
	v_min_u32_e32 v6, 16, v6
	v_cvt_f32_u32_e32 v6, v6
	v_rcp_f32_e32 v4, v6
	s_waitcnt vmcnt(15)
	v_lshlrev_b32_e32 v16, 16, v144
	v_and_b32_e32 v17, 0xffff0000, v144
	v_lshlrev_b32_e32 v18, 16, v145
	v_and_b32_e32 v19, 0xffff0000, v145
	v_lshlrev_b32_e32 v20, 16, v146
	v_and_b32_e32 v21, 0xffff0000, v146
	v_lshlrev_b32_e32 v22, 16, v147
	v_and_b32_e32 v23, 0xffff0000, v147
	v_pk_add_f32 v[8:9], v[8:9], v[16:17]
	v_pk_add_f32 v[10:11], v[10:11], v[18:19]
	v_pk_add_f32 v[12:13], v[12:13], v[20:21]
	v_pk_add_f32 v[14:15], v[14:15], v[22:23]
	v_pk_fma_f32 v[32:33], v[4:5], v[8:9], v[16:17] op_sel_hi:[0,1,1] neg_lo:[0,0,1] neg_hi:[0,0,1]
	v_pk_fma_f32 v[34:35], v[4:5], v[10:11], v[18:19] op_sel_hi:[0,1,1] neg_lo:[0,0,1] neg_hi:[0,0,1]
	v_pk_fma_f32 v[36:37], v[4:5], v[12:13], v[20:21] op_sel_hi:[0,1,1] neg_lo:[0,0,1] neg_hi:[0,0,1]
	v_pk_fma_f32 v[38:39], v[4:5], v[14:15], v[22:23] op_sel_hi:[0,1,1] neg_lo:[0,0,1] neg_hi:[0,0,1]
	v_lshlrev_b32_e32 v24, 16, v84
	v_and_b32_e32 v25, 0xffff0000, v84
	v_lshlrev_b32_e32 v26, 16, v85
	v_and_b32_e32 v27, 0xffff0000, v85
	v_lshlrev_b32_e32 v28, 16, v86
	v_and_b32_e32 v29, 0xffff0000, v86
	v_lshlrev_b32_e32 v30, 16, v87
	v_and_b32_e32 v31, 0xffff0000, v87
	v_cvt_pk_bf16_f32 v44, v32, v33
	v_cvt_pk_bf16_f32 v45, v34, v35
	v_cvt_pk_bf16_f32 v46, v36, v37
	v_cvt_pk_bf16_f32 v47, v38, v39
	v_pk_add_f32 v[8:9], v[8:9], v[24:25] neg_lo:[0,1] neg_hi:[0,1]
	v_pk_add_f32 v[10:11], v[10:11], v[26:27] neg_lo:[0,1] neg_hi:[0,1]
	v_pk_add_f32 v[12:13], v[12:13], v[28:29] neg_lo:[0,1] neg_hi:[0,1]
	v_pk_add_f32 v[14:15], v[14:15], v[30:31] neg_lo:[0,1] neg_hi:[0,1]
	global_store_dwordx4 v1, v[44:47], s[84:85] offset:1280
	v_add_u32_e32 v6, 7, v2
	v_min_u32_e32 v6, 16, v6
	v_cvt_f32_u32_e32 v6, v6
	v_rcp_f32_e32 v4, v6
	s_waitcnt vmcnt(15)
; __device__ __forceinline__ float bf_lo(unsigned w) { return __uint_as_float(w << 16); }
; __device__ __forceinline__ float bf_hi(unsigned w) { return __uint_as_float(w & 0xffff0000u); }
; __device__ __forceinline__ unsigned pk2(float lo, float hi) { return f2bf(lo) | (f2bf(hi) << 16); }
; template <int W> __device__ __forceinline__ v4u pool_window(const bf16* up, int t) {
;     ...
;     for (int j = 0; j < W; ++j) { const float wgt = (j <= t) ? 1.f : 0.f;
;         acc[0] += wgt * pg8::bf_lo(q[j].x); acc[1] += wgt * pg8::bf_hi(q[j].x); acc[2] += wgt * pg8::bf_lo(q[j].y); acc[3] += wgt * pg8::bf_hi(q[j].y);
;         acc[4] += wgt * pg8::bf_lo(q[j].z); acc[5] += wgt * pg8::bf_hi(q[j].z); acc[6] += wgt * pg8::bf_lo(q[j].w); acc[7] += wgt * pg8::bf_hi(q[j].w); }
;     const float inv = 1.0f / (float)((t + 1 < W) ? (t + 1) : W);
;     v4u o;
;     o.x = pk2(acc[0] * inv - pg8::bf_lo(q[0].x), acc[1] * inv - pg8::bf_hi(q[0].x)); o.y = pk2(acc[2] * inv - pg8::bf_lo(q[0].y), acc[3] * inv - pg8::bf_hi(q[0].y));
;     o.z = pk2(acc[4] * inv - pg8::bf_lo(q[0].z), acc[5] * inv - pg8::bf_hi(q[0].z)); o.w = pk2(acc[6] * inv - pg8::bf_lo(q[0].w), acc[7] * inv - pg8::bf_hi(q[0].w));
	v_lshlrev_b32_e32 v16, 16, v148
	v_and_b32_e32 v17, 0xffff0000, v148
	v_lshlrev_b32_e32 v18, 16, v149
	v_and_b32_e32 v19, 0xffff0000, v149
	v_lshlrev_b32_e32 v20, 16, v150
	v_and_b32_e32 v21, 0xffff0000, v150
	v_lshlrev_b32_e32 v22, 16, v151
	v_and_b32_e32 v23, 0xffff0000, v151
	v_pk_add_f32 v[8:9], v[8:9], v[16:17]
	v_pk_add_f32 v[10:11], v[10:11], v[18:19]
	v_pk_add_f32 v[12:13], v[12:13], v[20:21]
	v_pk_add_f32 v[14:15], v[14:15], v[22:23]
	v_pk_fma_f32 v[32:33], v[4:5], v[8:9], v[16:17] op_sel_hi:[0,1,1] neg_lo:[0,0,1] neg_hi:[0,0,1]
	v_pk_fma_f32 v[34:35], v[4:5], v[10:11], v[18:19] op_sel_hi:[0,1,1] neg_lo:[0,0,1] neg_hi:[0,0,1]
	v_pk_fma_f32 v[36:37], v[4:5], v[12:13], v[20:21] op_sel_hi:[0,1,1] neg_lo:[0,0,1] neg_hi:[0,0,1]
	v_pk_fma_f32 v[38:39], v[4:5], v[14:15], v[22:23] op_sel_hi:[0,1,1] neg_lo:[0,0,1] neg_hi:[0,0,1]
	v_lshlrev_b32_e32 v24, 16, v88
	v_and_b32_e32 v25, 0xffff0000, v88
	v_lshlrev_b32_e32 v26, 16, v89
	v_and_b32_e32 v27, 0xffff0000, v89
	v_lshlrev_b32_e32 v28, 16, v90
	v_and_b32_e32 v29, 0xffff0000, v90
	v_lshlrev_b32_e32 v30, 16, v91
	v_and_b32_e32 v31, 0xffff0000, v91
	v_cvt_pk_bf16_f32 v40, v32, v33
	v_cvt_pk_bf16_f32 v41, v34, v35
	v_cvt_pk_bf16_f32 v42, v36, v37
	v_cvt_pk_bf16_f32 v43, v38, v39
	v_pk_add_f32 v[8:9], v[8:9], v[24:25] neg_lo:[0,1] neg_hi:[0,1]
	v_pk_add_f32 v[10:11], v[10:11], v[26:27] neg_lo:[0,1] neg_hi:[0,1]
	v_pk_add_f32 v[12:13], v[12:13], v[28:29] neg_lo:[0,1] neg_hi:[0,1]
	v_pk_add_f32 v[14:15], v[14:15], v[30:31] neg_lo:[0,1] neg_hi:[0,1]
	global_store_dwordx4 v1, v[40:43], s[84:85] offset:1536
	v_add_u32_e32 v6, 8, v2
	v_min_u32_e32 v6, 16, v6
	v_cvt_f32_u32_e32 v6, v6
	v_rcp_f32_e32 v4, v6
	s_waitcnt vmcnt(15)
	v_lshlrev_b32_e32 v16, 16, v152
	v_and_b32_e32 v17, 0xffff0000, v152
	v_lshlrev_b32_e32 v18, 16, v153
	v_and_b32_e32 v19, 0xffff0000, v153
	v_lshlrev_b32_e32 v20, 16, v154
	v_and_b32_e32 v21, 0xffff0000, v154
	v_lshlrev_b32_e32 v22, 16, v155
	v_and_b32_e32 v23, 0xffff0000, v155
	v_pk_add_f32 v[8:9], v[8:9], v[16:17]
	v_pk_add_f32 v[10:11], v[10:11], v[18:19]
	v_pk_add_f32 v[12:13], v[12:13], v[20:21]
	v_pk_add_f32 v[14:15], v[14:15], v[22:23]
	v_pk_fma_f32 v[32:33], v[4:5], v[8:9], v[16:17] op_sel_hi:[0,1,1] neg_lo:[0,0,1] neg_hi:[0,0,1]
	v_pk_fma_f32 v[34:35], v[4:5], v[10:11], v[18:19] op_sel_hi:[0,1,1] neg_lo:[0,0,1] neg_hi:[0,0,1]
	v_pk_fma_f32 v[36:37], v[4:5], v[12:13], v[20:21] op_sel_hi:[0,1,1] neg_lo:[0,0,1] neg_hi:[0,0,1]
	v_pk_fma_f32 v[38:39], v[4:5], v[14:15], v[22:23] op_sel_hi:[0,1,1] neg_lo:[0,0,1] neg_hi:[0,0,1]
	v_lshlrev_b32_e32 v24, 16, v92
	v_and_b32_e32 v25, 0xffff0000, v92
	v_lshlrev_b32_e32 v26, 16, v93
	v_and_b32_e32 v27, 0xffff0000, v93
	v_lshlrev_b32_e32 v28, 16, v94
	v_and_b32_e32 v29, 0xffff0000, v94
	v_lshlrev_b32_e32 v30, 16, v95
	v_and_b32_e32 v31, 0xffff0000, v95
	v_cvt_pk_bf16_f32 v44, v32, v33
	v_cvt_pk_bf16_f32 v45, v34, v35
	v_cvt_pk_bf16_f32 v46, v36, v37
	v_cvt_pk_bf16_f32 v47, v38, v39
	v_pk_add_f32 v[8:9], v[8:9], v[24:25] neg_lo:[0,1] neg_hi:[0,1]
	v_pk_add_f32 v[10:11], v[10:11], v[26:27] neg_lo:[0,1] neg_hi:[0,1]
	v_pk_add_f32 v[12:13], v[12:13], v[28:29] neg_lo:[0,1] neg_hi:[0,1]
	v_pk_add_f32 v[14:15], v[14:15], v[30:31] neg_lo:[0,1] neg_hi:[0,1]
	global_store_dwordx4 v1, v[44:47], s[84:85] offset:1792
	v_add_u32_e32 v6, 9, v2
	v_min_u32_e32 v6, 16, v6
	v_cvt_f32_u32_e32 v6, v6
	v_rcp_f32_e32 v4, v6
	s_waitcnt vmcnt(15)
	v_lshlrev_b32_e32 v16, 16, v156
	v_and_b32_e32 v17, 0xffff0000, v156
	v_lshlrev_b32_e32 v18, 16, v157
	v_and_b32_e32 v19, 0xffff0000, v157
	v_lshlrev_b32_e32 v20, 16, v158
	v_and_b32_e32 v21, 0xffff0000, v158
	v_lshlrev_b32_e32 v22, 16, v159
	v_and_b32_e32 v23, 0xffff0000, v159
	v_pk_add_f32 v[8:9], v[8:9], v[16:17]
	v_pk_add_f32 v[10:11], v[10:11], v[18:19]
	v_pk_add_f32 v[12:13], v[12:13], v[20:21]
	v_pk_add_f32 v[14:15], v[14:15], v[22:23]
	v_pk_fma_f32 v[32:33], v[4:5], v[8:9], v[16:17] op_sel_hi:[0,1,1] neg_lo:[0,0,1] neg_hi:[0,0,1]
	v_pk_fma_f32 v[34:35], v[4:5], v[10:11], v[18:19] op_sel_hi:[0,1,1] neg_lo:[0,0,1] neg_hi:[0,0,1]
	v_pk_fma_f32 v[36:37], v[4:5], v[12:13], v[20:21] op_sel_hi:[0,1,1] neg_lo:[0,0,1] neg_hi:[0,0,1]
	v_pk_fma_f32 v[38:39], v[4:5], v[14:15], v[22:23] op_sel_hi:[0,1,1] neg_lo:[0,0,1] neg_hi:[0,0,1]
	v_lshlrev_b32_e32 v24, 16, v96
	v_and_b32_e32 v25, 0xffff0000, v96
	v_lshlrev_b32_e32 v26, 16, v97
	v_and_b32_e32 v27, 0xffff0000, v97
	v_lshlrev_b32_e32 v28, 16, v98
	v_and_b32_e32 v29, 0xffff0000, v98
	v_lshlrev_b32_e32 v30, 16, v99
	v_and_b32_e32 v31, 0xffff0000, v99
	v_cvt_pk_bf16_f32 v40, v32, v33
	v_cvt_pk_bf16_f32 v41, v34, v35
	v_cvt_pk_bf16_f32 v42, v36, v37
	v_cvt_pk_bf16_f32 v43, v38, v39
	v_pk_add_f32 v[8:9], v[8:9], v[24:25] neg_lo:[0,1] neg_hi:[0,1]
	v_pk_add_f32 v[10:11], v[10:11], v[26:27] neg_lo:[0,1] neg_hi:[0,1]
	v_pk_add_f32 v[12:13], v[12:13], v[28:29] neg_lo:[0,1] neg_hi:[0,1]
	v_pk_add_f32 v[14:15], v[14:15], v[30:31] neg_lo:[0,1] neg_hi:[0,1]
	global_store_dwordx4 v1, v[40:43], s[84:85] offset:2048
	v_add_u32_e32 v6, 10, v2
	v_min_u32_e32 v6, 16, v6
	v_cvt_f32_u32_e32 v6, v6
	v_rcp_f32_e32 v4, v6
	s_waitcnt vmcnt(15)
; __device__ __forceinline__ float bf_lo(unsigned w) { return __uint_as_float(w << 16); }
; __device__ __forceinline__ float bf_hi(unsigned w) { return __uint_as_float(w & 0xffff0000u); }
; __device__ __forceinline__ unsigned pk2(float lo, float hi) { return f2bf(lo) | (f2bf(hi) << 16); }
; template <int W> __device__ __forceinline__ v4u pool_window(const bf16* up, int t) {
;     ...
;     for (int j = 0; j < W; ++j) { const float wgt = (j <= t) ? 1.f : 0.f;
;         acc[0] += wgt * pg8::bf_lo(q[j].x); acc[1] += wgt * pg8::bf_hi(q[j].x); acc[2] += wgt * pg8::bf_lo(q[j].y); acc[3] += wgt * pg8::bf_hi(q[j].y);
;         acc[4] += wgt * pg8::bf_lo(q[j].z); acc[5] += wgt * pg8::bf_hi(q[j].z); acc[6] += wgt * pg8::bf_lo(q[j].w); acc[7] += wgt * pg8::bf_hi(q[j].w); }
;     const float inv = 1.0f / (float)((t + 1 < W) ? (t + 1) : W);
;     v4u o;
;     o.x = pk2(acc[0] * inv - pg8::bf_lo(q[0].x), acc[1] * inv - pg8::bf_hi(q[0].x)); o.y = pk2(acc[2] * inv - pg8::bf_lo(q[0].y), acc[3] * inv - pg8::bf_hi(q[0].y));
;     o.z = pk2(acc[4] * inv - pg8::bf_lo(q[0].z), acc[5] * inv - pg8::bf_hi(q[0].z)); o.w = pk2(acc[6] * inv - pg8::bf_lo(q[0].w), acc[7] * inv - pg8::bf_hi(q[0].w));
	v_lshlrev_b32_e32 v16, 16, v160
	v_and_b32_e32 v17, 0xffff0000, v160
	v_lshlrev_b32_e32 v18, 16, v161
	v_and_b32_e32 v19, 0xffff0000, v161
	v_lshlrev_b32_e32 v20, 16, v162
	v_and_b32_e32 v21, 0xffff0000, v162
	v_lshlrev_b32_e32 v22, 16, v163
	v_and_b32_e32 v23, 0xffff0000, v163
	v_pk_add_f32 v[8:9], v[8:9], v[16:17]
	v_pk_add_f32 v[10:11], v[10:11], v[18:19]
	v_pk_add_f32 v[12:13], v[12:13], v[20:21]
	v_pk_add_f32 v[14:15], v[14:15], v[22:23]
	v_pk_fma_f32 v[32:33], v[4:5], v[8:9], v[16:17] op_sel_hi:[0,1,1] neg_lo:[0,0,1] neg_hi:[0,0,1]
	v_pk_fma_f32 v[34:35], v[4:5], v[10:11], v[18:19] op_sel_hi:[0,1,1] neg_lo:[0,0,1] neg_hi:[0,0,1]
	v_pk_fma_f32 v[36:37], v[4:5], v[12:13], v[20:21] op_sel_hi:[0,1,1] neg_lo:[0,0,1] neg_hi:[0,0,1]
	v_pk_fma_f32 v[38:39], v[4:5], v[14:15], v[22:23] op_sel_hi:[0,1,1] neg_lo:[0,0,1] neg_hi:[0,0,1]
	v_lshlrev_b32_e32 v24, 16, v100
	v_and_b32_e32 v25, 0xffff0000, v100
	v_lshlrev_b32_e32 v26, 16, v101
	v_and_b32_e32 v27, 0xffff0000, v101
	v_lshlrev_b32_e32 v28, 16, v102
	v_and_b32_e32 v29, 0xffff0000, v102
	v_lshlrev_b32_e32 v30, 16, v103
	v_and_b32_e32 v31, 0xffff0000, v103
	v_cvt_pk_bf16_f32 v44, v32, v33
	v_cvt_pk_bf16_f32 v45, v34, v35
	v_cvt_pk_bf16_f32 v46, v36, v37
	v_cvt_pk_bf16_f32 v47, v38, v39
	v_pk_add_f32 v[8:9], v[8:9], v[24:25] neg_lo:[0,1] neg_hi:[0,1]
	v_pk_add_f32 v[10:11], v[10:11], v[26:27] neg_lo:[0,1] neg_hi:[0,1]
	v_pk_add_f32 v[12:13], v[12:13], v[28:29] neg_lo:[0,1] neg_hi:[0,1]
	v_pk_add_f32 v[14:15], v[14:15], v[30:31] neg_lo:[0,1] neg_hi:[0,1]
	global_store_dwordx4 v1, v[44:47], s[84:85] offset:2304
	v_add_u32_e32 v6, 11, v2
	v_min_u32_e32 v6, 16, v6
	v_cvt_f32_u32_e32 v6, v6
	v_rcp_f32_e32 v4, v6
	s_waitcnt vmcnt(15)
	v_lshlrev_b32_e32 v16, 16, v164
	v_and_b32_e32 v17, 0xffff0000, v164
	v_lshlrev_b32_e32 v18, 16, v165
	v_and_b32_e32 v19, 0xffff0000, v165
	v_lshlrev_b32_e32 v20, 16, v166
	v_and_b32_e32 v21, 0xffff0000, v166
	v_lshlrev_b32_e32 v22, 16, v167
	v_and_b32_e32 v23, 0xffff0000, v167
	v_pk_add_f32 v[8:9], v[8:9], v[16:17]
	v_pk_add_f32 v[10:11], v[10:11], v[18:19]
	v_pk_add_f32 v[12:13], v[12:13], v[20:21]
	v_pk_add_f32 v[14:15], v[14:15], v[22:23]
	v_pk_fma_f32 v[32:33], v[4:5], v[8:9], v[16:17] op_sel_hi:[0,1,1] neg_lo:[0,0,1] neg_hi:[0,0,1]
	v_pk_fma_f32 v[34:35], v[4:5], v[10:11], v[18:19] op_sel_hi:[0,1,1] neg_lo:[0,0,1] neg_hi:[0,0,1]
	v_pk_fma_f32 v[36:37], v[4:5], v[12:13], v[20:21] op_sel_hi:[0,1,1] neg_lo:[0,0,1] neg_hi:[0,0,1]
	v_pk_fma_f32 v[38:39], v[4:5], v[14:15], v[22:23] op_sel_hi:[0,1,1] neg_lo:[0,0,1] neg_hi:[0,0,1]
	v_lshlrev_b32_e32 v24, 16, v104
	v_and_b32_e32 v25, 0xffff0000, v104
	v_lshlrev_b32_e32 v26, 16, v105
	v_and_b32_e32 v27, 0xffff0000, v105
	v_lshlrev_b32_e32 v28, 16, v106
	v_and_b32_e32 v29, 0xffff0000, v106
	v_lshlrev_b32_e32 v30, 16, v107
	v_and_b32_e32 v31, 0xffff0000, v107
	v_cvt_pk_bf16_f32 v40, v32, v33
	v_cvt_pk_bf16_f32 v41, v34, v35
	v_cvt_pk_bf16_f32 v42, v36, v37
	v_cvt_pk_bf16_f32 v43, v38, v39
	v_pk_add_f32 v[8:9], v[8:9], v[24:25] neg_lo:[0,1] neg_hi:[0,1]
	v_pk_add_f32 v[10:11], v[10:11], v[26:27] neg_lo:[0,1] neg_hi:[0,1]
	v_pk_add_f32 v[12:13], v[12:13], v[28:29] neg_lo:[0,1] neg_hi:[0,1]
	v_pk_add_f32 v[14:15], v[14:15], v[30:31] neg_lo:[0,1] neg_hi:[0,1]
	global_store_dwordx4 v1, v[40:43], s[84:85] offset:2560
	v_add_u32_e32 v6, 12, v2
	v_min_u32_e32 v6, 16, v6
	v_cvt_f32_u32_e32 v6, v6
	v_rcp_f32_e32 v4, v6
	s_waitcnt vmcnt(15)
	v_lshlrev_b32_e32 v16, 16, v168
	v_and_b32_e32 v17, 0xffff0000, v168
	v_lshlrev_b32_e32 v18, 16, v169
	v_and_b32_e32 v19, 0xffff0000, v169
	v_lshlrev_b32_e32 v20, 16, v170
	v_and_b32_e32 v21, 0xffff0000, v170
	v_lshlrev_b32_e32 v22, 16, v171
	v_and_b32_e32 v23, 0xffff0000, v171
	v_pk_add_f32 v[8:9], v[8:9], v[16:17]
	v_pk_add_f32 v[10:11], v[10:11], v[18:19]
	v_pk_add_f32 v[12:13], v[12:13], v[20:21]
	v_pk_add_f32 v[14:15], v[14:15], v[22:23]
	v_pk_fma_f32 v[32:33], v[4:5], v[8:9], v[16:17] op_sel_hi:[0,1,1] neg_lo:[0,0,1] neg_hi:[0,0,1]
	v_pk_fma_f32 v[34:35], v[4:5], v[10:11], v[18:19] op_sel_hi:[0,1,1] neg_lo:[0,0,1] neg_hi:[0,0,1]
	v_pk_fma_f32 v[36:37], v[4:5], v[12:13], v[20:21] op_sel_hi:[0,1,1] neg_lo:[0,0,1] neg_hi:[0,0,1]
	v_pk_fma_f32 v[38:39], v[4:5], v[14:15], v[22:23] op_sel_hi:[0,1,1] neg_lo:[0,0,1] neg_hi:[0,0,1]
	v_lshlrev_b32_e32 v24, 16, v108
	v_and_b32_e32 v25, 0xffff0000, v108
	v_lshlrev_b32_e32 v26, 16, v109
	v_and_b32_e32 v27, 0xffff0000, v109
	v_lshlrev_b32_e32 v28, 16, v110
	v_and_b32_e32 v29, 0xffff0000, v110
	v_lshlrev_b32_e32 v30, 16, v111
	v_and_b32_e32 v31, 0xffff0000, v111
	v_cvt_pk_bf16_f32 v44, v32, v33
	v_cvt_pk_bf16_f32 v45, v34, v35
	v_cvt_pk_bf16_f32 v46, v36, v37
	v_cvt_pk_bf16_f32 v47, v38, v39
	v_pk_add_f32 v[8:9], v[8:9], v[24:25] neg_lo:[0,1] neg_hi:[0,1]
	v_pk_add_f32 v[10:11], v[10:11], v[26:27] neg_lo:[0,1] neg_hi:[0,1]
	v_pk_add_f32 v[12:13], v[12:13], v[28:29] neg_lo:[0,1] neg_hi:[0,1]
	v_pk_add_f32 v[14:15], v[14:15], v[30:31] neg_lo:[0,1] neg_hi:[0,1]
	global_store_dwordx4 v1, v[44:47], s[84:85] offset:2816
	v_add_u32_e32 v6, 13, v2
	v_min_u32_e32 v6, 16, v6
	v_cvt_f32_u32_e32 v6, v6
	v_rcp_f32_e32 v4, v6
	s_waitcnt vmcnt(15)
; __device__ __forceinline__ float bf_lo(unsigned w) { return __uint_as_float(w << 16); }
; __device__ __forceinline__ float bf_hi(unsigned w) { return __uint_as_float(w & 0xffff0000u); }
; __device__ __forceinline__ unsigned pk2(float lo, float hi) { return f2bf(lo) | (f2bf(hi) << 16); }
; template <int W> __device__ __forceinline__ v4u pool_window(const bf16* up, int t) {
;     ...
;     for (int j = 0; j < W; ++j) { const float wgt = (j <= t) ? 1.f : 0.f;
;         acc[0] += wgt * pg8::bf_lo(q[j].x); acc[1] += wgt * pg8::bf_hi(q[j].x); acc[2] += wgt * pg8::bf_lo(q[j].y); acc[3] += wgt * pg8::bf_hi(q[j].y);
;         acc[4] += wgt * pg8::bf_lo(q[j].z); acc[5] += wgt * pg8::bf_hi(q[j].z); acc[6] += wgt * pg8::bf_lo(q[j].w); acc[7] += wgt * pg8::bf_hi(q[j].w); }
;     const float inv = 1.0f / (float)((t + 1 < W) ? (t + 1) : W);
;     v4u o;
;     o.x = pk2(acc[0] * inv - pg8::bf_lo(q[0].x), acc[1] * inv - pg8::bf_hi(q[0].x)); o.y = pk2(acc[2] * inv - pg8::bf_lo(q[0].y), acc[3] * inv - pg8::bf_hi(q[0].y));
;     o.z = pk2(acc[4] * inv - pg8::bf_lo(q[0].z), acc[5] * inv - pg8::bf_hi(q[0].z)); o.w = pk2(acc[6] * inv - pg8::bf_lo(q[0].w), acc[7] * inv - pg8::bf_hi(q[0].w));
; __global__ void __launch_bounds__(NWAVES * 64, 2) hybrid_fwd(Args a) {
;     ...
;         for (int wi = gw; wi < M; wi += NGW) {
;             const int rq = wi >> 2, gp = ((wi & 3) + (wi >> 11)) & 3;
;             const int row = 4 * rq + (lane >> 4), t = row & (SEQ - 1);
;             const bf16* up = Ub + (size_t)row * 512 + gp * 128 + (lane & 15) * 8;
;             v4u o;
;             if (gp == 0) o = pool_window<2>(up, t); else if (gp == 1) o = pool_window<4>(up, t); else if (gp == 2) o = pool_window<8>(up, t); else o = pool_window<16>(up, t);
;             *(v4u*)(Dp + ((size_t)gp * M + row) * 128 + (lane & 15) * 8) = o;
	v_lshlrev_b32_e32 v16, 16, v172
	v_and_b32_e32 v17, 0xffff0000, v172
	v_lshlrev_b32_e32 v18, 16, v173
	v_and_b32_e32 v19, 0xffff0000, v173
	v_lshlrev_b32_e32 v20, 16, v174
	v_and_b32_e32 v21, 0xffff0000, v174
	v_lshlrev_b32_e32 v22, 16, v175
	v_and_b32_e32 v23, 0xffff0000, v175
	v_pk_add_f32 v[8:9], v[8:9], v[16:17]
	v_pk_add_f32 v[10:11], v[10:11], v[18:19]
	v_pk_add_f32 v[12:13], v[12:13], v[20:21]
	v_pk_add_f32 v[14:15], v[14:15], v[22:23]
	v_pk_fma_f32 v[32:33], v[4:5], v[8:9], v[16:17] op_sel_hi:[0,1,1] neg_lo:[0,0,1] neg_hi:[0,0,1]
	v_pk_fma_f32 v[34:35], v[4:5], v[10:11], v[18:19] op_sel_hi:[0,1,1] neg_lo:[0,0,1] neg_hi:[0,0,1]
	v_pk_fma_f32 v[36:37], v[4:5], v[12:13], v[20:21] op_sel_hi:[0,1,1] neg_lo:[0,0,1] neg_hi:[0,0,1]
	v_pk_fma_f32 v[38:39], v[4:5], v[14:15], v[22:23] op_sel_hi:[0,1,1] neg_lo:[0,0,1] neg_hi:[0,0,1]
	v_lshlrev_b32_e32 v24, 16, v112
	v_and_b32_e32 v25, 0xffff0000, v112
	v_lshlrev_b32_e32 v26, 16, v113
	v_and_b32_e32 v27, 0xffff0000, v113
	v_lshlrev_b32_e32 v28, 16, v114
	v_and_b32_e32 v29, 0xffff0000, v114
	v_lshlrev_b32_e32 v30, 16, v115
	v_and_b32_e32 v31, 0xffff0000, v115
	v_cvt_pk_bf16_f32 v40, v32, v33
	v_cvt_pk_bf16_f32 v41, v34, v35
	v_cvt_pk_bf16_f32 v42, v36, v37
	v_cvt_pk_bf16_f32 v43, v38, v39
	v_pk_add_f32 v[8:9], v[8:9], v[24:25] neg_lo:[0,1] neg_hi:[0,1]
	v_pk_add_f32 v[10:11], v[10:11], v[26:27] neg_lo:[0,1] neg_hi:[0,1]
	v_pk_add_f32 v[12:13], v[12:13], v[28:29] neg_lo:[0,1] neg_hi:[0,1]
	v_pk_add_f32 v[14:15], v[14:15], v[30:31] neg_lo:[0,1] neg_hi:[0,1]
	global_store_dwordx4 v1, v[40:43], s[84:85] offset:3072
	v_add_u32_e32 v6, 14, v2
	v_min_u32_e32 v6, 16, v6
	v_cvt_f32_u32_e32 v6, v6
	v_rcp_f32_e32 v4, v6
	s_waitcnt vmcnt(15)
	v_lshlrev_b32_e32 v16, 16, v176
	v_and_b32_e32 v17, 0xffff0000, v176
	v_lshlrev_b32_e32 v18, 16, v177
	v_and_b32_e32 v19, 0xffff0000, v177
	v_lshlrev_b32_e32 v20, 16, v178
	v_and_b32_e32 v21, 0xffff0000, v178
	v_lshlrev_b32_e32 v22, 16, v179
	v_and_b32_e32 v23, 0xffff0000, v179
	v_pk_add_f32 v[8:9], v[8:9], v[16:17]
	v_pk_add_f32 v[10:11], v[10:11], v[18:19]
	v_pk_add_f32 v[12:13], v[12:13], v[20:21]
	v_pk_add_f32 v[14:15], v[14:15], v[22:23]
	v_pk_fma_f32 v[32:33], v[4:5], v[8:9], v[16:17] op_sel_hi:[0,1,1] neg_lo:[0,0,1] neg_hi:[0,0,1]
	v_pk_fma_f32 v[34:35], v[4:5], v[10:11], v[18:19] op_sel_hi:[0,1,1] neg_lo:[0,0,1] neg_hi:[0,0,1]
	v_pk_fma_f32 v[36:37], v[4:5], v[12:13], v[20:21] op_sel_hi:[0,1,1] neg_lo:[0,0,1] neg_hi:[0,0,1]
	v_pk_fma_f32 v[38:39], v[4:5], v[14:15], v[22:23] op_sel_hi:[0,1,1] neg_lo:[0,0,1] neg_hi:[0,0,1]
	v_lshlrev_b32_e32 v24, 16, v116
	v_and_b32_e32 v25, 0xffff0000, v116
	v_lshlrev_b32_e32 v26, 16, v117
	v_and_b32_e32 v27, 0xffff0000, v117
	v_lshlrev_b32_e32 v28, 16, v118
	v_and_b32_e32 v29, 0xffff0000, v118
	v_lshlrev_b32_e32 v30, 16, v119
	v_and_b32_e32 v31, 0xffff0000, v119
	v_cvt_pk_bf16_f32 v44, v32, v33
	v_cvt_pk_bf16_f32 v45, v34, v35
	v_cvt_pk_bf16_f32 v46, v36, v37
	v_cvt_pk_bf16_f32 v47, v38, v39
	v_pk_add_f32 v[8:9], v[8:9], v[24:25] neg_lo:[0,1] neg_hi:[0,1]
	v_pk_add_f32 v[10:11], v[10:11], v[26:27] neg_lo:[0,1] neg_hi:[0,1]
	v_pk_add_f32 v[12:13], v[12:13], v[28:29] neg_lo:[0,1] neg_hi:[0,1]
	v_pk_add_f32 v[14:15], v[14:15], v[30:31] neg_lo:[0,1] neg_hi:[0,1]
	global_store_dwordx4 v1, v[44:47], s[84:85] offset:3328
	v_add_u32_e32 v6, 15, v2
	v_min_u32_e32 v6, 16, v6
	v_cvt_f32_u32_e32 v6, v6
	v_rcp_f32_e32 v4, v6
	s_waitcnt vmcnt(15)
	v_lshlrev_b32_e32 v16, 16, v180
	v_and_b32_e32 v17, 0xffff0000, v180
	v_lshlrev_b32_e32 v18, 16, v181
	v_and_b32_e32 v19, 0xffff0000, v181
	v_lshlrev_b32_e32 v20, 16, v182
	v_and_b32_e32 v21, 0xffff0000, v182
	v_lshlrev_b32_e32 v22, 16, v183
	v_and_b32_e32 v23, 0xffff0000, v183
	v_pk_add_f32 v[8:9], v[8:9], v[16:17]
	v_pk_add_f32 v[10:11], v[10:11], v[18:19]
	v_pk_add_f32 v[12:13], v[12:13], v[20:21]
	v_pk_add_f32 v[14:15], v[14:15], v[22:23]
	v_pk_fma_f32 v[32:33], v[4:5], v[8:9], v[16:17] op_sel_hi:[0,1,1] neg_lo:[0,0,1] neg_hi:[0,0,1]
	v_pk_fma_f32 v[34:35], v[4:5], v[10:11], v[18:19] op_sel_hi:[0,1,1] neg_lo:[0,0,1] neg_hi:[0,0,1]
	v_pk_fma_f32 v[36:37], v[4:5], v[12:13], v[20:21] op_sel_hi:[0,1,1] neg_lo:[0,0,1] neg_hi:[0,0,1]
	v_pk_fma_f32 v[38:39], v[4:5], v[14:15], v[22:23] op_sel_hi:[0,1,1] neg_lo:[0,0,1] neg_hi:[0,0,1]
	v_lshlrev_b32_e32 v24, 16, v120
	v_and_b32_e32 v25, 0xffff0000, v120
	v_lshlrev_b32_e32 v26, 16, v121
	v_and_b32_e32 v27, 0xffff0000, v121
	v_lshlrev_b32_e32 v28, 16, v122
	v_and_b32_e32 v29, 0xffff0000, v122
	v_lshlrev_b32_e32 v30, 16, v123
	v_and_b32_e32 v31, 0xffff0000, v123
	v_cvt_pk_bf16_f32 v40, v32, v33
	v_cvt_pk_bf16_f32 v41, v34, v35
	v_cvt_pk_bf16_f32 v42, v36, v37
	v_cvt_pk_bf16_f32 v43, v38, v39
	v_pk_add_f32 v[8:9], v[8:9], v[24:25] neg_lo:[0,1] neg_hi:[0,1]
	v_pk_add_f32 v[10:11], v[10:11], v[26:27] neg_lo:[0,1] neg_hi:[0,1]
	v_pk_add_f32 v[12:13], v[12:13], v[28:29] neg_lo:[0,1] neg_hi:[0,1]
	v_pk_add_f32 v[14:15], v[14:15], v[30:31] neg_lo:[0,1] neg_hi:[0,1]
	global_store_dwordx4 v1, v[40:43], s[84:85] offset:3584
	v_add_u32_e32 v6, 16, v2
	v_min_u32_e32 v6, 16, v6
	v_cvt_f32_u32_e32 v6, v6
	v_rcp_f32_e32 v4, v6
	s_waitcnt vmcnt(15)
	v_lshlrev_b32_e32 v16, 16, v184
	v_and_b32_e32 v17, 0xffff0000, v184
	v_lshlrev_b32_e32 v18, 16, v185
	v_and_b32_e32 v19, 0xffff0000, v185
	v_lshlrev_b32_e32 v20, 16, v186
	v_and_b32_e32 v21, 0xffff0000, v186
	v_lshlrev_b32_e32 v22, 16, v187
	v_and_b32_e32 v23, 0xffff0000, v187
	v_pk_add_f32 v[8:9], v[8:9], v[16:17]
	v_pk_add_f32 v[10:11], v[10:11], v[18:19]
	v_pk_add_f32 v[12:13], v[12:13], v[20:21]
	v_pk_add_f32 v[14:15], v[14:15], v[22:23]
	v_pk_fma_f32 v[32:33], v[4:5], v[8:9], v[16:17] op_sel_hi:[0,1,1] neg_lo:[0,0,1] neg_hi:[0,0,1]
	v_pk_fma_f32 v[34:35], v[4:5], v[10:11], v[18:19] op_sel_hi:[0,1,1] neg_lo:[0,0,1] neg_hi:[0,0,1]
	v_pk_fma_f32 v[36:37], v[4:5], v[12:13], v[20:21] op_sel_hi:[0,1,1] neg_lo:[0,0,1] neg_hi:[0,0,1]
	v_pk_fma_f32 v[38:39], v[4:5], v[14:15], v[22:23] op_sel_hi:[0,1,1] neg_lo:[0,0,1] neg_hi:[0,0,1]
	v_cvt_pk_bf16_f32 v44, v32, v33
	v_cvt_pk_bf16_f32 v45, v34, v35
	v_cvt_pk_bf16_f32 v46, v36, v37
	v_cvt_pk_bf16_f32 v47, v38, v39
	global_store_dwordx4 v1, v[44:47], s[84:85] offset:3840
	v_add_u32_e32 v0, 0x4000, v0
	v_add_u32_e32 v1, 0x1000, v1
	v_add_u32_e32 v2, 16, v2
	s_add_i32 s4, s4, 1
	s_cmp_lt_u32 s4, 2
	s_cbranch_scc1 .Lpool_pass_w16
	s_branch .Lpool_done

; __device__ __forceinline__ float bf_lo(unsigned w) { return __uint_as_float(w << 16); }
; __device__ __forceinline__ float bf_hi(unsigned w) { return __uint_as_float(w & 0xffff0000u); }
; template <int W> __device__ __forceinline__ v4u pool_window(const bf16* up, int t) {
;     ...
;     for (int j = 0; j < W; ++j) q[j] = *(const v4u*)(up - (size_t)((j <= t) ? j : 0) * 512);
;     float acc[8];
; #pragma unroll
;     for (int e = 0; e < 8; ++e) acc[e] = 0.f;
; #pragma unroll
;     for (int j = 0; j < W; ++j) { const float wgt = (j <= t) ? 1.f : 0.f;
;         acc[0] += wgt * pg8::bf_lo(q[j].x); acc[1] += wgt * pg8::bf_hi(q[j].x); acc[2] += wgt * pg8::bf_lo(q[j].y); acc[3] += wgt * pg8::bf_hi(q[j].y);
;         acc[4] += wgt * pg8::bf_lo(q[j].z); acc[5] += wgt * pg8::bf_hi(q[j].z); acc[6] += wgt * pg8::bf_lo(q[j].w); acc[7] += wgt * pg8::bf_hi(q[j].w); }
; __global__ void __launch_bounds__(NWAVES * 64, 2) hybrid_fwd(Args a) {
;     ...
;         for (int wi = gw; wi < M; wi += NGW) {
;             const int rq = wi >> 2, gp = ((wi & 3) + (wi >> 11)) & 3;
;             const int row = 4 * rq + (lane >> 4), t = row & (SEQ - 1);
;             const bf16* up = Ub + (size_t)row * 512 + gp * 128 + (lane & 15) * 8;
;             v4u o;
;             if (gp == 0) o = pool_window<2>(up, t); else if (gp == 1) o = pool_window<4>(up, t); else if (gp == 2) o = pool_window<8>(up, t); else o = pool_window<16>(up, t);
;             *(v4u*)(Dp + ((size_t)gp * M + row) * 128 + (lane & 15) * 8) = o;
.Lpool_pass_w8:
	v_mov_b32_e32 v64, 0
	v_mov_b32_e32 v65, 0
	v_mov_b32_e32 v66, 0
	v_mov_b32_e32 v67, 0
	v_mov_b32_e32 v68, 0
	v_mov_b32_e32 v69, 0
	v_mov_b32_e32 v70, 0
	v_mov_b32_e32 v71, 0
	v_mov_b32_e32 v72, 0
	v_mov_b32_e32 v73, 0
	v_mov_b32_e32 v74, 0
	v_mov_b32_e32 v75, 0
	v_mov_b32_e32 v76, 0
	v_mov_b32_e32 v77, 0
	v_mov_b32_e32 v78, 0
	v_mov_b32_e32 v79, 0
	v_mov_b32_e32 v80, 0
	v_mov_b32_e32 v81, 0
	v_mov_b32_e32 v82, 0
	v_mov_b32_e32 v83, 0
	v_mov_b32_e32 v84, 0
	v_mov_b32_e32 v85, 0
	v_mov_b32_e32 v86, 0
	v_mov_b32_e32 v87, 0
	v_mov_b32_e32 v88, 0
	v_mov_b32_e32 v89, 0
	v_mov_b32_e32 v90, 0
	v_mov_b32_e32 v91, 0
	v_cmp_ne_u32_e32 vcc, 0, v2
	s_and_saveexec_b64 s[2:3], vcc
	v_subrev_u32_e32 v3, 0x2000, v0
	global_load_dwordx4 v[64:67], v3, s[34:35] offset:1024
	global_load_dwordx4 v[68:71], v3, s[34:35] offset:2048
	global_load_dwordx4 v[72:75], v3, s[34:35] offset:3072
	v_subrev_u32_e32 v3, 0x1000, v0
	global_load_dwordx4 v[76:79], v3, s[34:35]
	global_load_dwordx4 v[80:83], v3, s[34:35] offset:1024
	global_load_dwordx4 v[84:87], v3, s[34:35] offset:2048
	global_load_dwordx4 v[88:91], v3, s[34:35] offset:3072
	s_mov_b64 exec, s[2:3]
	global_load_dwordx4 v[92:95], v0, s[34:35]
	global_load_dwordx4 v[96:99], v0, s[34:35] offset:1024
	global_load_dwordx4 v[100:103], v0, s[34:35] offset:2048
	global_load_dwordx4 v[104:107], v0, s[34:35] offset:3072
	v_add_u32_e32 v3, 0x1000, v0
	global_load_dwordx4 v[108:111], v3, s[34:35]
	global_load_dwordx4 v[112:115], v3, s[34:35] offset:1024
	global_load_dwordx4 v[116:119], v3, s[34:35] offset:2048
	global_load_dwordx4 v[120:123], v3, s[34:35] offset:3072
	v_add_u32_e32 v3, 0x2000, v0
	global_load_dwordx4 v[124:127], v3, s[34:35]
	global_load_dwordx4 v[128:131], v3, s[34:35] offset:1024
	global_load_dwordx4 v[132:135], v3, s[34:35] offset:2048
	global_load_dwordx4 v[136:139], v3, s[34:35] offset:3072
	v_add_u32_e32 v3, 0x3000, v0
	global_load_dwordx4 v[140:143], v3, s[34:35]
	global_load_dwordx4 v[144:147], v3, s[34:35] offset:1024
	global_load_dwordx4 v[148:151], v3, s[34:35] offset:2048
	global_load_dwordx4 v[152:155], v3, s[34:35] offset:3072
	v_mov_b32_e32 v8, 0
	v_mov_b32_e32 v9, 0
	v_mov_b32_e32 v10, 0
	v_mov_b32_e32 v11, 0
	v_mov_b32_e32 v12, 0
	v_mov_b32_e32 v13, 0
	v_mov_b32_e32 v14, 0
	v_mov_b32_e32 v15, 0
	s_waitcnt vmcnt(22)
	v_lshlrev_b32_e32 v16, 16, v64
	v_and_b32_e32 v17, 0xffff0000, v64
	v_lshlrev_b32_e32 v18, 16, v65
	v_and_b32_e32 v19, 0xffff0000, v65
	v_lshlrev_b32_e32 v20, 16, v66
	v_and_b32_e32 v21, 0xffff0000, v66
	v_lshlrev_b32_e32 v22, 16, v67
	v_and_b32_e32 v23, 0xffff0000, v67
	v_pk_add_f32 v[8:9], v[8:9], v[16:17]
	v_pk_add_f32 v[10:11], v[10:11], v[18:19]
	v_pk_add_f32 v[12:13], v[12:13], v[20:21]
	v_pk_add_f32 v[14:15], v[14:15], v[22:23]
	s_waitcnt vmcnt(21)
	v_lshlrev_b32_e32 v16, 16, v68
	v_and_b32_e32 v17, 0xffff0000, v68
	v_lshlrev_b32_e32 v18, 16, v69
	v_and_b32_e32 v19, 0xffff0000, v69
	v_lshlrev_b32_e32 v20, 16, v70
	v_and_b32_e32 v21, 0xffff0000, v70
	v_lshlrev_b32_e32 v22, 16, v71
	v_and_b32_e32 v23, 0xffff0000, v71
	v_pk_add_f32 v[8:9], v[8:9], v[16:17]
	v_pk_add_f32 v[10:11], v[10:11], v[18:19]
	v_pk_add_f32 v[12:13], v[12:13], v[20:21]
	v_pk_add_f32 v[14:15], v[14:15], v[22:23]
	s_waitcnt vmcnt(20)
	v_lshlrev_b32_e32 v16, 16, v72
	v_and_b32_e32 v17, 0xffff0000, v72
	v_lshlrev_b32_e32 v18, 16, v73
	v_and_b32_e32 v19, 0xffff0000, v73
	v_lshlrev_b32_e32 v20, 16, v74
	v_and_b32_e32 v21, 0xffff0000, v74
	v_lshlrev_b32_e32 v22, 16, v75
	v_and_b32_e32 v23, 0xffff0000, v75
	v_pk_add_f32 v[8:9], v[8:9], v[16:17]
	v_pk_add_f32 v[10:11], v[10:11], v[18:19]
	v_pk_add_f32 v[12:13], v[12:13], v[20:21]
	v_pk_add_f32 v[14:15], v[14:15], v[22:23]
	s_waitcnt vmcnt(19)
	v_lshlrev_b32_e32 v16, 16, v76
	v_and_b32_e32 v17, 0xffff0000, v76
	v_lshlrev_b32_e32 v18, 16, v77
	v_and_b32_e32 v19, 0xffff0000, v77
	v_lshlrev_b32_e32 v20, 16, v78
	v_and_b32_e32 v21, 0xffff0000, v78
	v_lshlrev_b32_e32 v22, 16, v79
	v_and_b32_e32 v23, 0xffff0000, v79
	v_pk_add_f32 v[8:9], v[8:9], v[16:17]
	v_pk_add_f32 v[10:11], v[10:11], v[18:19]
	v_pk_add_f32 v[12:13], v[12:13], v[20:21]
	v_pk_add_f32 v[14:15], v[14:15], v[22:23]
	s_waitcnt vmcnt(18)
	v_lshlrev_b32_e32 v16, 16, v80
	v_and_b32_e32 v17, 0xffff0000, v80
	v_lshlrev_b32_e32 v18, 16, v81
	v_and_b32_e32 v19, 0xffff0000, v81
	v_lshlrev_b32_e32 v20, 16, v82
	v_and_b32_e32 v21, 0xffff0000, v82
	v_lshlrev_b32_e32 v22, 16, v83
	v_and_b32_e32 v23, 0xffff0000, v83
	v_pk_add_f32 v[8:9], v[8:9], v[16:17]
	v_pk_add_f32 v[10:11], v[10:11], v[18:19]
	v_pk_add_f32 v[12:13], v[12:13], v[20:21]
	v_pk_add_f32 v[14:15], v[14:15], v[22:23]
	s_waitcnt vmcnt(17)
	v_lshlrev_b32_e32 v16, 16, v84
	v_and_b32_e32 v17, 0xffff0000, v84
	v_lshlrev_b32_e32 v18, 16, v85
	v_and_b32_e32 v19, 0xffff0000, v85
	v_lshlrev_b32_e32 v20, 16, v86
	v_and_b32_e32 v21, 0xffff0000, v86
	v_lshlrev_b32_e32 v22, 16, v87
	v_and_b32_e32 v23, 0xffff0000, v87
	v_pk_add_f32 v[8:9], v[8:9], v[16:17]
	v_pk_add_f32 v[10:11], v[10:11], v[18:19]
	v_pk_add_f32 v[12:13], v[12:13], v[20:21]
	v_pk_add_f32 v[14:15], v[14:15], v[22:23]
	s_waitcnt vmcnt(16)
	v_lshlrev_b32_e32 v16, 16, v88
	v_and_b32_e32 v17, 0xffff0000, v88
	v_lshlrev_b32_e32 v18, 16, v89
	v_and_b32_e32 v19, 0xffff0000, v89
	v_lshlrev_b32_e32 v20, 16, v90
	v_and_b32_e32 v21, 0xffff0000, v90
	v_lshlrev_b32_e32 v22, 16, v91
	v_and_b32_e32 v23, 0xffff0000, v91
	v_pk_add_f32 v[8:9], v[8:9], v[16:17]
	v_pk_add_f32 v[10:11], v[10:11], v[18:19]
	v_pk_add_f32 v[12:13], v[12:13], v[20:21]
	v_pk_add_f32 v[14:15], v[14:15], v[22:23]
	v_add_u32_e32 v6, 1, v2
	v_min_u32_e32 v6, 8, v6
	v_cvt_f32_u32_e32 v6, v6
	v_rcp_f32_e32 v4, v6
	s_waitcnt vmcnt(15)
; __device__ __forceinline__ float bf_lo(unsigned w) { return __uint_as_float(w << 16); }
; __device__ __forceinline__ float bf_hi(unsigned w) { return __uint_as_float(w & 0xffff0000u); }
; __device__ __forceinline__ unsigned pk2(float lo, float hi) { return f2bf(lo) | (f2bf(hi) << 16); }
; template <int W> __device__ __forceinline__ v4u pool_window(const bf16* up, int t) {
;     ...
;     for (int j = 0; j < W; ++j) { const float wgt = (j <= t) ? 1.f : 0.f;
;         acc[0] += wgt * pg8::bf_lo(q[j].x); acc[1] += wgt * pg8::bf_hi(q[j].x); acc[2] += wgt * pg8::bf_lo(q[j].y); acc[3] += wgt * pg8::bf_hi(q[j].y);
;         acc[4] += wgt * pg8::bf_lo(q[j].z); acc[5] += wgt * pg8::bf_hi(q[j].z); acc[6] += wgt * pg8::bf_lo(q[j].w); acc[7] += wgt * pg8::bf_hi(q[j].w); }
;     const float inv = 1.0f / (float)((t + 1 < W) ? (t + 1) : W);
;     v4u o;
;     o.x = pk2(acc[0] * inv - pg8::bf_lo(q[0].x), acc[1] * inv - pg8::bf_hi(q[0].x)); o.y = pk2(acc[2] * inv - pg8::bf_lo(q[0].y), acc[3] * inv - pg8::bf_hi(q[0].y));
;     o.z = pk2(acc[4] * inv - pg8::bf_lo(q[0].z), acc[5] * inv - pg8::bf_hi(q[0].z)); o.w = pk2(acc[6] * inv - pg8::bf_lo(q[0].w), acc[7] * inv - pg8::bf_hi(q[0].w));
	v_lshlrev_b32_e32 v16, 16, v92
	v_and_b32_e32 v17, 0xffff0000, v92
	v_lshlrev_b32_e32 v18, 16, v93
	v_and_b32_e32 v19, 0xffff0000, v93
	v_lshlrev_b32_e32 v20, 16, v94
	v_and_b32_e32 v21, 0xffff0000, v94
	v_lshlrev_b32_e32 v22, 16, v95
	v_and_b32_e32 v23, 0xffff0000, v95
	v_pk_add_f32 v[8:9], v[8:9], v[16:17]
	v_pk_add_f32 v[10:11], v[10:11], v[18:19]
	v_pk_add_f32 v[12:13], v[12:13], v[20:21]
	v_pk_add_f32 v[14:15], v[14:15], v[22:23]
	v_pk_fma_f32 v[32:33], v[4:5], v[8:9], v[16:17] op_sel_hi:[0,1,1] neg_lo:[0,0,1] neg_hi:[0,0,1]
	v_pk_fma_f32 v[34:35], v[4:5], v[10:11], v[18:19] op_sel_hi:[0,1,1] neg_lo:[0,0,1] neg_hi:[0,0,1]
	v_pk_fma_f32 v[36:37], v[4:5], v[12:13], v[20:21] op_sel_hi:[0,1,1] neg_lo:[0,0,1] neg_hi:[0,0,1]
	v_pk_fma_f32 v[38:39], v[4:5], v[14:15], v[22:23] op_sel_hi:[0,1,1] neg_lo:[0,0,1] neg_hi:[0,0,1]
	v_lshlrev_b32_e32 v24, 16, v64
	v_and_b32_e32 v25, 0xffff0000, v64
	v_lshlrev_b32_e32 v26, 16, v65
	v_and_b32_e32 v27, 0xffff0000, v65
	v_lshlrev_b32_e32 v28, 16, v66
	v_and_b32_e32 v29, 0xffff0000, v66
	v_lshlrev_b32_e32 v30, 16, v67
	v_and_b32_e32 v31, 0xffff0000, v67
	v_cvt_pk_bf16_f32 v40, v32, v33
	v_cvt_pk_bf16_f32 v41, v34, v35
	v_cvt_pk_bf16_f32 v42, v36, v37
	v_cvt_pk_bf16_f32 v43, v38, v39
	v_pk_add_f32 v[8:9], v[8:9], v[24:25] neg_lo:[0,1] neg_hi:[0,1]
	v_pk_add_f32 v[10:11], v[10:11], v[26:27] neg_lo:[0,1] neg_hi:[0,1]
	v_pk_add_f32 v[12:13], v[12:13], v[28:29] neg_lo:[0,1] neg_hi:[0,1]
	v_pk_add_f32 v[14:15], v[14:15], v[30:31] neg_lo:[0,1] neg_hi:[0,1]
	global_store_dwordx4 v1, v[40:43], s[84:85]
	v_add_u32_e32 v6, 2, v2
	v_min_u32_e32 v6, 8, v6
	v_cvt_f32_u32_e32 v6, v6
	v_rcp_f32_e32 v4, v6
	s_waitcnt vmcnt(15)
	v_lshlrev_b32_e32 v16, 16, v96
	v_and_b32_e32 v17, 0xffff0000, v96
	v_lshlrev_b32_e32 v18, 16, v97
	v_and_b32_e32 v19, 0xffff0000, v97
	v_lshlrev_b32_e32 v20, 16, v98
	v_and_b32_e32 v21, 0xffff0000, v98
	v_lshlrev_b32_e32 v22, 16, v99
	v_and_b32_e32 v23, 0xffff0000, v99
	v_pk_add_f32 v[8:9], v[8:9], v[16:17]
	v_pk_add_f32 v[10:11], v[10:11], v[18:19]
	v_pk_add_f32 v[12:13], v[12:13], v[20:21]
	v_pk_add_f32 v[14:15], v[14:15], v[22:23]
	v_pk_fma_f32 v[32:33], v[4:5], v[8:9], v[16:17] op_sel_hi:[0,1,1] neg_lo:[0,0,1] neg_hi:[0,0,1]
	v_pk_fma_f32 v[34:35], v[4:5], v[10:11], v[18:19] op_sel_hi:[0,1,1] neg_lo:[0,0,1] neg_hi:[0,0,1]
	v_pk_fma_f32 v[36:37], v[4:5], v[12:13], v[20:21] op_sel_hi:[0,1,1] neg_lo:[0,0,1] neg_hi:[0,0,1]
	v_pk_fma_f32 v[38:39], v[4:5], v[14:15], v[22:23] op_sel_hi:[0,1,1] neg_lo:[0,0,1] neg_hi:[0,0,1]
	v_lshlrev_b32_e32 v24, 16, v68
	v_and_b32_e32 v25, 0xffff0000, v68
	v_lshlrev_b32_e32 v26, 16, v69
	v_and_b32_e32 v27, 0xffff0000, v69
	v_lshlrev_b32_e32 v28, 16, v70
	v_and_b32_e32 v29, 0xffff0000, v70
	v_lshlrev_b32_e32 v30, 16, v71
	v_and_b32_e32 v31, 0xffff0000, v71
	v_cvt_pk_bf16_f32 v44, v32, v33
	v_cvt_pk_bf16_f32 v45, v34, v35
	v_cvt_pk_bf16_f32 v46, v36, v37
	v_cvt_pk_bf16_f32 v47, v38, v39
	v_pk_add_f32 v[8:9], v[8:9], v[24:25] neg_lo:[0,1] neg_hi:[0,1]
	v_pk_add_f32 v[10:11], v[10:11], v[26:27] neg_lo:[0,1] neg_hi:[0,1]
	v_pk_add_f32 v[12:13], v[12:13], v[28:29] neg_lo:[0,1] neg_hi:[0,1]
	v_pk_add_f32 v[14:15], v[14:15], v[30:31] neg_lo:[0,1] neg_hi:[0,1]
	global_store_dwordx4 v1, v[44:47], s[84:85] offset:256
	v_add_u32_e32 v6, 3, v2
	v_min_u32_e32 v6, 8, v6
	v_cvt_f32_u32_e32 v6, v6
	v_rcp_f32_e32 v4, v6
	s_waitcnt vmcnt(15)
	v_lshlrev_b32_e32 v16, 16, v100
	v_and_b32_e32 v17, 0xffff0000, v100
	v_lshlrev_b32_e32 v18, 16, v101
	v_and_b32_e32 v19, 0xffff0000, v101
	v_lshlrev_b32_e32 v20, 16, v102
	v_and_b32_e32 v21, 0xffff0000, v102
	v_lshlrev_b32_e32 v22, 16, v103
	v_and_b32_e32 v23, 0xffff0000, v103
	v_pk_add_f32 v[8:9], v[8:9], v[16:17]
	v_pk_add_f32 v[10:11], v[10:11], v[18:19]
	v_pk_add_f32 v[12:13], v[12:13], v[20:21]
	v_pk_add_f32 v[14:15], v[14:15], v[22:23]
	v_pk_fma_f32 v[32:33], v[4:5], v[8:9], v[16:17] op_sel_hi:[0,1,1] neg_lo:[0,0,1] neg_hi:[0,0,1]
	v_pk_fma_f32 v[34:35], v[4:5], v[10:11], v[18:19] op_sel_hi:[0,1,1] neg_lo:[0,0,1] neg_hi:[0,0,1]
	v_pk_fma_f32 v[36:37], v[4:5], v[12:13], v[20:21] op_sel_hi:[0,1,1] neg_lo:[0,0,1] neg_hi:[0,0,1]
	v_pk_fma_f32 v[38:39], v[4:5], v[14:15], v[22:23] op_sel_hi:[0,1,1] neg_lo:[0,0,1] neg_hi:[0,0,1]
	v_lshlrev_b32_e32 v24, 16, v72
	v_and_b32_e32 v25, 0xffff0000, v72
	v_lshlrev_b32_e32 v26, 16, v73
	v_and_b32_e32 v27, 0xffff0000, v73
	v_lshlrev_b32_e32 v28, 16, v74
	v_and_b32_e32 v29, 0xffff0000, v74
	v_lshlrev_b32_e32 v30, 16, v75
	v_and_b32_e32 v31, 0xffff0000, v75
	v_cvt_pk_bf16_f32 v40, v32, v33
	v_cvt_pk_bf16_f32 v41, v34, v35
	v_cvt_pk_bf16_f32 v42, v36, v37
	v_cvt_pk_bf16_f32 v43, v38, v39
	v_pk_add_f32 v[8:9], v[8:9], v[24:25] neg_lo:[0,1] neg_hi:[0,1]
	v_pk_add_f32 v[10:11], v[10:11], v[26:27] neg_lo:[0,1] neg_hi:[0,1]
	v_pk_add_f32 v[12:13], v[12:13], v[28:29] neg_lo:[0,1] neg_hi:[0,1]
	v_pk_add_f32 v[14:15], v[14:15], v[30:31] neg_lo:[0,1] neg_hi:[0,1]
	global_store_dwordx4 v1, v[40:43], s[84:85] offset:512
	v_add_u32_e32 v6, 4, v2
	v_min_u32_e32 v6, 8, v6
	v_cvt_f32_u32_e32 v6, v6
	v_rcp_f32_e32 v4, v6
	s_waitcnt vmcnt(15)
; __device__ __forceinline__ float bf_lo(unsigned w) { return __uint_as_float(w << 16); }
; __device__ __forceinline__ float bf_hi(unsigned w) { return __uint_as_float(w & 0xffff0000u); }
; __device__ __forceinline__ unsigned pk2(float lo, float hi) { return f2bf(lo) | (f2bf(hi) << 16); }
; template <int W> __device__ __forceinline__ v4u pool_window(const bf16* up, int t) {
;     ...
;     for (int j = 0; j < W; ++j) { const float wgt = (j <= t) ? 1.f : 0.f;
;         acc[0] += wgt * pg8::bf_lo(q[j].x); acc[1] += wgt * pg8::bf_hi(q[j].x); acc[2] += wgt * pg8::bf_lo(q[j].y); acc[3] += wgt * pg8::bf_hi(q[j].y);
;         acc[4] += wgt * pg8::bf_lo(q[j].z); acc[5] += wgt * pg8::bf_hi(q[j].z); acc[6] += wgt * pg8::bf_lo(q[j].w); acc[7] += wgt * pg8::bf_hi(q[j].w); }
;     const float inv = 1.0f / (float)((t + 1 < W) ? (t + 1) : W);
;     v4u o;
;     o.x = pk2(acc[0] * inv - pg8::bf_lo(q[0].x), acc[1] * inv - pg8::bf_hi(q[0].x)); o.y = pk2(acc[2] * inv - pg8::bf_lo(q[0].y), acc[3] * inv - pg8::bf_hi(q[0].y));
;     o.z = pk2(acc[4] * inv - pg8::bf_lo(q[0].z), acc[5] * inv - pg8::bf_hi(q[0].z)); o.w = pk2(acc[6] * inv - pg8::bf_lo(q[0].w), acc[7] * inv - pg8::bf_hi(q[0].w));
	v_lshlrev_b32_e32 v16, 16, v104
	v_and_b32_e32 v17, 0xffff0000, v104
	v_lshlrev_b32_e32 v18, 16, v105
	v_and_b32_e32 v19, 0xffff0000, v105
	v_lshlrev_b32_e32 v20, 16, v106
	v_and_b32_e32 v21, 0xffff0000, v106
	v_lshlrev_b32_e32 v22, 16, v107
	v_and_b32_e32 v23, 0xffff0000, v107
	v_pk_add_f32 v[8:9], v[8:9], v[16:17]
	v_pk_add_f32 v[10:11], v[10:11], v[18:19]
	v_pk_add_f32 v[12:13], v[12:13], v[20:21]
	v_pk_add_f32 v[14:15], v[14:15], v[22:23]
	v_pk_fma_f32 v[32:33], v[4:5], v[8:9], v[16:17] op_sel_hi:[0,1,1] neg_lo:[0,0,1] neg_hi:[0,0,1]
	v_pk_fma_f32 v[34:35], v[4:5], v[10:11], v[18:19] op_sel_hi:[0,1,1] neg_lo:[0,0,1] neg_hi:[0,0,1]
	v_pk_fma_f32 v[36:37], v[4:5], v[12:13], v[20:21] op_sel_hi:[0,1,1] neg_lo:[0,0,1] neg_hi:[0,0,1]
	v_pk_fma_f32 v[38:39], v[4:5], v[14:15], v[22:23] op_sel_hi:[0,1,1] neg_lo:[0,0,1] neg_hi:[0,0,1]
	v_lshlrev_b32_e32 v24, 16, v76
	v_and_b32_e32 v25, 0xffff0000, v76
	v_lshlrev_b32_e32 v26, 16, v77
	v_and_b32_e32 v27, 0xffff0000, v77
	v_lshlrev_b32_e32 v28, 16, v78
	v_and_b32_e32 v29, 0xffff0000, v78
	v_lshlrev_b32_e32 v30, 16, v79
	v_and_b32_e32 v31, 0xffff0000, v79
	v_cvt_pk_bf16_f32 v44, v32, v33
	v_cvt_pk_bf16_f32 v45, v34, v35
	v_cvt_pk_bf16_f32 v46, v36, v37
	v_cvt_pk_bf16_f32 v47, v38, v39
	v_pk_add_f32 v[8:9], v[8:9], v[24:25] neg_lo:[0,1] neg_hi:[0,1]
	v_pk_add_f32 v[10:11], v[10:11], v[26:27] neg_lo:[0,1] neg_hi:[0,1]
	v_pk_add_f32 v[12:13], v[12:13], v[28:29] neg_lo:[0,1] neg_hi:[0,1]
	v_pk_add_f32 v[14:15], v[14:15], v[30:31] neg_lo:[0,1] neg_hi:[0,1]
	global_store_dwordx4 v1, v[44:47], s[84:85] offset:768
	v_add_u32_e32 v6, 5, v2
	v_min_u32_e32 v6, 8, v6
	v_cvt_f32_u32_e32 v6, v6
	v_rcp_f32_e32 v4, v6
	s_waitcnt vmcnt(15)
	v_lshlrev_b32_e32 v16, 16, v108
	v_and_b32_e32 v17, 0xffff0000, v108
	v_lshlrev_b32_e32 v18, 16, v109
	v_and_b32_e32 v19, 0xffff0000, v109
	v_lshlrev_b32_e32 v20, 16, v110
	v_and_b32_e32 v21, 0xffff0000, v110
	v_lshlrev_b32_e32 v22, 16, v111
	v_and_b32_e32 v23, 0xffff0000, v111
	v_pk_add_f32 v[8:9], v[8:9], v[16:17]
	v_pk_add_f32 v[10:11], v[10:11], v[18:19]
	v_pk_add_f32 v[12:13], v[12:13], v[20:21]
	v_pk_add_f32 v[14:15], v[14:15], v[22:23]
	v_pk_fma_f32 v[32:33], v[4:5], v[8:9], v[16:17] op_sel_hi:[0,1,1] neg_lo:[0,0,1] neg_hi:[0,0,1]
	v_pk_fma_f32 v[34:35], v[4:5], v[10:11], v[18:19] op_sel_hi:[0,1,1] neg_lo:[0,0,1] neg_hi:[0,0,1]
	v_pk_fma_f32 v[36:37], v[4:5], v[12:13], v[20:21] op_sel_hi:[0,1,1] neg_lo:[0,0,1] neg_hi:[0,0,1]
	v_pk_fma_f32 v[38:39], v[4:5], v[14:15], v[22:23] op_sel_hi:[0,1,1] neg_lo:[0,0,1] neg_hi:[0,0,1]
	v_lshlrev_b32_e32 v24, 16, v80
	v_and_b32_e32 v25, 0xffff0000, v80
	v_lshlrev_b32_e32 v26, 16, v81
	v_and_b32_e32 v27, 0xffff0000, v81
	v_lshlrev_b32_e32 v28, 16, v82
	v_and_b32_e32 v29, 0xffff0000, v82
	v_lshlrev_b32_e32 v30, 16, v83
	v_and_b32_e32 v31, 0xffff0000, v83
	v_cvt_pk_bf16_f32 v40, v32, v33
	v_cvt_pk_bf16_f32 v41, v34, v35
	v_cvt_pk_bf16_f32 v42, v36, v37
	v_cvt_pk_bf16_f32 v43, v38, v39
	v_pk_add_f32 v[8:9], v[8:9], v[24:25] neg_lo:[0,1] neg_hi:[0,1]
	v_pk_add_f32 v[10:11], v[10:11], v[26:27] neg_lo:[0,1] neg_hi:[0,1]
	v_pk_add_f32 v[12:13], v[12:13], v[28:29] neg_lo:[0,1] neg_hi:[0,1]
	v_pk_add_f32 v[14:15], v[14:15], v[30:31] neg_lo:[0,1] neg_hi:[0,1]
	global_store_dwordx4 v1, v[40:43], s[84:85] offset:1024
	v_add_u32_e32 v6, 6, v2
	v_min_u32_e32 v6, 8, v6
	v_cvt_f32_u32_e32 v6, v6
	v_rcp_f32_e32 v4, v6
	s_waitcnt vmcnt(15)
	v_lshlrev_b32_e32 v16, 16, v112
	v_and_b32_e32 v17, 0xffff0000, v112
	v_lshlrev_b32_e32 v18, 16, v113
	v_and_b32_e32 v19, 0xffff0000, v113
	v_lshlrev_b32_e32 v20, 16, v114
	v_and_b32_e32 v21, 0xffff0000, v114
	v_lshlrev_b32_e32 v22, 16, v115
	v_and_b32_e32 v23, 0xffff0000, v115
	v_pk_add_f32 v[8:9], v[8:9], v[16:17]
	v_pk_add_f32 v[10:11], v[10:11], v[18:19]
	v_pk_add_f32 v[12:13], v[12:13], v[20:21]
	v_pk_add_f32 v[14:15], v[14:15], v[22:23]
	v_pk_fma_f32 v[32:33], v[4:5], v[8:9], v[16:17] op_sel_hi:[0,1,1] neg_lo:[0,0,1] neg_hi:[0,0,1]
	v_pk_fma_f32 v[34:35], v[4:5], v[10:11], v[18:19] op_sel_hi:[0,1,1] neg_lo:[0,0,1] neg_hi:[0,0,1]
	v_pk_fma_f32 v[36:37], v[4:5], v[12:13], v[20:21] op_sel_hi:[0,1,1] neg_lo:[0,0,1] neg_hi:[0,0,1]
	v_pk_fma_f32 v[38:39], v[4:5], v[14:15], v[22:23] op_sel_hi:[0,1,1] neg_lo:[0,0,1] neg_hi:[0,0,1]
	v_lshlrev_b32_e32 v24, 16, v84
	v_and_b32_e32 v25, 0xffff0000, v84
	v_lshlrev_b32_e32 v26, 16, v85
	v_and_b32_e32 v27, 0xffff0000, v85
	v_lshlrev_b32_e32 v28, 16, v86
	v_and_b32_e32 v29, 0xffff0000, v86
	v_lshlrev_b32_e32 v30, 16, v87
	v_and_b32_e32 v31, 0xffff0000, v87
	v_cvt_pk_bf16_f32 v44, v32, v33
	v_cvt_pk_bf16_f32 v45, v34, v35
	v_cvt_pk_bf16_f32 v46, v36, v37
	v_cvt_pk_bf16_f32 v47, v38, v39
	v_pk_add_f32 v[8:9], v[8:9], v[24:25] neg_lo:[0,1] neg_hi:[0,1]
	v_pk_add_f32 v[10:11], v[10:11], v[26:27] neg_lo:[0,1] neg_hi:[0,1]
	v_pk_add_f32 v[12:13], v[12:13], v[28:29] neg_lo:[0,1] neg_hi:[0,1]
	v_pk_add_f32 v[14:15], v[14:15], v[30:31] neg_lo:[0,1] neg_hi:[0,1]
	global_store_dwordx4 v1, v[44:47], s[84:85] offset:1280
	v_add_u32_e32 v6, 7, v2
	v_min_u32_e32 v6, 8, v6
	v_cvt_f32_u32_e32 v6, v6
	v_rcp_f32_e32 v4, v6
	s_waitcnt vmcnt(15)
; __device__ __forceinline__ float bf_lo(unsigned w) { return __uint_as_float(w << 16); }
; __device__ __forceinline__ float bf_hi(unsigned w) { return __uint_as_float(w & 0xffff0000u); }
; __device__ __forceinline__ unsigned pk2(float lo, float hi) { return f2bf(lo) | (f2bf(hi) << 16); }
; template <int W> __device__ __forceinline__ v4u pool_window(const bf16* up, int t) {
;     ...
;     for (int j = 0; j < W; ++j) { const float wgt = (j <= t) ? 1.f : 0.f;
;         acc[0] += wgt * pg8::bf_lo(q[j].x); acc[1] += wgt * pg8::bf_hi(q[j].x); acc[2] += wgt * pg8::bf_lo(q[j].y); acc[3] += wgt * pg8::bf_hi(q[j].y);
;         acc[4] += wgt * pg8::bf_lo(q[j].z); acc[5] += wgt * pg8::bf_hi(q[j].z); acc[6] += wgt * pg8::bf_lo(q[j].w); acc[7] += wgt * pg8::bf_hi(q[j].w); }
;     const float inv = 1.0f / (float)((t + 1 < W) ? (t + 1) : W);
;     v4u o;
;     o.x = pk2(acc[0] * inv - pg8::bf_lo(q[0].x), acc[1] * inv - pg8::bf_hi(q[0].x)); o.y = pk2(acc[2] * inv - pg8::bf_lo(q[0].y), acc[3] * inv - pg8::bf_hi(q[0].y));
;     o.z = pk2(acc[4] * inv - pg8::bf_lo(q[0].z), acc[5] * inv - pg8::bf_hi(q[0].z)); o.w = pk2(acc[6] * inv - pg8::bf_lo(q[0].w), acc[7] * inv - pg8::bf_hi(q[0].w));
	v_lshlrev_b32_e32 v16, 16, v116
	v_and_b32_e32 v17, 0xffff0000, v116
	v_lshlrev_b32_e32 v18, 16, v117
	v_and_b32_e32 v19, 0xffff0000, v117
	v_lshlrev_b32_e32 v20, 16, v118
	v_and_b32_e32 v21, 0xffff0000, v118
	v_lshlrev_b32_e32 v22, 16, v119
	v_and_b32_e32 v23, 0xffff0000, v119
	v_pk_add_f32 v[8:9], v[8:9], v[16:17]
	v_pk_add_f32 v[10:11], v[10:11], v[18:19]
	v_pk_add_f32 v[12:13], v[12:13], v[20:21]
	v_pk_add_f32 v[14:15], v[14:15], v[22:23]
	v_pk_fma_f32 v[32:33], v[4:5], v[8:9], v[16:17] op_sel_hi:[0,1,1] neg_lo:[0,0,1] neg_hi:[0,0,1]
	v_pk_fma_f32 v[34:35], v[4:5], v[10:11], v[18:19] op_sel_hi:[0,1,1] neg_lo:[0,0,1] neg_hi:[0,0,1]
	v_pk_fma_f32 v[36:37], v[4:5], v[12:13], v[20:21] op_sel_hi:[0,1,1] neg_lo:[0,0,1] neg_hi:[0,0,1]
	v_pk_fma_f32 v[38:39], v[4:5], v[14:15], v[22:23] op_sel_hi:[0,1,1] neg_lo:[0,0,1] neg_hi:[0,0,1]
	v_lshlrev_b32_e32 v24, 16, v88
	v_and_b32_e32 v25, 0xffff0000, v88
	v_lshlrev_b32_e32 v26, 16, v89
	v_and_b32_e32 v27, 0xffff0000, v89
	v_lshlrev_b32_e32 v28, 16, v90
	v_and_b32_e32 v29, 0xffff0000, v90
	v_lshlrev_b32_e32 v30, 16, v91
	v_and_b32_e32 v31, 0xffff0000, v91
	v_cvt_pk_bf16_f32 v40, v32, v33
	v_cvt_pk_bf16_f32 v41, v34, v35
	v_cvt_pk_bf16_f32 v42, v36, v37
	v_cvt_pk_bf16_f32 v43, v38, v39
	v_pk_add_f32 v[8:9], v[8:9], v[24:25] neg_lo:[0,1] neg_hi:[0,1]
	v_pk_add_f32 v[10:11], v[10:11], v[26:27] neg_lo:[0,1] neg_hi:[0,1]
	v_pk_add_f32 v[12:13], v[12:13], v[28:29] neg_lo:[0,1] neg_hi:[0,1]
	v_pk_add_f32 v[14:15], v[14:15], v[30:31] neg_lo:[0,1] neg_hi:[0,1]
	global_store_dwordx4 v1, v[40:43], s[84:85] offset:1536
	v_add_u32_e32 v6, 8, v2
	v_min_u32_e32 v6, 8, v6
	v_cvt_f32_u32_e32 v6, v6
	v_rcp_f32_e32 v4, v6
	s_waitcnt vmcnt(15)
	v_lshlrev_b32_e32 v16, 16, v120
	v_and_b32_e32 v17, 0xffff0000, v120
	v_lshlrev_b32_e32 v18, 16, v121
	v_and_b32_e32 v19, 0xffff0000, v121
	v_lshlrev_b32_e32 v20, 16, v122
	v_and_b32_e32 v21, 0xffff0000, v122
	v_lshlrev_b32_e32 v22, 16, v123
	v_and_b32_e32 v23, 0xffff0000, v123
	v_pk_add_f32 v[8:9], v[8:9], v[16:17]
	v_pk_add_f32 v[10:11], v[10:11], v[18:19]
	v_pk_add_f32 v[12:13], v[12:13], v[20:21]
	v_pk_add_f32 v[14:15], v[14:15], v[22:23]
	v_pk_fma_f32 v[32:33], v[4:5], v[8:9], v[16:17] op_sel_hi:[0,1,1] neg_lo:[0,0,1] neg_hi:[0,0,1]
	v_pk_fma_f32 v[34:35], v[4:5], v[10:11], v[18:19] op_sel_hi:[0,1,1] neg_lo:[0,0,1] neg_hi:[0,0,1]
	v_pk_fma_f32 v[36:37], v[4:5], v[12:13], v[20:21] op_sel_hi:[0,1,1] neg_lo:[0,0,1] neg_hi:[0,0,1]
	v_pk_fma_f32 v[38:39], v[4:5], v[14:15], v[22:23] op_sel_hi:[0,1,1] neg_lo:[0,0,1] neg_hi:[0,0,1]
	v_lshlrev_b32_e32 v24, 16, v92
	v_and_b32_e32 v25, 0xffff0000, v92
	v_lshlrev_b32_e32 v26, 16, v93
	v_and_b32_e32 v27, 0xffff0000, v93
	v_lshlrev_b32_e32 v28, 16, v94
	v_and_b32_e32 v29, 0xffff0000, v94
	v_lshlrev_b32_e32 v30, 16, v95
	v_and_b32_e32 v31, 0xffff0000, v95
	v_cvt_pk_bf16_f32 v44, v32, v33
	v_cvt_pk_bf16_f32 v45, v34, v35
	v_cvt_pk_bf16_f32 v46, v36, v37
	v_cvt_pk_bf16_f32 v47, v38, v39
	v_pk_add_f32 v[8:9], v[8:9], v[24:25] neg_lo:[0,1] neg_hi:[0,1]
	v_pk_add_f32 v[10:11], v[10:11], v[26:27] neg_lo:[0,1] neg_hi:[0,1]
	v_pk_add_f32 v[12:13], v[12:13], v[28:29] neg_lo:[0,1] neg_hi:[0,1]
	v_pk_add_f32 v[14:15], v[14:15], v[30:31] neg_lo:[0,1] neg_hi:[0,1]
	global_store_dwordx4 v1, v[44:47], s[84:85] offset:1792
	v_add_u32_e32 v6, 9, v2
	v_min_u32_e32 v6, 8, v6
	v_cvt_f32_u32_e32 v6, v6
	v_rcp_f32_e32 v4, v6
	s_waitcnt vmcnt(15)
	v_lshlrev_b32_e32 v16, 16, v124
	v_and_b32_e32 v17, 0xffff0000, v124
	v_lshlrev_b32_e32 v18, 16, v125
	v_and_b32_e32 v19, 0xffff0000, v125
	v_lshlrev_b32_e32 v20, 16, v126
	v_and_b32_e32 v21, 0xffff0000, v126
	v_lshlrev_b32_e32 v22, 16, v127
	v_and_b32_e32 v23, 0xffff0000, v127
	v_pk_add_f32 v[8:9], v[8:9], v[16:17]
	v_pk_add_f32 v[10:11], v[10:11], v[18:19]
	v_pk_add_f32 v[12:13], v[12:13], v[20:21]
	v_pk_add_f32 v[14:15], v[14:15], v[22:23]
	v_pk_fma_f32 v[32:33], v[4:5], v[8:9], v[16:17] op_sel_hi:[0,1,1] neg_lo:[0,0,1] neg_hi:[0,0,1]
	v_pk_fma_f32 v[34:35], v[4:5], v[10:11], v[18:19] op_sel_hi:[0,1,1] neg_lo:[0,0,1] neg_hi:[0,0,1]
	v_pk_fma_f32 v[36:37], v[4:5], v[12:13], v[20:21] op_sel_hi:[0,1,1] neg_lo:[0,0,1] neg_hi:[0,0,1]
	v_pk_fma_f32 v[38:39], v[4:5], v[14:15], v[22:23] op_sel_hi:[0,1,1] neg_lo:[0,0,1] neg_hi:[0,0,1]
	v_lshlrev_b32_e32 v24, 16, v96
	v_and_b32_e32 v25, 0xffff0000, v96
	v_lshlrev_b32_e32 v26, 16, v97
	v_and_b32_e32 v27, 0xffff0000, v97
	v_lshlrev_b32_e32 v28, 16, v98
	v_and_b32_e32 v29, 0xffff0000, v98
	v_lshlrev_b32_e32 v30, 16, v99
	v_and_b32_e32 v31, 0xffff0000, v99
	v_cvt_pk_bf16_f32 v40, v32, v33
	v_cvt_pk_bf16_f32 v41, v34, v35
	v_cvt_pk_bf16_f32 v42, v36, v37
	v_cvt_pk_bf16_f32 v43, v38, v39
	v_pk_add_f32 v[8:9], v[8:9], v[24:25] neg_lo:[0,1] neg_hi:[0,1]
	v_pk_add_f32 v[10:11], v[10:11], v[26:27] neg_lo:[0,1] neg_hi:[0,1]
	v_pk_add_f32 v[12:13], v[12:13], v[28:29] neg_lo:[0,1] neg_hi:[0,1]
	v_pk_add_f32 v[14:15], v[14:15], v[30:31] neg_lo:[0,1] neg_hi:[0,1]
	global_store_dwordx4 v1, v[40:43], s[84:85] offset:2048
	v_add_u32_e32 v6, 10, v2
	v_min_u32_e32 v6, 8, v6
	v_cvt_f32_u32_e32 v6, v6
	v_rcp_f32_e32 v4, v6
	s_waitcnt vmcnt(15)
; __device__ __forceinline__ float bf_lo(unsigned w) { return __uint_as_float(w << 16); }
; __device__ __forceinline__ float bf_hi(unsigned w) { return __uint_as_float(w & 0xffff0000u); }
; __device__ __forceinline__ unsigned pk2(float lo, float hi) { return f2bf(lo) | (f2bf(hi) << 16); }
; template <int W> __device__ __forceinline__ v4u pool_window(const bf16* up, int t) {
;     ...
;     for (int j = 0; j < W; ++j) { const float wgt = (j <= t) ? 1.f : 0.f;
;         acc[0] += wgt * pg8::bf_lo(q[j].x); acc[1] += wgt * pg8::bf_hi(q[j].x); acc[2] += wgt * pg8::bf_lo(q[j].y); acc[3] += wgt * pg8::bf_hi(q[j].y);
;         acc[4] += wgt * pg8::bf_lo(q[j].z); acc[5] += wgt * pg8::bf_hi(q[j].z); acc[6] += wgt * pg8::bf_lo(q[j].w); acc[7] += wgt * pg8::bf_hi(q[j].w); }
;     const float inv = 1.0f / (float)((t + 1 < W) ? (t + 1) : W);
;     v4u o;
;     o.x = pk2(acc[0] * inv - pg8::bf_lo(q[0].x), acc[1] * inv - pg8::bf_hi(q[0].x)); o.y = pk2(acc[2] * inv - pg8::bf_lo(q[0].y), acc[3] * inv - pg8::bf_hi(q[0].y));
;     o.z = pk2(acc[4] * inv - pg8::bf_lo(q[0].z), acc[5] * inv - pg8::bf_hi(q[0].z)); o.w = pk2(acc[6] * inv - pg8::bf_lo(q[0].w), acc[7] * inv - pg8::bf_hi(q[0].w));
	v_lshlrev_b32_e32 v16, 16, v128
	v_and_b32_e32 v17, 0xffff0000, v128
	v_lshlrev_b32_e32 v18, 16, v129
	v_and_b32_e32 v19, 0xffff0000, v129
	v_lshlrev_b32_e32 v20, 16, v130
	v_and_b32_e32 v21, 0xffff0000, v130
	v_lshlrev_b32_e32 v22, 16, v131
	v_and_b32_e32 v23, 0xffff0000, v131
	v_pk_add_f32 v[8:9], v[8:9], v[16:17]
	v_pk_add_f32 v[10:11], v[10:11], v[18:19]
	v_pk_add_f32 v[12:13], v[12:13], v[20:21]
	v_pk_add_f32 v[14:15], v[14:15], v[22:23]
	v_pk_fma_f32 v[32:33], v[4:5], v[8:9], v[16:17] op_sel_hi:[0,1,1] neg_lo:[0,0,1] neg_hi:[0,0,1]
	v_pk_fma_f32 v[34:35], v[4:5], v[10:11], v[18:19] op_sel_hi:[0,1,1] neg_lo:[0,0,1] neg_hi:[0,0,1]
	v_pk_fma_f32 v[36:37], v[4:5], v[12:13], v[20:21] op_sel_hi:[0,1,1] neg_lo:[0,0,1] neg_hi:[0,0,1]
	v_pk_fma_f32 v[38:39], v[4:5], v[14:15], v[22:23] op_sel_hi:[0,1,1] neg_lo:[0,0,1] neg_hi:[0,0,1]
	v_lshlrev_b32_e32 v24, 16, v100
	v_and_b32_e32 v25, 0xffff0000, v100
	v_lshlrev_b32_e32 v26, 16, v101
	v_and_b32_e32 v27, 0xffff0000, v101
	v_lshlrev_b32_e32 v28, 16, v102
	v_and_b32_e32 v29, 0xffff0000, v102
	v_lshlrev_b32_e32 v30, 16, v103
	v_and_b32_e32 v31, 0xffff0000, v103
	v_cvt_pk_bf16_f32 v44, v32, v33
	v_cvt_pk_bf16_f32 v45, v34, v35
	v_cvt_pk_bf16_f32 v46, v36, v37
	v_cvt_pk_bf16_f32 v47, v38, v39
	v_pk_add_f32 v[8:9], v[8:9], v[24:25] neg_lo:[0,1] neg_hi:[0,1]
	v_pk_add_f32 v[10:11], v[10:11], v[26:27] neg_lo:[0,1] neg_hi:[0,1]
	v_pk_add_f32 v[12:13], v[12:13], v[28:29] neg_lo:[0,1] neg_hi:[0,1]
	v_pk_add_f32 v[14:15], v[14:15], v[30:31] neg_lo:[0,1] neg_hi:[0,1]
	global_store_dwordx4 v1, v[44:47], s[84:85] offset:2304
	v_add_u32_e32 v6, 11, v2
	v_min_u32_e32 v6, 8, v6
	v_cvt_f32_u32_e32 v6, v6
	v_rcp_f32_e32 v4, v6
	s_waitcnt vmcnt(15)
	v_lshlrev_b32_e32 v16, 16, v132
	v_and_b32_e32 v17, 0xffff0000, v132
	v_lshlrev_b32_e32 v18, 16, v133
	v_and_b32_e32 v19, 0xffff0000, v133
	v_lshlrev_b32_e32 v20, 16, v134
	v_and_b32_e32 v21, 0xffff0000, v134
	v_lshlrev_b32_e32 v22, 16, v135
	v_and_b32_e32 v23, 0xffff0000, v135
	v_pk_add_f32 v[8:9], v[8:9], v[16:17]
	v_pk_add_f32 v[10:11], v[10:11], v[18:19]
	v_pk_add_f32 v[12:13], v[12:13], v[20:21]
	v_pk_add_f32 v[14:15], v[14:15], v[22:23]
	v_pk_fma_f32 v[32:33], v[4:5], v[8:9], v[16:17] op_sel_hi:[0,1,1] neg_lo:[0,0,1] neg_hi:[0,0,1]
	v_pk_fma_f32 v[34:35], v[4:5], v[10:11], v[18:19] op_sel_hi:[0,1,1] neg_lo:[0,0,1] neg_hi:[0,0,1]
	v_pk_fma_f32 v[36:37], v[4:5], v[12:13], v[20:21] op_sel_hi:[0,1,1] neg_lo:[0,0,1] neg_hi:[0,0,1]
	v_pk_fma_f32 v[38:39], v[4:5], v[14:15], v[22:23] op_sel_hi:[0,1,1] neg_lo:[0,0,1] neg_hi:[0,0,1]
	v_lshlrev_b32_e32 v24, 16, v104
	v_and_b32_e32 v25, 0xffff0000, v104
	v_lshlrev_b32_e32 v26, 16, v105
	v_and_b32_e32 v27, 0xffff0000, v105
	v_lshlrev_b32_e32 v28, 16, v106
	v_and_b32_e32 v29, 0xffff0000, v106
	v_lshlrev_b32_e32 v30, 16, v107
	v_and_b32_e32 v31, 0xffff0000, v107
	v_cvt_pk_bf16_f32 v40, v32, v33
	v_cvt_pk_bf16_f32 v41, v34, v35
	v_cvt_pk_bf16_f32 v42, v36, v37
	v_cvt_pk_bf16_f32 v43, v38, v39
	v_pk_add_f32 v[8:9], v[8:9], v[24:25] neg_lo:[0,1] neg_hi:[0,1]
	v_pk_add_f32 v[10:11], v[10:11], v[26:27] neg_lo:[0,1] neg_hi:[0,1]
	v_pk_add_f32 v[12:13], v[12:13], v[28:29] neg_lo:[0,1] neg_hi:[0,1]
	v_pk_add_f32 v[14:15], v[14:15], v[30:31] neg_lo:[0,1] neg_hi:[0,1]
	global_store_dwordx4 v1, v[40:43], s[84:85] offset:2560
	v_add_u32_e32 v6, 12, v2
	v_min_u32_e32 v6, 8, v6
	v_cvt_f32_u32_e32 v6, v6
	v_rcp_f32_e32 v4, v6
	s_waitcnt vmcnt(15)
	v_lshlrev_b32_e32 v16, 16, v136
	v_and_b32_e32 v17, 0xffff0000, v136
	v_lshlrev_b32_e32 v18, 16, v137
	v_and_b32_e32 v19, 0xffff0000, v137
	v_lshlrev_b32_e32 v20, 16, v138
	v_and_b32_e32 v21, 0xffff0000, v138
	v_lshlrev_b32_e32 v22, 16, v139
	v_and_b32_e32 v23, 0xffff0000, v139
	v_pk_add_f32 v[8:9], v[8:9], v[16:17]
	v_pk_add_f32 v[10:11], v[10:11], v[18:19]
	v_pk_add_f32 v[12:13], v[12:13], v[20:21]
	v_pk_add_f32 v[14:15], v[14:15], v[22:23]
	v_pk_fma_f32 v[32:33], v[4:5], v[8:9], v[16:17] op_sel_hi:[0,1,1] neg_lo:[0,0,1] neg_hi:[0,0,1]
	v_pk_fma_f32 v[34:35], v[4:5], v[10:11], v[18:19] op_sel_hi:[0,1,1] neg_lo:[0,0,1] neg_hi:[0,0,1]
	v_pk_fma_f32 v[36:37], v[4:5], v[12:13], v[20:21] op_sel_hi:[0,1,1] neg_lo:[0,0,1] neg_hi:[0,0,1]
	v_pk_fma_f32 v[38:39], v[4:5], v[14:15], v[22:23] op_sel_hi:[0,1,1] neg_lo:[0,0,1] neg_hi:[0,0,1]
	v_lshlrev_b32_e32 v24, 16, v108
	v_and_b32_e32 v25, 0xffff0000, v108
	v_lshlrev_b32_e32 v26, 16, v109
	v_and_b32_e32 v27, 0xffff0000, v109
	v_lshlrev_b32_e32 v28, 16, v110
	v_and_b32_e32 v29, 0xffff0000, v110
	v_lshlrev_b32_e32 v30, 16, v111
	v_and_b32_e32 v31, 0xffff0000, v111
	v_cvt_pk_bf16_f32 v44, v32, v33
	v_cvt_pk_bf16_f32 v45, v34, v35
	v_cvt_pk_bf16_f32 v46, v36, v37
	v_cvt_pk_bf16_f32 v47, v38, v39
	v_pk_add_f32 v[8:9], v[8:9], v[24:25] neg_lo:[0,1] neg_hi:[0,1]
	v_pk_add_f32 v[10:11], v[10:11], v[26:27] neg_lo:[0,1] neg_hi:[0,1]
	v_pk_add_f32 v[12:13], v[12:13], v[28:29] neg_lo:[0,1] neg_hi:[0,1]
	v_pk_add_f32 v[14:15], v[14:15], v[30:31] neg_lo:[0,1] neg_hi:[0,1]
	global_store_dwordx4 v1, v[44:47], s[84:85] offset:2816
	v_add_u32_e32 v6, 13, v2
	v_min_u32_e32 v6, 8, v6
	v_cvt_f32_u32_e32 v6, v6
	v_rcp_f32_e32 v4, v6
	s_waitcnt vmcnt(15)
; __device__ __forceinline__ float bf_lo(unsigned w) { return __uint_as_float(w << 16); }
; __device__ __forceinline__ float bf_hi(unsigned w) { return __uint_as_float(w & 0xffff0000u); }
; __device__ __forceinline__ unsigned pk2(float lo, float hi) { return f2bf(lo) | (f2bf(hi) << 16); }
; template <int W> __device__ __forceinline__ v4u pool_window(const bf16* up, int t) {
;     ...
;     for (int j = 0; j < W; ++j) { const float wgt = (j <= t) ? 1.f : 0.f;
;         acc[0] += wgt * pg8::bf_lo(q[j].x); acc[1] += wgt * pg8::bf_hi(q[j].x); acc[2] += wgt * pg8::bf_lo(q[j].y); acc[3] += wgt * pg8::bf_hi(q[j].y);
;         acc[4] += wgt * pg8::bf_lo(q[j].z); acc[5] += wgt * pg8::bf_hi(q[j].z); acc[6] += wgt * pg8::bf_lo(q[j].w); acc[7] += wgt * pg8::bf_hi(q[j].w); }
;     const float inv = 1.0f / (float)((t + 1 < W) ? (t + 1) : W);
;     v4u o;
;     o.x = pk2(acc[0] * inv - pg8::bf_lo(q[0].x), acc[1] * inv - pg8::bf_hi(q[0].x)); o.y = pk2(acc[2] * inv - pg8::bf_lo(q[0].y), acc[3] * inv - pg8::bf_hi(q[0].y));
;     o.z = pk2(acc[4] * inv - pg8::bf_lo(q[0].z), acc[5] * inv - pg8::bf_hi(q[0].z)); o.w = pk2(acc[6] * inv - pg8::bf_lo(q[0].w), acc[7] * inv - pg8::bf_hi(q[0].w));
; __global__ void __launch_bounds__(NWAVES * 64, 2) hybrid_fwd(Args a) {
;     ...
;         for (int wi = gw; wi < M; wi += NGW) {
;             const int rq = wi >> 2, gp = ((wi & 3) + (wi >> 11)) & 3;
;             const int row = 4 * rq + (lane >> 4), t = row & (SEQ - 1);
;             const bf16* up = Ub + (size_t)row * 512 + gp * 128 + (lane & 15) * 8;
;             v4u o;
;             if (gp == 0) o = pool_window<2>(up, t); else if (gp == 1) o = pool_window<4>(up, t); else if (gp == 2) o = pool_window<8>(up, t); else o = pool_window<16>(up, t);
;             *(v4u*)(Dp + ((size_t)gp * M + row) * 128 + (lane & 15) * 8) = o;
	v_lshlrev_b32_e32 v16, 16, v140
	v_and_b32_e32 v17, 0xffff0000, v140
	v_lshlrev_b32_e32 v18, 16, v141
	v_and_b32_e32 v19, 0xffff0000, v141
	v_lshlrev_b32_e32 v20, 16, v142
	v_and_b32_e32 v21, 0xffff0000, v142
	v_lshlrev_b32_e32 v22, 16, v143
	v_and_b32_e32 v23, 0xffff0000, v143
	v_pk_add_f32 v[8:9], v[8:9], v[16:17]
	v_pk_add_f32 v[10:11], v[10:11], v[18:19]
	v_pk_add_f32 v[12:13], v[12:13], v[20:21]
	v_pk_add_f32 v[14:15], v[14:15], v[22:23]
	v_pk_fma_f32 v[32:33], v[4:5], v[8:9], v[16:17] op_sel_hi:[0,1,1] neg_lo:[0,0,1] neg_hi:[0,0,1]
	v_pk_fma_f32 v[34:35], v[4:5], v[10:11], v[18:19] op_sel_hi:[0,1,1] neg_lo:[0,0,1] neg_hi:[0,0,1]
	v_pk_fma_f32 v[36:37], v[4:5], v[12:13], v[20:21] op_sel_hi:[0,1,1] neg_lo:[0,0,1] neg_hi:[0,0,1]
	v_pk_fma_f32 v[38:39], v[4:5], v[14:15], v[22:23] op_sel_hi:[0,1,1] neg_lo:[0,0,1] neg_hi:[0,0,1]
	v_lshlrev_b32_e32 v24, 16, v112
	v_and_b32_e32 v25, 0xffff0000, v112
	v_lshlrev_b32_e32 v26, 16, v113
	v_and_b32_e32 v27, 0xffff0000, v113
	v_lshlrev_b32_e32 v28, 16, v114
	v_and_b32_e32 v29, 0xffff0000, v114
	v_lshlrev_b32_e32 v30, 16, v115
	v_and_b32_e32 v31, 0xffff0000, v115
	v_cvt_pk_bf16_f32 v40, v32, v33
	v_cvt_pk_bf16_f32 v41, v34, v35
	v_cvt_pk_bf16_f32 v42, v36, v37
	v_cvt_pk_bf16_f32 v43, v38, v39
	v_pk_add_f32 v[8:9], v[8:9], v[24:25] neg_lo:[0,1] neg_hi:[0,1]
	v_pk_add_f32 v[10:11], v[10:11], v[26:27] neg_lo:[0,1] neg_hi:[0,1]
	v_pk_add_f32 v[12:13], v[12:13], v[28:29] neg_lo:[0,1] neg_hi:[0,1]
	v_pk_add_f32 v[14:15], v[14:15], v[30:31] neg_lo:[0,1] neg_hi:[0,1]
	global_store_dwordx4 v1, v[40:43], s[84:85] offset:3072
	v_add_u32_e32 v6, 14, v2
	v_min_u32_e32 v6, 8, v6
	v_cvt_f32_u32_e32 v6, v6
	v_rcp_f32_e32 v4, v6
	s_waitcnt vmcnt(15)
	v_lshlrev_b32_e32 v16, 16, v144
	v_and_b32_e32 v17, 0xffff0000, v144
	v_lshlrev_b32_e32 v18, 16, v145
	v_and_b32_e32 v19, 0xffff0000, v145
	v_lshlrev_b32_e32 v20, 16, v146
	v_and_b32_e32 v21, 0xffff0000, v146
	v_lshlrev_b32_e32 v22, 16, v147
	v_and_b32_e32 v23, 0xffff0000, v147
	v_pk_add_f32 v[8:9], v[8:9], v[16:17]
	v_pk_add_f32 v[10:11], v[10:11], v[18:19]
	v_pk_add_f32 v[12:13], v[12:13], v[20:21]
	v_pk_add_f32 v[14:15], v[14:15], v[22:23]
	v_pk_fma_f32 v[32:33], v[4:5], v[8:9], v[16:17] op_sel_hi:[0,1,1] neg_lo:[0,0,1] neg_hi:[0,0,1]
	v_pk_fma_f32 v[34:35], v[4:5], v[10:11], v[18:19] op_sel_hi:[0,1,1] neg_lo:[0,0,1] neg_hi:[0,0,1]
	v_pk_fma_f32 v[36:37], v[4:5], v[12:13], v[20:21] op_sel_hi:[0,1,1] neg_lo:[0,0,1] neg_hi:[0,0,1]
	v_pk_fma_f32 v[38:39], v[4:5], v[14:15], v[22:23] op_sel_hi:[0,1,1] neg_lo:[0,0,1] neg_hi:[0,0,1]
	v_lshlrev_b32_e32 v24, 16, v116
	v_and_b32_e32 v25, 0xffff0000, v116
	v_lshlrev_b32_e32 v26, 16, v117
	v_and_b32_e32 v27, 0xffff0000, v117
	v_lshlrev_b32_e32 v28, 16, v118
	v_and_b32_e32 v29, 0xffff0000, v118
	v_lshlrev_b32_e32 v30, 16, v119
	v_and_b32_e32 v31, 0xffff0000, v119
	v_cvt_pk_bf16_f32 v44, v32, v33
	v_cvt_pk_bf16_f32 v45, v34, v35
	v_cvt_pk_bf16_f32 v46, v36, v37
	v_cvt_pk_bf16_f32 v47, v38, v39
	v_pk_add_f32 v[8:9], v[8:9], v[24:25] neg_lo:[0,1] neg_hi:[0,1]
	v_pk_add_f32 v[10:11], v[10:11], v[26:27] neg_lo:[0,1] neg_hi:[0,1]
	v_pk_add_f32 v[12:13], v[12:13], v[28:29] neg_lo:[0,1] neg_hi:[0,1]
	v_pk_add_f32 v[14:15], v[14:15], v[30:31] neg_lo:[0,1] neg_hi:[0,1]
	global_store_dwordx4 v1, v[44:47], s[84:85] offset:3328
	v_add_u32_e32 v6, 15, v2
	v_min_u32_e32 v6, 8, v6
	v_cvt_f32_u32_e32 v6, v6
	v_rcp_f32_e32 v4, v6
	s_waitcnt vmcnt(15)
	v_lshlrev_b32_e32 v16, 16, v148
	v_and_b32_e32 v17, 0xffff0000, v148
	v_lshlrev_b32_e32 v18, 16, v149
	v_and_b32_e32 v19, 0xffff0000, v149
	v_lshlrev_b32_e32 v20, 16, v150
	v_and_b32_e32 v21, 0xffff0000, v150
	v_lshlrev_b32_e32 v22, 16, v151
	v_and_b32_e32 v23, 0xffff0000, v151
	v_pk_add_f32 v[8:9], v[8:9], v[16:17]
	v_pk_add_f32 v[10:11], v[10:11], v[18:19]
	v_pk_add_f32 v[12:13], v[12:13], v[20:21]
	v_pk_add_f32 v[14:15], v[14:15], v[22:23]
	v_pk_fma_f32 v[32:33], v[4:5], v[8:9], v[16:17] op_sel_hi:[0,1,1] neg_lo:[0,0,1] neg_hi:[0,0,1]
	v_pk_fma_f32 v[34:35], v[4:5], v[10:11], v[18:19] op_sel_hi:[0,1,1] neg_lo:[0,0,1] neg_hi:[0,0,1]
	v_pk_fma_f32 v[36:37], v[4:5], v[12:13], v[20:21] op_sel_hi:[0,1,1] neg_lo:[0,0,1] neg_hi:[0,0,1]
	v_pk_fma_f32 v[38:39], v[4:5], v[14:15], v[22:23] op_sel_hi:[0,1,1] neg_lo:[0,0,1] neg_hi:[0,0,1]
	v_lshlrev_b32_e32 v24, 16, v120
	v_and_b32_e32 v25, 0xffff0000, v120
	v_lshlrev_b32_e32 v26, 16, v121
	v_and_b32_e32 v27, 0xffff0000, v121
	v_lshlrev_b32_e32 v28, 16, v122
	v_and_b32_e32 v29, 0xffff0000, v122
	v_lshlrev_b32_e32 v30, 16, v123
	v_and_b32_e32 v31, 0xffff0000, v123
	v_cvt_pk_bf16_f32 v40, v32, v33
	v_cvt_pk_bf16_f32 v41, v34, v35
	v_cvt_pk_bf16_f32 v42, v36, v37
	v_cvt_pk_bf16_f32 v43, v38, v39
	v_pk_add_f32 v[8:9], v[8:9], v[24:25] neg_lo:[0,1] neg_hi:[0,1]
	v_pk_add_f32 v[10:11], v[10:11], v[26:27] neg_lo:[0,1] neg_hi:[0,1]
	v_pk_add_f32 v[12:13], v[12:13], v[28:29] neg_lo:[0,1] neg_hi:[0,1]
	v_pk_add_f32 v[14:15], v[14:15], v[30:31] neg_lo:[0,1] neg_hi:[0,1]
	global_store_dwordx4 v1, v[40:43], s[84:85] offset:3584
	v_add_u32_e32 v6, 16, v2
	v_min_u32_e32 v6, 8, v6
	v_cvt_f32_u32_e32 v6, v6
	v_rcp_f32_e32 v4, v6
	s_waitcnt vmcnt(15)
	v_lshlrev_b32_e32 v16, 16, v152
	v_and_b32_e32 v17, 0xffff0000, v152
	v_lshlrev_b32_e32 v18, 16, v153
	v_and_b32_e32 v19, 0xffff0000, v153
	v_lshlrev_b32_e32 v20, 16, v154
	v_and_b32_e32 v21, 0xffff0000, v154
	v_lshlrev_b32_e32 v22, 16, v155
	v_and_b32_e32 v23, 0xffff0000, v155
	v_pk_add_f32 v[8:9], v[8:9], v[16:17]
	v_pk_add_f32 v[10:11], v[10:11], v[18:19]
	v_pk_add_f32 v[12:13], v[12:13], v[20:21]
	v_pk_add_f32 v[14:15], v[14:15], v[22:23]
	v_pk_fma_f32 v[32:33], v[4:5], v[8:9], v[16:17] op_sel_hi:[0,1,1] neg_lo:[0,0,1] neg_hi:[0,0,1]
	v_pk_fma_f32 v[34:35], v[4:5], v[10:11], v[18:19] op_sel_hi:[0,1,1] neg_lo:[0,0,1] neg_hi:[0,0,1]
	v_pk_fma_f32 v[36:37], v[4:5], v[12:13], v[20:21] op_sel_hi:[0,1,1] neg_lo:[0,0,1] neg_hi:[0,0,1]
	v_pk_fma_f32 v[38:39], v[4:5], v[14:15], v[22:23] op_sel_hi:[0,1,1] neg_lo:[0,0,1] neg_hi:[0,0,1]
	v_cvt_pk_bf16_f32 v44, v32, v33
	v_cvt_pk_bf16_f32 v45, v34, v35
	v_cvt_pk_bf16_f32 v46, v36, v37
	v_cvt_pk_bf16_f32 v47, v38, v39
	global_store_dwordx4 v1, v[44:47], s[84:85] offset:3840
	v_add_u32_e32 v0, 0x4000, v0
	v_add_u32_e32 v1, 0x1000, v1
	v_add_u32_e32 v2, 16, v2
	s_add_i32 s4, s4, 1
	s_cmp_lt_u32 s4, 2
	s_cbranch_scc1 .Lpool_pass_w8
	s_branch .Lpool_done

; __device__ __forceinline__ float bf_lo(unsigned w) { return __uint_as_float(w << 16); }
; __device__ __forceinline__ float bf_hi(unsigned w) { return __uint_as_float(w & 0xffff0000u); }
; __device__ __forceinline__ unsigned pk2(float lo, float hi) { return f2bf(lo) | (f2bf(hi) << 16); }
; template <int W> __device__ __forceinline__ v4u pool_window(const bf16* up, int t) {
;     ...
;     for (int j = 0; j < W; ++j) q[j] = *(const v4u*)(up - (size_t)((j <= t) ? j : 0) * 512);
;     float acc[8];
; #pragma unroll
;     for (int e = 0; e < 8; ++e) acc[e] = 0.f;
; #pragma unroll
;     for (int j = 0; j < W; ++j) { const float wgt = (j <= t) ? 1.f : 0.f;
;         acc[0] += wgt * pg8::bf_lo(q[j].x); acc[1] += wgt * pg8::bf_hi(q[j].x); acc[2] += wgt * pg8::bf_lo(q[j].y); acc[3] += wgt * pg8::bf_hi(q[j].y);
;         acc[4] += wgt * pg8::bf_lo(q[j].z); acc[5] += wgt * pg8::bf_hi(q[j].z); acc[6] += wgt * pg8::bf_lo(q[j].w); acc[7] += wgt * pg8::bf_hi(q[j].w); }
;     const float inv = 1.0f / (float)((t + 1 < W) ? (t + 1) : W);
;     v4u o;
;     o.x = pk2(acc[0] * inv - pg8::bf_lo(q[0].x), acc[1] * inv - pg8::bf_hi(q[0].x)); o.y = pk2(acc[2] * inv - pg8::bf_lo(q[0].y), acc[3] * inv - pg8::bf_hi(q[0].y));
;     o.z = pk2(acc[4] * inv - pg8::bf_lo(q[0].z), acc[5] * inv - pg8::bf_hi(q[0].z)); o.w = pk2(acc[6] * inv - pg8::bf_lo(q[0].w), acc[7] * inv - pg8::bf_hi(q[0].w));
.Lpool_pass_w4:
	v_mov_b32_e32 v64, 0
	v_mov_b32_e32 v65, 0
	v_mov_b32_e32 v66, 0
	v_mov_b32_e32 v67, 0
	v_mov_b32_e32 v68, 0
	v_mov_b32_e32 v69, 0
	v_mov_b32_e32 v70, 0
	v_mov_b32_e32 v71, 0
	v_mov_b32_e32 v72, 0
	v_mov_b32_e32 v73, 0
	v_mov_b32_e32 v74, 0
	v_mov_b32_e32 v75, 0
	v_cmp_ne_u32_e32 vcc, 0, v2
	s_and_saveexec_b64 s[2:3], vcc
	v_subrev_u32_e32 v3, 0x1000, v0
	global_load_dwordx4 v[64:67], v3, s[34:35] offset:1024
	global_load_dwordx4 v[68:71], v3, s[34:35] offset:2048
	global_load_dwordx4 v[72:75], v3, s[34:35] offset:3072
	s_mov_b64 exec, s[2:3]
	global_load_dwordx4 v[76:79], v0, s[34:35]
	global_load_dwordx4 v[80:83], v0, s[34:35] offset:1024
	global_load_dwordx4 v[84:87], v0, s[34:35] offset:2048
	global_load_dwordx4 v[88:91], v0, s[34:35] offset:3072
	v_add_u32_e32 v3, 0x1000, v0
	global_load_dwordx4 v[92:95], v3, s[34:35]
	global_load_dwordx4 v[96:99], v3, s[34:35] offset:1024
	global_load_dwordx4 v[100:103], v3, s[34:35] offset:2048
	global_load_dwordx4 v[104:107], v3, s[34:35] offset:3072
	v_add_u32_e32 v3, 0x2000, v0
	global_load_dwordx4 v[108:111], v3, s[34:35]
	global_load_dwordx4 v[112:115], v3, s[34:35] offset:1024
	global_load_dwordx4 v[116:119], v3, s[34:35] offset:2048
	global_load_dwordx4 v[120:123], v3, s[34:35] offset:3072
	v_add_u32_e32 v3, 0x3000, v0
	global_load_dwordx4 v[124:127], v3, s[34:35]
	global_load_dwordx4 v[128:131], v3, s[34:35] offset:1024
	global_load_dwordx4 v[132:135], v3, s[34:35] offset:2048
	global_load_dwordx4 v[136:139], v3, s[34:35] offset:3072
	v_mov_b32_e32 v8, 0
	v_mov_b32_e32 v9, 0
	v_mov_b32_e32 v10, 0
	v_mov_b32_e32 v11, 0
	v_mov_b32_e32 v12, 0
	v_mov_b32_e32 v13, 0
	v_mov_b32_e32 v14, 0
	v_mov_b32_e32 v15, 0
	s_waitcnt vmcnt(18)
	v_lshlrev_b32_e32 v16, 16, v64
	v_and_b32_e32 v17, 0xffff0000, v64
	v_lshlrev_b32_e32 v18, 16, v65
	v_and_b32_e32 v19, 0xffff0000, v65
	v_lshlrev_b32_e32 v20, 16, v66
	v_and_b32_e32 v21, 0xffff0000, v66
	v_lshlrev_b32_e32 v22, 16, v67
	v_and_b32_e32 v23, 0xffff0000, v67
	v_pk_add_f32 v[8:9], v[8:9], v[16:17]
	v_pk_add_f32 v[10:11], v[10:11], v[18:19]
	v_pk_add_f32 v[12:13], v[12:13], v[20:21]
	v_pk_add_f32 v[14:15], v[14:15], v[22:23]
	s_waitcnt vmcnt(17)
	v_lshlrev_b32_e32 v16, 16, v68
	v_and_b32_e32 v17, 0xffff0000, v68
	v_lshlrev_b32_e32 v18, 16, v69
	v_and_b32_e32 v19, 0xffff0000, v69
	v_lshlrev_b32_e32 v20, 16, v70
	v_and_b32_e32 v21, 0xffff0000, v70
	v_lshlrev_b32_e32 v22, 16, v71
	v_and_b32_e32 v23, 0xffff0000, v71
	v_pk_add_f32 v[8:9], v[8:9], v[16:17]
	v_pk_add_f32 v[10:11], v[10:11], v[18:19]
	v_pk_add_f32 v[12:13], v[12:13], v[20:21]
	v_pk_add_f32 v[14:15], v[14:15], v[22:23]
	s_waitcnt vmcnt(16)
	v_lshlrev_b32_e32 v16, 16, v72
	v_and_b32_e32 v17, 0xffff0000, v72
	v_lshlrev_b32_e32 v18, 16, v73
	v_and_b32_e32 v19, 0xffff0000, v73
	v_lshlrev_b32_e32 v20, 16, v74
	v_and_b32_e32 v21, 0xffff0000, v74
	v_lshlrev_b32_e32 v22, 16, v75
	v_and_b32_e32 v23, 0xffff0000, v75
	v_pk_add_f32 v[8:9], v[8:9], v[16:17]
	v_pk_add_f32 v[10:11], v[10:11], v[18:19]
	v_pk_add_f32 v[12:13], v[12:13], v[20:21]
	v_pk_add_f32 v[14:15], v[14:15], v[22:23]
	v_add_u32_e32 v6, 1, v2
	v_min_u32_e32 v6, 4, v6
	v_cvt_f32_u32_e32 v6, v6
	v_rcp_f32_e32 v4, v6
	s_waitcnt vmcnt(15)
	v_lshlrev_b32_e32 v16, 16, v76
	v_and_b32_e32 v17, 0xffff0000, v76
	v_lshlrev_b32_e32 v18, 16, v77
	v_and_b32_e32 v19, 0xffff0000, v77
	v_lshlrev_b32_e32 v20, 16, v78
	v_and_b32_e32 v21, 0xffff0000, v78
	v_lshlrev_b32_e32 v22, 16, v79
	v_and_b32_e32 v23, 0xffff0000, v79
	v_pk_add_f32 v[8:9], v[8:9], v[16:17]
	v_pk_add_f32 v[10:11], v[10:11], v[18:19]
	v_pk_add_f32 v[12:13], v[12:13], v[20:21]
	v_pk_add_f32 v[14:15], v[14:15], v[22:23]
	v_pk_fma_f32 v[32:33], v[4:5], v[8:9], v[16:17] op_sel_hi:[0,1,1] neg_lo:[0,0,1] neg_hi:[0,0,1]
	v_pk_fma_f32 v[34:35], v[4:5], v[10:11], v[18:19] op_sel_hi:[0,1,1] neg_lo:[0,0,1] neg_hi:[0,0,1]
	v_pk_fma_f32 v[36:37], v[4:5], v[12:13], v[20:21] op_sel_hi:[0,1,1] neg_lo:[0,0,1] neg_hi:[0,0,1]
	v_pk_fma_f32 v[38:39], v[4:5], v[14:15], v[22:23] op_sel_hi:[0,1,1] neg_lo:[0,0,1] neg_hi:[0,0,1]
	v_lshlrev_b32_e32 v24, 16, v64
	v_and_b32_e32 v25, 0xffff0000, v64
	v_lshlrev_b32_e32 v26, 16, v65
	v_and_b32_e32 v27, 0xffff0000, v65
	v_lshlrev_b32_e32 v28, 16, v66
	v_and_b32_e32 v29, 0xffff0000, v66
	v_lshlrev_b32_e32 v30, 16, v67
	v_and_b32_e32 v31, 0xffff0000, v67
	v_cvt_pk_bf16_f32 v40, v32, v33
	v_cvt_pk_bf16_f32 v41, v34, v35
	v_cvt_pk_bf16_f32 v42, v36, v37
	v_cvt_pk_bf16_f32 v43, v38, v39
	v_pk_add_f32 v[8:9], v[8:9], v[24:25] neg_lo:[0,1] neg_hi:[0,1]
	v_pk_add_f32 v[10:11], v[10:11], v[26:27] neg_lo:[0,1] neg_hi:[0,1]
	v_pk_add_f32 v[12:13], v[12:13], v[28:29] neg_lo:[0,1] neg_hi:[0,1]
	v_pk_add_f32 v[14:15], v[14:15], v[30:31] neg_lo:[0,1] neg_hi:[0,1]
	global_store_dwordx4 v1, v[40:43], s[84:85]
	v_add_u32_e32 v6, 2, v2
	v_min_u32_e32 v6, 4, v6
	v_cvt_f32_u32_e32 v6, v6
	v_rcp_f32_e32 v4, v6
	s_waitcnt vmcnt(15)
; __device__ __forceinline__ float bf_lo(unsigned w) { return __uint_as_float(w << 16); }
; __device__ __forceinline__ float bf_hi(unsigned w) { return __uint_as_float(w & 0xffff0000u); }
; __device__ __forceinline__ unsigned pk2(float lo, float hi) { return f2bf(lo) | (f2bf(hi) << 16); }
; template <int W> __device__ __forceinline__ v4u pool_window(const bf16* up, int t) {
;     ...
;     for (int j = 0; j < W; ++j) { const float wgt = (j <= t) ? 1.f : 0.f;
;         acc[0] += wgt * pg8::bf_lo(q[j].x); acc[1] += wgt * pg8::bf_hi(q[j].x); acc[2] += wgt * pg8::bf_lo(q[j].y); acc[3] += wgt * pg8::bf_hi(q[j].y);
;         acc[4] += wgt * pg8::bf_lo(q[j].z); acc[5] += wgt * pg8::bf_hi(q[j].z); acc[6] += wgt * pg8::bf_lo(q[j].w); acc[7] += wgt * pg8::bf_hi(q[j].w); }
;     const float inv = 1.0f / (float)((t + 1 < W) ? (t + 1) : W);
;     v4u o;
;     o.x = pk2(acc[0] * inv - pg8::bf_lo(q[0].x), acc[1] * inv - pg8::bf_hi(q[0].x)); o.y = pk2(acc[2] * inv - pg8::bf_lo(q[0].y), acc[3] * inv - pg8::bf_hi(q[0].y));
;     o.z = pk2(acc[4] * inv - pg8::bf_lo(q[0].z), acc[5] * inv - pg8::bf_hi(q[0].z)); o.w = pk2(acc[6] * inv - pg8::bf_lo(q[0].w), acc[7] * inv - pg8::bf_hi(q[0].w));
	v_lshlrev_b32_e32 v16, 16, v80
	v_and_b32_e32 v17, 0xffff0000, v80
	v_lshlrev_b32_e32 v18, 16, v81
	v_and_b32_e32 v19, 0xffff0000, v81
	v_lshlrev_b32_e32 v20, 16, v82
	v_and_b32_e32 v21, 0xffff0000, v82
	v_lshlrev_b32_e32 v22, 16, v83
	v_and_b32_e32 v23, 0xffff0000, v83
	v_pk_add_f32 v[8:9], v[8:9], v[16:17]
	v_pk_add_f32 v[10:11], v[10:11], v[18:19]
	v_pk_add_f32 v[12:13], v[12:13], v[20:21]
	v_pk_add_f32 v[14:15], v[14:15], v[22:23]
	v_pk_fma_f32 v[32:33], v[4:5], v[8:9], v[16:17] op_sel_hi:[0,1,1] neg_lo:[0,0,1] neg_hi:[0,0,1]
	v_pk_fma_f32 v[34:35], v[4:5], v[10:11], v[18:19] op_sel_hi:[0,1,1] neg_lo:[0,0,1] neg_hi:[0,0,1]
	v_pk_fma_f32 v[36:37], v[4:5], v[12:13], v[20:21] op_sel_hi:[0,1,1] neg_lo:[0,0,1] neg_hi:[0,0,1]
	v_pk_fma_f32 v[38:39], v[4:5], v[14:15], v[22:23] op_sel_hi:[0,1,1] neg_lo:[0,0,1] neg_hi:[0,0,1]
	v_lshlrev_b32_e32 v24, 16, v68
	v_and_b32_e32 v25, 0xffff0000, v68
	v_lshlrev_b32_e32 v26, 16, v69
	v_and_b32_e32 v27, 0xffff0000, v69
	v_lshlrev_b32_e32 v28, 16, v70
	v_and_b32_e32 v29, 0xffff0000, v70
	v_lshlrev_b32_e32 v30, 16, v71
	v_and_b32_e32 v31, 0xffff0000, v71
	v_cvt_pk_bf16_f32 v44, v32, v33
	v_cvt_pk_bf16_f32 v45, v34, v35
	v_cvt_pk_bf16_f32 v46, v36, v37
	v_cvt_pk_bf16_f32 v47, v38, v39
	v_pk_add_f32 v[8:9], v[8:9], v[24:25] neg_lo:[0,1] neg_hi:[0,1]
	v_pk_add_f32 v[10:11], v[10:11], v[26:27] neg_lo:[0,1] neg_hi:[0,1]
	v_pk_add_f32 v[12:13], v[12:13], v[28:29] neg_lo:[0,1] neg_hi:[0,1]
	v_pk_add_f32 v[14:15], v[14:15], v[30:31] neg_lo:[0,1] neg_hi:[0,1]
	global_store_dwordx4 v1, v[44:47], s[84:85] offset:256
	v_add_u32_e32 v6, 3, v2
	v_min_u32_e32 v6, 4, v6
	v_cvt_f32_u32_e32 v6, v6
	v_rcp_f32_e32 v4, v6
	s_waitcnt vmcnt(15)
	v_lshlrev_b32_e32 v16, 16, v84
	v_and_b32_e32 v17, 0xffff0000, v84
	v_lshlrev_b32_e32 v18, 16, v85
	v_and_b32_e32 v19, 0xffff0000, v85
	v_lshlrev_b32_e32 v20, 16, v86
	v_and_b32_e32 v21, 0xffff0000, v86
	v_lshlrev_b32_e32 v22, 16, v87
	v_and_b32_e32 v23, 0xffff0000, v87
	v_pk_add_f32 v[8:9], v[8:9], v[16:17]
	v_pk_add_f32 v[10:11], v[10:11], v[18:19]
	v_pk_add_f32 v[12:13], v[12:13], v[20:21]
	v_pk_add_f32 v[14:15], v[14:15], v[22:23]
	v_pk_fma_f32 v[32:33], v[4:5], v[8:9], v[16:17] op_sel_hi:[0,1,1] neg_lo:[0,0,1] neg_hi:[0,0,1]
	v_pk_fma_f32 v[34:35], v[4:5], v[10:11], v[18:19] op_sel_hi:[0,1,1] neg_lo:[0,0,1] neg_hi:[0,0,1]
	v_pk_fma_f32 v[36:37], v[4:5], v[12:13], v[20:21] op_sel_hi:[0,1,1] neg_lo:[0,0,1] neg_hi:[0,0,1]
	v_pk_fma_f32 v[38:39], v[4:5], v[14:15], v[22:23] op_sel_hi:[0,1,1] neg_lo:[0,0,1] neg_hi:[0,0,1]
	v_lshlrev_b32_e32 v24, 16, v72
	v_and_b32_e32 v25, 0xffff0000, v72
	v_lshlrev_b32_e32 v26, 16, v73
	v_and_b32_e32 v27, 0xffff0000, v73
	v_lshlrev_b32_e32 v28, 16, v74
	v_and_b32_e32 v29, 0xffff0000, v74
	v_lshlrev_b32_e32 v30, 16, v75
	v_and_b32_e32 v31, 0xffff0000, v75
	v_cvt_pk_bf16_f32 v40, v32, v33
	v_cvt_pk_bf16_f32 v41, v34, v35
	v_cvt_pk_bf16_f32 v42, v36, v37
	v_cvt_pk_bf16_f32 v43, v38, v39
	v_pk_add_f32 v[8:9], v[8:9], v[24:25] neg_lo:[0,1] neg_hi:[0,1]
	v_pk_add_f32 v[10:11], v[10:11], v[26:27] neg_lo:[0,1] neg_hi:[0,1]
	v_pk_add_f32 v[12:13], v[12:13], v[28:29] neg_lo:[0,1] neg_hi:[0,1]
	v_pk_add_f32 v[14:15], v[14:15], v[30:31] neg_lo:[0,1] neg_hi:[0,1]
	global_store_dwordx4 v1, v[40:43], s[84:85] offset:512
	v_add_u32_e32 v6, 4, v2
	v_min_u32_e32 v6, 4, v6
	v_cvt_f32_u32_e32 v6, v6
	v_rcp_f32_e32 v4, v6
	s_waitcnt vmcnt(15)
	v_lshlrev_b32_e32 v16, 16, v88
	v_and_b32_e32 v17, 0xffff0000, v88
	v_lshlrev_b32_e32 v18, 16, v89
	v_and_b32_e32 v19, 0xffff0000, v89
	v_lshlrev_b32_e32 v20, 16, v90
	v_and_b32_e32 v21, 0xffff0000, v90
	v_lshlrev_b32_e32 v22, 16, v91
	v_and_b32_e32 v23, 0xffff0000, v91
	v_pk_add_f32 v[8:9], v[8:9], v[16:17]
	v_pk_add_f32 v[10:11], v[10:11], v[18:19]
	v_pk_add_f32 v[12:13], v[12:13], v[20:21]
	v_pk_add_f32 v[14:15], v[14:15], v[22:23]
	v_pk_fma_f32 v[32:33], v[4:5], v[8:9], v[16:17] op_sel_hi:[0,1,1] neg_lo:[0,0,1] neg_hi:[0,0,1]
	v_pk_fma_f32 v[34:35], v[4:5], v[10:11], v[18:19] op_sel_hi:[0,1,1] neg_lo:[0,0,1] neg_hi:[0,0,1]
	v_pk_fma_f32 v[36:37], v[4:5], v[12:13], v[20:21] op_sel_hi:[0,1,1] neg_lo:[0,0,1] neg_hi:[0,0,1]
	v_pk_fma_f32 v[38:39], v[4:5], v[14:15], v[22:23] op_sel_hi:[0,1,1] neg_lo:[0,0,1] neg_hi:[0,0,1]
	v_lshlrev_b32_e32 v24, 16, v76
	v_and_b32_e32 v25, 0xffff0000, v76
	v_lshlrev_b32_e32 v26, 16, v77
	v_and_b32_e32 v27, 0xffff0000, v77
	v_lshlrev_b32_e32 v28, 16, v78
	v_and_b32_e32 v29, 0xffff0000, v78
	v_lshlrev_b32_e32 v30, 16, v79
	v_and_b32_e32 v31, 0xffff0000, v79
	v_cvt_pk_bf16_f32 v44, v32, v33
	v_cvt_pk_bf16_f32 v45, v34, v35
	v_cvt_pk_bf16_f32 v46, v36, v37
	v_cvt_pk_bf16_f32 v47, v38, v39
	v_pk_add_f32 v[8:9], v[8:9], v[24:25] neg_lo:[0,1] neg_hi:[0,1]
	v_pk_add_f32 v[10:11], v[10:11], v[26:27] neg_lo:[0,1] neg_hi:[0,1]
	v_pk_add_f32 v[12:13], v[12:13], v[28:29] neg_lo:[0,1] neg_hi:[0,1]
	v_pk_add_f32 v[14:15], v[14:15], v[30:31] neg_lo:[0,1] neg_hi:[0,1]
	global_store_dwordx4 v1, v[44:47], s[84:85] offset:768
	v_add_u32_e32 v6, 5, v2
	v_min_u32_e32 v6, 4, v6
	v_cvt_f32_u32_e32 v6, v6
	v_rcp_f32_e32 v4, v6
	s_waitcnt vmcnt(15)
; __device__ __forceinline__ float bf_lo(unsigned w) { return __uint_as_float(w << 16); }
; __device__ __forceinline__ float bf_hi(unsigned w) { return __uint_as_float(w & 0xffff0000u); }
; __device__ __forceinline__ unsigned pk2(float lo, float hi) { return f2bf(lo) | (f2bf(hi) << 16); }
; template <int W> __device__ __forceinline__ v4u pool_window(const bf16* up, int t) {
;     ...
;     for (int j = 0; j < W; ++j) { const float wgt = (j <= t) ? 1.f : 0.f;
;         acc[0] += wgt * pg8::bf_lo(q[j].x); acc[1] += wgt * pg8::bf_hi(q[j].x); acc[2] += wgt * pg8::bf_lo(q[j].y); acc[3] += wgt * pg8::bf_hi(q[j].y);
;         acc[4] += wgt * pg8::bf_lo(q[j].z); acc[5] += wgt * pg8::bf_hi(q[j].z); acc[6] += wgt * pg8::bf_lo(q[j].w); acc[7] += wgt * pg8::bf_hi(q[j].w); }
;     const float inv = 1.0f / (float)((t + 1 < W) ? (t + 1) : W);
;     v4u o;
;     o.x = pk2(acc[0] * inv - pg8::bf_lo(q[0].x), acc[1] * inv - pg8::bf_hi(q[0].x)); o.y = pk2(acc[2] * inv - pg8::bf_lo(q[0].y), acc[3] * inv - pg8::bf_hi(q[0].y));
;     o.z = pk2(acc[4] * inv - pg8::bf_lo(q[0].z), acc[5] * inv - pg8::bf_hi(q[0].z)); o.w = pk2(acc[6] * inv - pg8::bf_lo(q[0].w), acc[7] * inv - pg8::bf_hi(q[0].w));
	v_lshlrev_b32_e32 v16, 16, v92
	v_and_b32_e32 v17, 0xffff0000, v92
	v_lshlrev_b32_e32 v18, 16, v93
	v_and_b32_e32 v19, 0xffff0000, v93
	v_lshlrev_b32_e32 v20, 16, v94
	v_and_b32_e32 v21, 0xffff0000, v94
	v_lshlrev_b32_e32 v22, 16, v95
	v_and_b32_e32 v23, 0xffff0000, v95
	v_pk_add_f32 v[8:9], v[8:9], v[16:17]
	v_pk_add_f32 v[10:11], v[10:11], v[18:19]
	v_pk_add_f32 v[12:13], v[12:13], v[20:21]
	v_pk_add_f32 v[14:15], v[14:15], v[22:23]
	v_pk_fma_f32 v[32:33], v[4:5], v[8:9], v[16:17] op_sel_hi:[0,1,1] neg_lo:[0,0,1] neg_hi:[0,0,1]
	v_pk_fma_f32 v[34:35], v[4:5], v[10:11], v[18:19] op_sel_hi:[0,1,1] neg_lo:[0,0,1] neg_hi:[0,0,1]
	v_pk_fma_f32 v[36:37], v[4:5], v[12:13], v[20:21] op_sel_hi:[0,1,1] neg_lo:[0,0,1] neg_hi:[0,0,1]
	v_pk_fma_f32 v[38:39], v[4:5], v[14:15], v[22:23] op_sel_hi:[0,1,1] neg_lo:[0,0,1] neg_hi:[0,0,1]
	v_lshlrev_b32_e32 v24, 16, v80
	v_and_b32_e32 v25, 0xffff0000, v80
	v_lshlrev_b32_e32 v26, 16, v81
	v_and_b32_e32 v27, 0xffff0000, v81
	v_lshlrev_b32_e32 v28, 16, v82
	v_and_b32_e32 v29, 0xffff0000, v82
	v_lshlrev_b32_e32 v30, 16, v83
	v_and_b32_e32 v31, 0xffff0000, v83
	v_cvt_pk_bf16_f32 v40, v32, v33
	v_cvt_pk_bf16_f32 v41, v34, v35
	v_cvt_pk_bf16_f32 v42, v36, v37
	v_cvt_pk_bf16_f32 v43, v38, v39
	v_pk_add_f32 v[8:9], v[8:9], v[24:25] neg_lo:[0,1] neg_hi:[0,1]
	v_pk_add_f32 v[10:11], v[10:11], v[26:27] neg_lo:[0,1] neg_hi:[0,1]
	v_pk_add_f32 v[12:13], v[12:13], v[28:29] neg_lo:[0,1] neg_hi:[0,1]
	v_pk_add_f32 v[14:15], v[14:15], v[30:31] neg_lo:[0,1] neg_hi:[0,1]
	global_store_dwordx4 v1, v[40:43], s[84:85] offset:1024
	v_add_u32_e32 v6, 6, v2
	v_min_u32_e32 v6, 4, v6
	v_cvt_f32_u32_e32 v6, v6
	v_rcp_f32_e32 v4, v6
	s_waitcnt vmcnt(15)
	v_lshlrev_b32_e32 v16, 16, v96
	v_and_b32_e32 v17, 0xffff0000, v96
	v_lshlrev_b32_e32 v18, 16, v97
	v_and_b32_e32 v19, 0xffff0000, v97
	v_lshlrev_b32_e32 v20, 16, v98
	v_and_b32_e32 v21, 0xffff0000, v98
	v_lshlrev_b32_e32 v22, 16, v99
	v_and_b32_e32 v23, 0xffff0000, v99
	v_pk_add_f32 v[8:9], v[8:9], v[16:17]
	v_pk_add_f32 v[10:11], v[10:11], v[18:19]
	v_pk_add_f32 v[12:13], v[12:13], v[20:21]
	v_pk_add_f32 v[14:15], v[14:15], v[22:23]
	v_pk_fma_f32 v[32:33], v[4:5], v[8:9], v[16:17] op_sel_hi:[0,1,1] neg_lo:[0,0,1] neg_hi:[0,0,1]
	v_pk_fma_f32 v[34:35], v[4:5], v[10:11], v[18:19] op_sel_hi:[0,1,1] neg_lo:[0,0,1] neg_hi:[0,0,1]
	v_pk_fma_f32 v[36:37], v[4:5], v[12:13], v[20:21] op_sel_hi:[0,1,1] neg_lo:[0,0,1] neg_hi:[0,0,1]
	v_pk_fma_f32 v[38:39], v[4:5], v[14:15], v[22:23] op_sel_hi:[0,1,1] neg_lo:[0,0,1] neg_hi:[0,0,1]
	v_lshlrev_b32_e32 v24, 16, v84
	v_and_b32_e32 v25, 0xffff0000, v84
	v_lshlrev_b32_e32 v26, 16, v85
	v_and_b32_e32 v27, 0xffff0000, v85
	v_lshlrev_b32_e32 v28, 16, v86
	v_and_b32_e32 v29, 0xffff0000, v86
	v_lshlrev_b32_e32 v30, 16, v87
	v_and_b32_e32 v31, 0xffff0000, v87
	v_cvt_pk_bf16_f32 v44, v32, v33
	v_cvt_pk_bf16_f32 v45, v34, v35
	v_cvt_pk_bf16_f32 v46, v36, v37
	v_cvt_pk_bf16_f32 v47, v38, v39
	v_pk_add_f32 v[8:9], v[8:9], v[24:25] neg_lo:[0,1] neg_hi:[0,1]
	v_pk_add_f32 v[10:11], v[10:11], v[26:27] neg_lo:[0,1] neg_hi:[0,1]
	v_pk_add_f32 v[12:13], v[12:13], v[28:29] neg_lo:[0,1] neg_hi:[0,1]
	v_pk_add_f32 v[14:15], v[14:15], v[30:31] neg_lo:[0,1] neg_hi:[0,1]
	global_store_dwordx4 v1, v[44:47], s[84:85] offset:1280
	v_add_u32_e32 v6, 7, v2
	v_min_u32_e32 v6, 4, v6
	v_cvt_f32_u32_e32 v6, v6
	v_rcp_f32_e32 v4, v6
	s_waitcnt vmcnt(15)
	v_lshlrev_b32_e32 v16, 16, v100
	v_and_b32_e32 v17, 0xffff0000, v100
	v_lshlrev_b32_e32 v18, 16, v101
	v_and_b32_e32 v19, 0xffff0000, v101
	v_lshlrev_b32_e32 v20, 16, v102
	v_and_b32_e32 v21, 0xffff0000, v102
	v_lshlrev_b32_e32 v22, 16, v103
	v_and_b32_e32 v23, 0xffff0000, v103
	v_pk_add_f32 v[8:9], v[8:9], v[16:17]
	v_pk_add_f32 v[10:11], v[10:11], v[18:19]
	v_pk_add_f32 v[12:13], v[12:13], v[20:21]
	v_pk_add_f32 v[14:15], v[14:15], v[22:23]
	v_pk_fma_f32 v[32:33], v[4:5], v[8:9], v[16:17] op_sel_hi:[0,1,1] neg_lo:[0,0,1] neg_hi:[0,0,1]
	v_pk_fma_f32 v[34:35], v[4:5], v[10:11], v[18:19] op_sel_hi:[0,1,1] neg_lo:[0,0,1] neg_hi:[0,0,1]
	v_pk_fma_f32 v[36:37], v[4:5], v[12:13], v[20:21] op_sel_hi:[0,1,1] neg_lo:[0,0,1] neg_hi:[0,0,1]
	v_pk_fma_f32 v[38:39], v[4:5], v[14:15], v[22:23] op_sel_hi:[0,1,1] neg_lo:[0,0,1] neg_hi:[0,0,1]
	v_lshlrev_b32_e32 v24, 16, v88
	v_and_b32_e32 v25, 0xffff0000, v88
	v_lshlrev_b32_e32 v26, 16, v89
	v_and_b32_e32 v27, 0xffff0000, v89
	v_lshlrev_b32_e32 v28, 16, v90
	v_and_b32_e32 v29, 0xffff0000, v90
	v_lshlrev_b32_e32 v30, 16, v91
	v_and_b32_e32 v31, 0xffff0000, v91
	v_cvt_pk_bf16_f32 v40, v32, v33
	v_cvt_pk_bf16_f32 v41, v34, v35
	v_cvt_pk_bf16_f32 v42, v36, v37
	v_cvt_pk_bf16_f32 v43, v38, v39
	v_pk_add_f32 v[8:9], v[8:9], v[24:25] neg_lo:[0,1] neg_hi:[0,1]
	v_pk_add_f32 v[10:11], v[10:11], v[26:27] neg_lo:[0,1] neg_hi:[0,1]
	v_pk_add_f32 v[12:13], v[12:13], v[28:29] neg_lo:[0,1] neg_hi:[0,1]
	v_pk_add_f32 v[14:15], v[14:15], v[30:31] neg_lo:[0,1] neg_hi:[0,1]
	global_store_dwordx4 v1, v[40:43], s[84:85] offset:1536
	v_add_u32_e32 v6, 8, v2
	v_min_u32_e32 v6, 4, v6
	v_cvt_f32_u32_e32 v6, v6
	v_rcp_f32_e32 v4, v6
	s_waitcnt vmcnt(15)
; __device__ __forceinline__ float bf_lo(unsigned w) { return __uint_as_float(w << 16); }
; __device__ __forceinline__ float bf_hi(unsigned w) { return __uint_as_float(w & 0xffff0000u); }
; __device__ __forceinline__ unsigned pk2(float lo, float hi) { return f2bf(lo) | (f2bf(hi) << 16); }
; template <int W> __device__ __forceinline__ v4u pool_window(const bf16* up, int t) {
;     ...
;     for (int j = 0; j < W; ++j) { const float wgt = (j <= t) ? 1.f : 0.f;
;         acc[0] += wgt * pg8::bf_lo(q[j].x); acc[1] += wgt * pg8::bf_hi(q[j].x); acc[2] += wgt * pg8::bf_lo(q[j].y); acc[3] += wgt * pg8::bf_hi(q[j].y);
;         acc[4] += wgt * pg8::bf_lo(q[j].z); acc[5] += wgt * pg8::bf_hi(q[j].z); acc[6] += wgt * pg8::bf_lo(q[j].w); acc[7] += wgt * pg8::bf_hi(q[j].w); }
;     const float inv = 1.0f / (float)((t + 1 < W) ? (t + 1) : W);
;     v4u o;
;     o.x = pk2(acc[0] * inv - pg8::bf_lo(q[0].x), acc[1] * inv - pg8::bf_hi(q[0].x)); o.y = pk2(acc[2] * inv - pg8::bf_lo(q[0].y), acc[3] * inv - pg8::bf_hi(q[0].y));
;     o.z = pk2(acc[4] * inv - pg8::bf_lo(q[0].z), acc[5] * inv - pg8::bf_hi(q[0].z)); o.w = pk2(acc[6] * inv - pg8::bf_lo(q[0].w), acc[7] * inv - pg8::bf_hi(q[0].w));
	v_lshlrev_b32_e32 v16, 16, v104
	v_and_b32_e32 v17, 0xffff0000, v104
	v_lshlrev_b32_e32 v18, 16, v105
	v_and_b32_e32 v19, 0xffff0000, v105
	v_lshlrev_b32_e32 v20, 16, v106
	v_and_b32_e32 v21, 0xffff0000, v106
	v_lshlrev_b32_e32 v22, 16, v107
	v_and_b32_e32 v23, 0xffff0000, v107
	v_pk_add_f32 v[8:9], v[8:9], v[16:17]
	v_pk_add_f32 v[10:11], v[10:11], v[18:19]
	v_pk_add_f32 v[12:13], v[12:13], v[20:21]
	v_pk_add_f32 v[14:15], v[14:15], v[22:23]
	v_pk_fma_f32 v[32:33], v[4:5], v[8:9], v[16:17] op_sel_hi:[0,1,1] neg_lo:[0,0,1] neg_hi:[0,0,1]
	v_pk_fma_f32 v[34:35], v[4:5], v[10:11], v[18:19] op_sel_hi:[0,1,1] neg_lo:[0,0,1] neg_hi:[0,0,1]
	v_pk_fma_f32 v[36:37], v[4:5], v[12:13], v[20:21] op_sel_hi:[0,1,1] neg_lo:[0,0,1] neg_hi:[0,0,1]
	v_pk_fma_f32 v[38:39], v[4:5], v[14:15], v[22:23] op_sel_hi:[0,1,1] neg_lo:[0,0,1] neg_hi:[0,0,1]
	v_lshlrev_b32_e32 v24, 16, v92
	v_and_b32_e32 v25, 0xffff0000, v92
	v_lshlrev_b32_e32 v26, 16, v93
	v_and_b32_e32 v27, 0xffff0000, v93
	v_lshlrev_b32_e32 v28, 16, v94
	v_and_b32_e32 v29, 0xffff0000, v94
	v_lshlrev_b32_e32 v30, 16, v95
	v_and_b32_e32 v31, 0xffff0000, v95
	v_cvt_pk_bf16_f32 v44, v32, v33
	v_cvt_pk_bf16_f32 v45, v34, v35
	v_cvt_pk_bf16_f32 v46, v36, v37
	v_cvt_pk_bf16_f32 v47, v38, v39
	v_pk_add_f32 v[8:9], v[8:9], v[24:25] neg_lo:[0,1] neg_hi:[0,1]
	v_pk_add_f32 v[10:11], v[10:11], v[26:27] neg_lo:[0,1] neg_hi:[0,1]
	v_pk_add_f32 v[12:13], v[12:13], v[28:29] neg_lo:[0,1] neg_hi:[0,1]
	v_pk_add_f32 v[14:15], v[14:15], v[30:31] neg_lo:[0,1] neg_hi:[0,1]
	global_store_dwordx4 v1, v[44:47], s[84:85] offset:1792
	v_add_u32_e32 v6, 9, v2
	v_min_u32_e32 v6, 4, v6
	v_cvt_f32_u32_e32 v6, v6
	v_rcp_f32_e32 v4, v6
	s_waitcnt vmcnt(15)
	v_lshlrev_b32_e32 v16, 16, v108
	v_and_b32_e32 v17, 0xffff0000, v108
	v_lshlrev_b32_e32 v18, 16, v109
	v_and_b32_e32 v19, 0xffff0000, v109
	v_lshlrev_b32_e32 v20, 16, v110
	v_and_b32_e32 v21, 0xffff0000, v110
	v_lshlrev_b32_e32 v22, 16, v111
	v_and_b32_e32 v23, 0xffff0000, v111
	v_pk_add_f32 v[8:9], v[8:9], v[16:17]
	v_pk_add_f32 v[10:11], v[10:11], v[18:19]
	v_pk_add_f32 v[12:13], v[12:13], v[20:21]
	v_pk_add_f32 v[14:15], v[14:15], v[22:23]
	v_pk_fma_f32 v[32:33], v[4:5], v[8:9], v[16:17] op_sel_hi:[0,1,1] neg_lo:[0,0,1] neg_hi:[0,0,1]
	v_pk_fma_f32 v[34:35], v[4:5], v[10:11], v[18:19] op_sel_hi:[0,1,1] neg_lo:[0,0,1] neg_hi:[0,0,1]
	v_pk_fma_f32 v[36:37], v[4:5], v[12:13], v[20:21] op_sel_hi:[0,1,1] neg_lo:[0,0,1] neg_hi:[0,0,1]
	v_pk_fma_f32 v[38:39], v[4:5], v[14:15], v[22:23] op_sel_hi:[0,1,1] neg_lo:[0,0,1] neg_hi:[0,0,1]
	v_lshlrev_b32_e32 v24, 16, v96
	v_and_b32_e32 v25, 0xffff0000, v96
	v_lshlrev_b32_e32 v26, 16, v97
	v_and_b32_e32 v27, 0xffff0000, v97
	v_lshlrev_b32_e32 v28, 16, v98
	v_and_b32_e32 v29, 0xffff0000, v98
	v_lshlrev_b32_e32 v30, 16, v99
	v_and_b32_e32 v31, 0xffff0000, v99
	v_cvt_pk_bf16_f32 v40, v32, v33
	v_cvt_pk_bf16_f32 v41, v34, v35
	v_cvt_pk_bf16_f32 v42, v36, v37
	v_cvt_pk_bf16_f32 v43, v38, v39
	v_pk_add_f32 v[8:9], v[8:9], v[24:25] neg_lo:[0,1] neg_hi:[0,1]
	v_pk_add_f32 v[10:11], v[10:11], v[26:27] neg_lo:[0,1] neg_hi:[0,1]
	v_pk_add_f32 v[12:13], v[12:13], v[28:29] neg_lo:[0,1] neg_hi:[0,1]
	v_pk_add_f32 v[14:15], v[14:15], v[30:31] neg_lo:[0,1] neg_hi:[0,1]
	global_store_dwordx4 v1, v[40:43], s[84:85] offset:2048
	v_add_u32_e32 v6, 10, v2
	v_min_u32_e32 v6, 4, v6
	v_cvt_f32_u32_e32 v6, v6
	v_rcp_f32_e32 v4, v6
	s_waitcnt vmcnt(15)
	v_lshlrev_b32_e32 v16, 16, v112
	v_and_b32_e32 v17, 0xffff0000, v112
	v_lshlrev_b32_e32 v18, 16, v113
	v_and_b32_e32 v19, 0xffff0000, v113
	v_lshlrev_b32_e32 v20, 16, v114
	v_and_b32_e32 v21, 0xffff0000, v114
	v_lshlrev_b32_e32 v22, 16, v115
	v_and_b32_e32 v23, 0xffff0000, v115
	v_pk_add_f32 v[8:9], v[8:9], v[16:17]
	v_pk_add_f32 v[10:11], v[10:11], v[18:19]
	v_pk_add_f32 v[12:13], v[12:13], v[20:21]
	v_pk_add_f32 v[14:15], v[14:15], v[22:23]
	v_pk_fma_f32 v[32:33], v[4:5], v[8:9], v[16:17] op_sel_hi:[0,1,1] neg_lo:[0,0,1] neg_hi:[0,0,1]
	v_pk_fma_f32 v[34:35], v[4:5], v[10:11], v[18:19] op_sel_hi:[0,1,1] neg_lo:[0,0,1] neg_hi:[0,0,1]
	v_pk_fma_f32 v[36:37], v[4:5], v[12:13], v[20:21] op_sel_hi:[0,1,1] neg_lo:[0,0,1] neg_hi:[0,0,1]
	v_pk_fma_f32 v[38:39], v[4:5], v[14:15], v[22:23] op_sel_hi:[0,1,1] neg_lo:[0,0,1] neg_hi:[0,0,1]
	v_lshlrev_b32_e32 v24, 16, v100
	v_and_b32_e32 v25, 0xffff0000, v100
	v_lshlrev_b32_e32 v26, 16, v101
	v_and_b32_e32 v27, 0xffff0000, v101
	v_lshlrev_b32_e32 v28, 16, v102
	v_and_b32_e32 v29, 0xffff0000, v102
	v_lshlrev_b32_e32 v30, 16, v103
	v_and_b32_e32 v31, 0xffff0000, v103
	v_cvt_pk_bf16_f32 v44, v32, v33
	v_cvt_pk_bf16_f32 v45, v34, v35
	v_cvt_pk_bf16_f32 v46, v36, v37
	v_cvt_pk_bf16_f32 v47, v38, v39
	v_pk_add_f32 v[8:9], v[8:9], v[24:25] neg_lo:[0,1] neg_hi:[0,1]
	v_pk_add_f32 v[10:11], v[10:11], v[26:27] neg_lo:[0,1] neg_hi:[0,1]
	v_pk_add_f32 v[12:13], v[12:13], v[28:29] neg_lo:[0,1] neg_hi:[0,1]
	v_pk_add_f32 v[14:15], v[14:15], v[30:31] neg_lo:[0,1] neg_hi:[0,1]
	global_store_dwordx4 v1, v[44:47], s[84:85] offset:2304
	v_add_u32_e32 v6, 11, v2
	v_min_u32_e32 v6, 4, v6
	v_cvt_f32_u32_e32 v6, v6
	v_rcp_f32_e32 v4, v6
	s_waitcnt vmcnt(15)
; __device__ __forceinline__ float bf_lo(unsigned w) { return __uint_as_float(w << 16); }
; __device__ __forceinline__ float bf_hi(unsigned w) { return __uint_as_float(w & 0xffff0000u); }
; __device__ __forceinline__ unsigned pk2(float lo, float hi) { return f2bf(lo) | (f2bf(hi) << 16); }
; template <int W> __device__ __forceinline__ v4u pool_window(const bf16* up, int t) {
;     ...
;     for (int j = 0; j < W; ++j) { const float wgt = (j <= t) ? 1.f : 0.f;
;         acc[0] += wgt * pg8::bf_lo(q[j].x); acc[1] += wgt * pg8::bf_hi(q[j].x); acc[2] += wgt * pg8::bf_lo(q[j].y); acc[3] += wgt * pg8::bf_hi(q[j].y);
;         acc[4] += wgt * pg8::bf_lo(q[j].z); acc[5] += wgt * pg8::bf_hi(q[j].z); acc[6] += wgt * pg8::bf_lo(q[j].w); acc[7] += wgt * pg8::bf_hi(q[j].w); }
;     const float inv = 1.0f / (float)((t + 1 < W) ? (t + 1) : W);
;     v4u o;
;     o.x = pk2(acc[0] * inv - pg8::bf_lo(q[0].x), acc[1] * inv - pg8::bf_hi(q[0].x)); o.y = pk2(acc[2] * inv - pg8::bf_lo(q[0].y), acc[3] * inv - pg8::bf_hi(q[0].y));
;     o.z = pk2(acc[4] * inv - pg8::bf_lo(q[0].z), acc[5] * inv - pg8::bf_hi(q[0].z)); o.w = pk2(acc[6] * inv - pg8::bf_lo(q[0].w), acc[7] * inv - pg8::bf_hi(q[0].w));
	v_lshlrev_b32_e32 v16, 16, v116
	v_and_b32_e32 v17, 0xffff0000, v116
	v_lshlrev_b32_e32 v18, 16, v117
	v_and_b32_e32 v19, 0xffff0000, v117
	v_lshlrev_b32_e32 v20, 16, v118
	v_and_b32_e32 v21, 0xffff0000, v118
	v_lshlrev_b32_e32 v22, 16, v119
	v_and_b32_e32 v23, 0xffff0000, v119
	v_pk_add_f32 v[8:9], v[8:9], v[16:17]
	v_pk_add_f32 v[10:11], v[10:11], v[18:19]
	v_pk_add_f32 v[12:13], v[12:13], v[20:21]
	v_pk_add_f32 v[14:15], v[14:15], v[22:23]
	v_pk_fma_f32 v[32:33], v[4:5], v[8:9], v[16:17] op_sel_hi:[0,1,1] neg_lo:[0,0,1] neg_hi:[0,0,1]
	v_pk_fma_f32 v[34:35], v[4:5], v[10:11], v[18:19] op_sel_hi:[0,1,1] neg_lo:[0,0,1] neg_hi:[0,0,1]
	v_pk_fma_f32 v[36:37], v[4:5], v[12:13], v[20:21] op_sel_hi:[0,1,1] neg_lo:[0,0,1] neg_hi:[0,0,1]
	v_pk_fma_f32 v[38:39], v[4:5], v[14:15], v[22:23] op_sel_hi:[0,1,1] neg_lo:[0,0,1] neg_hi:[0,0,1]
	v_lshlrev_b32_e32 v24, 16, v104
	v_and_b32_e32 v25, 0xffff0000, v104
	v_lshlrev_b32_e32 v26, 16, v105
	v_and_b32_e32 v27, 0xffff0000, v105
	v_lshlrev_b32_e32 v28, 16, v106
	v_and_b32_e32 v29, 0xffff0000, v106
	v_lshlrev_b32_e32 v30, 16, v107
	v_and_b32_e32 v31, 0xffff0000, v107
	v_cvt_pk_bf16_f32 v40, v32, v33
	v_cvt_pk_bf16_f32 v41, v34, v35
	v_cvt_pk_bf16_f32 v42, v36, v37
	v_cvt_pk_bf16_f32 v43, v38, v39
	v_pk_add_f32 v[8:9], v[8:9], v[24:25] neg_lo:[0,1] neg_hi:[0,1]
	v_pk_add_f32 v[10:11], v[10:11], v[26:27] neg_lo:[0,1] neg_hi:[0,1]
	v_pk_add_f32 v[12:13], v[12:13], v[28:29] neg_lo:[0,1] neg_hi:[0,1]
	v_pk_add_f32 v[14:15], v[14:15], v[30:31] neg_lo:[0,1] neg_hi:[0,1]
	global_store_dwordx4 v1, v[40:43], s[84:85] offset:2560
	v_add_u32_e32 v6, 12, v2
	v_min_u32_e32 v6, 4, v6
	v_cvt_f32_u32_e32 v6, v6
	v_rcp_f32_e32 v4, v6
	s_waitcnt vmcnt(15)
	v_lshlrev_b32_e32 v16, 16, v120
	v_and_b32_e32 v17, 0xffff0000, v120
	v_lshlrev_b32_e32 v18, 16, v121
	v_and_b32_e32 v19, 0xffff0000, v121
	v_lshlrev_b32_e32 v20, 16, v122
	v_and_b32_e32 v21, 0xffff0000, v122
	v_lshlrev_b32_e32 v22, 16, v123
	v_and_b32_e32 v23, 0xffff0000, v123
	v_pk_add_f32 v[8:9], v[8:9], v[16:17]
	v_pk_add_f32 v[10:11], v[10:11], v[18:19]
	v_pk_add_f32 v[12:13], v[12:13], v[20:21]
	v_pk_add_f32 v[14:15], v[14:15], v[22:23]
	v_pk_fma_f32 v[32:33], v[4:5], v[8:9], v[16:17] op_sel_hi:[0,1,1] neg_lo:[0,0,1] neg_hi:[0,0,1]
	v_pk_fma_f32 v[34:35], v[4:5], v[10:11], v[18:19] op_sel_hi:[0,1,1] neg_lo:[0,0,1] neg_hi:[0,0,1]
	v_pk_fma_f32 v[36:37], v[4:5], v[12:13], v[20:21] op_sel_hi:[0,1,1] neg_lo:[0,0,1] neg_hi:[0,0,1]
	v_pk_fma_f32 v[38:39], v[4:5], v[14:15], v[22:23] op_sel_hi:[0,1,1] neg_lo:[0,0,1] neg_hi:[0,0,1]
	v_lshlrev_b32_e32 v24, 16, v108
	v_and_b32_e32 v25, 0xffff0000, v108
	v_lshlrev_b32_e32 v26, 16, v109
	v_and_b32_e32 v27, 0xffff0000, v109
	v_lshlrev_b32_e32 v28, 16, v110
	v_and_b32_e32 v29, 0xffff0000, v110
	v_lshlrev_b32_e32 v30, 16, v111
	v_and_b32_e32 v31, 0xffff0000, v111
	v_cvt_pk_bf16_f32 v44, v32, v33
	v_cvt_pk_bf16_f32 v45, v34, v35
	v_cvt_pk_bf16_f32 v46, v36, v37
	v_cvt_pk_bf16_f32 v47, v38, v39
	v_pk_add_f32 v[8:9], v[8:9], v[24:25] neg_lo:[0,1] neg_hi:[0,1]
	v_pk_add_f32 v[10:11], v[10:11], v[26:27] neg_lo:[0,1] neg_hi:[0,1]
	v_pk_add_f32 v[12:13], v[12:13], v[28:29] neg_lo:[0,1] neg_hi:[0,1]
	v_pk_add_f32 v[14:15], v[14:15], v[30:31] neg_lo:[0,1] neg_hi:[0,1]
	global_store_dwordx4 v1, v[44:47], s[84:85] offset:2816
	v_add_u32_e32 v6, 13, v2
	v_min_u32_e32 v6, 4, v6
	v_cvt_f32_u32_e32 v6, v6
	v_rcp_f32_e32 v4, v6
	s_waitcnt vmcnt(15)
	v_lshlrev_b32_e32 v16, 16, v124
	v_and_b32_e32 v17, 0xffff0000, v124
	v_lshlrev_b32_e32 v18, 16, v125
	v_and_b32_e32 v19, 0xffff0000, v125
	v_lshlrev_b32_e32 v20, 16, v126
	v_and_b32_e32 v21, 0xffff0000, v126
	v_lshlrev_b32_e32 v22, 16, v127
	v_and_b32_e32 v23, 0xffff0000, v127
	v_pk_add_f32 v[8:9], v[8:9], v[16:17]
	v_pk_add_f32 v[10:11], v[10:11], v[18:19]
	v_pk_add_f32 v[12:13], v[12:13], v[20:21]
	v_pk_add_f32 v[14:15], v[14:15], v[22:23]
	v_pk_fma_f32 v[32:33], v[4:5], v[8:9], v[16:17] op_sel_hi:[0,1,1] neg_lo:[0,0,1] neg_hi:[0,0,1]
	v_pk_fma_f32 v[34:35], v[4:5], v[10:11], v[18:19] op_sel_hi:[0,1,1] neg_lo:[0,0,1] neg_hi:[0,0,1]
	v_pk_fma_f32 v[36:37], v[4:5], v[12:13], v[20:21] op_sel_hi:[0,1,1] neg_lo:[0,0,1] neg_hi:[0,0,1]
	v_pk_fma_f32 v[38:39], v[4:5], v[14:15], v[22:23] op_sel_hi:[0,1,1] neg_lo:[0,0,1] neg_hi:[0,0,1]
	v_lshlrev_b32_e32 v24, 16, v112
	v_and_b32_e32 v25, 0xffff0000, v112
	v_lshlrev_b32_e32 v26, 16, v113
	v_and_b32_e32 v27, 0xffff0000, v113
	v_lshlrev_b32_e32 v28, 16, v114
	v_and_b32_e32 v29, 0xffff0000, v114
	v_lshlrev_b32_e32 v30, 16, v115
	v_and_b32_e32 v31, 0xffff0000, v115
	v_cvt_pk_bf16_f32 v40, v32, v33
	v_cvt_pk_bf16_f32 v41, v34, v35
	v_cvt_pk_bf16_f32 v42, v36, v37
	v_cvt_pk_bf16_f32 v43, v38, v39
	v_pk_add_f32 v[8:9], v[8:9], v[24:25] neg_lo:[0,1] neg_hi:[0,1]
	v_pk_add_f32 v[10:11], v[10:11], v[26:27] neg_lo:[0,1] neg_hi:[0,1]
	v_pk_add_f32 v[12:13], v[12:13], v[28:29] neg_lo:[0,1] neg_hi:[0,1]
	v_pk_add_f32 v[14:15], v[14:15], v[30:31] neg_lo:[0,1] neg_hi:[0,1]
	global_store_dwordx4 v1, v[40:43], s[84:85] offset:3072
	v_add_u32_e32 v6, 14, v2
	v_min_u32_e32 v6, 4, v6
	v_cvt_f32_u32_e32 v6, v6
	v_rcp_f32_e32 v4, v6
	s_waitcnt vmcnt(15)
; __device__ __forceinline__ float bf_lo(unsigned w) { return __uint_as_float(w << 16); }
; __device__ __forceinline__ float bf_hi(unsigned w) { return __uint_as_float(w & 0xffff0000u); }
; __device__ __forceinline__ unsigned pk2(float lo, float hi) { return f2bf(lo) | (f2bf(hi) << 16); }
; template <int W> __device__ __forceinline__ v4u pool_window(const bf16* up, int t) {
;     ...
;     for (int j = 0; j < W; ++j) q[j] = *(const v4u*)(up - (size_t)((j <= t) ? j : 0) * 512);
;     float acc[8];
; #pragma unroll
;     for (int e = 0; e < 8; ++e) acc[e] = 0.f;
; #pragma unroll
;     for (int j = 0; j < W; ++j) { const float wgt = (j <= t) ? 1.f : 0.f;
;         acc[0] += wgt * pg8::bf_lo(q[j].x); acc[1] += wgt * pg8::bf_hi(q[j].x); acc[2] += wgt * pg8::bf_lo(q[j].y); acc[3] += wgt * pg8::bf_hi(q[j].y);
;         acc[4] += wgt * pg8::bf_lo(q[j].z); acc[5] += wgt * pg8::bf_hi(q[j].z); acc[6] += wgt * pg8::bf_lo(q[j].w); acc[7] += wgt * pg8::bf_hi(q[j].w); }
;     const float inv = 1.0f / (float)((t + 1 < W) ? (t + 1) : W);
;     v4u o;
;     o.x = pk2(acc[0] * inv - pg8::bf_lo(q[0].x), acc[1] * inv - pg8::bf_hi(q[0].x)); o.y = pk2(acc[2] * inv - pg8::bf_lo(q[0].y), acc[3] * inv - pg8::bf_hi(q[0].y));
;     o.z = pk2(acc[4] * inv - pg8::bf_lo(q[0].z), acc[5] * inv - pg8::bf_hi(q[0].z)); o.w = pk2(acc[6] * inv - pg8::bf_lo(q[0].w), acc[7] * inv - pg8::bf_hi(q[0].w));
	v_lshlrev_b32_e32 v16, 16, v128
	v_and_b32_e32 v17, 0xffff0000, v128
	v_lshlrev_b32_e32 v18, 16, v129
	v_and_b32_e32 v19, 0xffff0000, v129
	v_lshlrev_b32_e32 v20, 16, v130
	v_and_b32_e32 v21, 0xffff0000, v130
	v_lshlrev_b32_e32 v22, 16, v131
	v_and_b32_e32 v23, 0xffff0000, v131
	v_pk_add_f32 v[8:9], v[8:9], v[16:17]
	v_pk_add_f32 v[10:11], v[10:11], v[18:19]
	v_pk_add_f32 v[12:13], v[12:13], v[20:21]
	v_pk_add_f32 v[14:15], v[14:15], v[22:23]
	v_pk_fma_f32 v[32:33], v[4:5], v[8:9], v[16:17] op_sel_hi:[0,1,1] neg_lo:[0,0,1] neg_hi:[0,0,1]
	v_pk_fma_f32 v[34:35], v[4:5], v[10:11], v[18:19] op_sel_hi:[0,1,1] neg_lo:[0,0,1] neg_hi:[0,0,1]
	v_pk_fma_f32 v[36:37], v[4:5], v[12:13], v[20:21] op_sel_hi:[0,1,1] neg_lo:[0,0,1] neg_hi:[0,0,1]
	v_pk_fma_f32 v[38:39], v[4:5], v[14:15], v[22:23] op_sel_hi:[0,1,1] neg_lo:[0,0,1] neg_hi:[0,0,1]
	v_lshlrev_b32_e32 v24, 16, v116
	v_and_b32_e32 v25, 0xffff0000, v116
	v_lshlrev_b32_e32 v26, 16, v117
	v_and_b32_e32 v27, 0xffff0000, v117
	v_lshlrev_b32_e32 v28, 16, v118
	v_and_b32_e32 v29, 0xffff0000, v118
	v_lshlrev_b32_e32 v30, 16, v119
	v_and_b32_e32 v31, 0xffff0000, v119
	v_cvt_pk_bf16_f32 v44, v32, v33
	v_cvt_pk_bf16_f32 v45, v34, v35
	v_cvt_pk_bf16_f32 v46, v36, v37
	v_cvt_pk_bf16_f32 v47, v38, v39
	v_pk_add_f32 v[8:9], v[8:9], v[24:25] neg_lo:[0,1] neg_hi:[0,1]
	v_pk_add_f32 v[10:11], v[10:11], v[26:27] neg_lo:[0,1] neg_hi:[0,1]
	v_pk_add_f32 v[12:13], v[12:13], v[28:29] neg_lo:[0,1] neg_hi:[0,1]
	v_pk_add_f32 v[14:15], v[14:15], v[30:31] neg_lo:[0,1] neg_hi:[0,1]
	global_store_dwordx4 v1, v[44:47], s[84:85] offset:3328
	v_add_u32_e32 v6, 15, v2
	v_min_u32_e32 v6, 4, v6
	v_cvt_f32_u32_e32 v6, v6
	v_rcp_f32_e32 v4, v6
	s_waitcnt vmcnt(15)
	v_lshlrev_b32_e32 v16, 16, v132
	v_and_b32_e32 v17, 0xffff0000, v132
	v_lshlrev_b32_e32 v18, 16, v133
	v_and_b32_e32 v19, 0xffff0000, v133
	v_lshlrev_b32_e32 v20, 16, v134
	v_and_b32_e32 v21, 0xffff0000, v134
	v_lshlrev_b32_e32 v22, 16, v135
	v_and_b32_e32 v23, 0xffff0000, v135
	v_pk_add_f32 v[8:9], v[8:9], v[16:17]
	v_pk_add_f32 v[10:11], v[10:11], v[18:19]
	v_pk_add_f32 v[12:13], v[12:13], v[20:21]
	v_pk_add_f32 v[14:15], v[14:15], v[22:23]
	v_pk_fma_f32 v[32:33], v[4:5], v[8:9], v[16:17] op_sel_hi:[0,1,1] neg_lo:[0,0,1] neg_hi:[0,0,1]
	v_pk_fma_f32 v[34:35], v[4:5], v[10:11], v[18:19] op_sel_hi:[0,1,1] neg_lo:[0,0,1] neg_hi:[0,0,1]
	v_pk_fma_f32 v[36:37], v[4:5], v[12:13], v[20:21] op_sel_hi:[0,1,1] neg_lo:[0,0,1] neg_hi:[0,0,1]
	v_pk_fma_f32 v[38:39], v[4:5], v[14:15], v[22:23] op_sel_hi:[0,1,1] neg_lo:[0,0,1] neg_hi:[0,0,1]
	v_lshlrev_b32_e32 v24, 16, v120
	v_and_b32_e32 v25, 0xffff0000, v120
	v_lshlrev_b32_e32 v26, 16, v121
	v_and_b32_e32 v27, 0xffff0000, v121
	v_lshlrev_b32_e32 v28, 16, v122
	v_and_b32_e32 v29, 0xffff0000, v122
	v_lshlrev_b32_e32 v30, 16, v123
	v_and_b32_e32 v31, 0xffff0000, v123
	v_cvt_pk_bf16_f32 v40, v32, v33
	v_cvt_pk_bf16_f32 v41, v34, v35
	v_cvt_pk_bf16_f32 v42, v36, v37
	v_cvt_pk_bf16_f32 v43, v38, v39
	v_pk_add_f32 v[8:9], v[8:9], v[24:25] neg_lo:[0,1] neg_hi:[0,1]
	v_pk_add_f32 v[10:11], v[10:11], v[26:27] neg_lo:[0,1] neg_hi:[0,1]
	v_pk_add_f32 v[12:13], v[12:13], v[28:29] neg_lo:[0,1] neg_hi:[0,1]
	v_pk_add_f32 v[14:15], v[14:15], v[30:31] neg_lo:[0,1] neg_hi:[0,1]
	global_store_dwordx4 v1, v[40:43], s[84:85] offset:3584
	v_add_u32_e32 v6, 16, v2
	v_min_u32_e32 v6, 4, v6
	v_cvt_f32_u32_e32 v6, v6
	v_rcp_f32_e32 v4, v6
	s_waitcnt vmcnt(15)
	v_lshlrev_b32_e32 v16, 16, v136
	v_and_b32_e32 v17, 0xffff0000, v136
	v_lshlrev_b32_e32 v18, 16, v137
	v_and_b32_e32 v19, 0xffff0000, v137
	v_lshlrev_b32_e32 v20, 16, v138
	v_and_b32_e32 v21, 0xffff0000, v138
	v_lshlrev_b32_e32 v22, 16, v139
	v_and_b32_e32 v23, 0xffff0000, v139
	v_pk_add_f32 v[8:9], v[8:9], v[16:17]
	v_pk_add_f32 v[10:11], v[10:11], v[18:19]
	v_pk_add_f32 v[12:13], v[12:13], v[20:21]
	v_pk_add_f32 v[14:15], v[14:15], v[22:23]
	v_pk_fma_f32 v[32:33], v[4:5], v[8:9], v[16:17] op_sel_hi:[0,1,1] neg_lo:[0,0,1] neg_hi:[0,0,1]
	v_pk_fma_f32 v[34:35], v[4:5], v[10:11], v[18:19] op_sel_hi:[0,1,1] neg_lo:[0,0,1] neg_hi:[0,0,1]
	v_pk_fma_f32 v[36:37], v[4:5], v[12:13], v[20:21] op_sel_hi:[0,1,1] neg_lo:[0,0,1] neg_hi:[0,0,1]
	v_pk_fma_f32 v[38:39], v[4:5], v[14:15], v[22:23] op_sel_hi:[0,1,1] neg_lo:[0,0,1] neg_hi:[0,0,1]
	v_cvt_pk_bf16_f32 v44, v32, v33
	v_cvt_pk_bf16_f32 v45, v34, v35
	v_cvt_pk_bf16_f32 v46, v36, v37
	v_cvt_pk_bf16_f32 v47, v38, v39
	global_store_dwordx4 v1, v[44:47], s[84:85] offset:3840
	v_add_u32_e32 v0, 0x4000, v0
	v_add_u32_e32 v1, 0x1000, v1
	v_add_u32_e32 v2, 16, v2
	s_add_i32 s4, s4, 1
	s_cmp_lt_u32 s4, 2
	s_cbranch_scc1 .Lpool_pass_w4
	s_branch .Lpool_done

; __device__ __forceinline__ float bf_lo(unsigned w) { return __uint_as_float(w << 16); }
; __device__ __forceinline__ float bf_hi(unsigned w) { return __uint_as_float(w & 0xffff0000u); }
; __device__ __forceinline__ unsigned pk2(float lo, float hi) { return f2bf(lo) | (f2bf(hi) << 16); }
; template <int W> __device__ __forceinline__ v4u pool_window(const bf16* up, int t) {
;     ...
;     for (int j = 0; j < W; ++j) q[j] = *(const v4u*)(up - (size_t)((j <= t) ? j : 0) * 512);
;     float acc[8];
; #pragma unroll
;     for (int e = 0; e < 8; ++e) acc[e] = 0.f;
; #pragma unroll
;     for (int j = 0; j < W; ++j) { const float wgt = (j <= t) ? 1.f : 0.f;
;         acc[0] += wgt * pg8::bf_lo(q[j].x); acc[1] += wgt * pg8::bf_hi(q[j].x); acc[2] += wgt * pg8::bf_lo(q[j].y); acc[3] += wgt * pg8::bf_hi(q[j].y);
;         acc[4] += wgt * pg8::bf_lo(q[j].z); acc[5] += wgt * pg8::bf_hi(q[j].z); acc[6] += wgt * pg8::bf_lo(q[j].w); acc[7] += wgt * pg8::bf_hi(q[j].w); }
;     const float inv = 1.0f / (float)((t + 1 < W) ? (t + 1) : W);
;     v4u o;
;     o.x = pk2(acc[0] * inv - pg8::bf_lo(q[0].x), acc[1] * inv - pg8::bf_hi(q[0].x)); o.y = pk2(acc[2] * inv - pg8::bf_lo(q[0].y), acc[3] * inv - pg8::bf_hi(q[0].y));
;     o.z = pk2(acc[4] * inv - pg8::bf_lo(q[0].z), acc[5] * inv - pg8::bf_hi(q[0].z)); o.w = pk2(acc[6] * inv - pg8::bf_lo(q[0].w), acc[7] * inv - pg8::bf_hi(q[0].w));
.Lpool_pass_w2:
	v_mov_b32_e32 v64, 0
	v_mov_b32_e32 v65, 0
	v_mov_b32_e32 v66, 0
	v_mov_b32_e32 v67, 0
	v_cmp_ne_u32_e32 vcc, 0, v2
	s_and_saveexec_b64 s[2:3], vcc
	v_subrev_u32_e32 v3, 0x1000, v0
	global_load_dwordx4 v[64:67], v3, s[34:35] offset:3072
	s_mov_b64 exec, s[2:3]
	global_load_dwordx4 v[68:71], v0, s[34:35]
	global_load_dwordx4 v[72:75], v0, s[34:35] offset:1024
	global_load_dwordx4 v[76:79], v0, s[34:35] offset:2048
	global_load_dwordx4 v[80:83], v0, s[34:35] offset:3072
	v_add_u32_e32 v3, 0x1000, v0
	global_load_dwordx4 v[84:87], v3, s[34:35]
	global_load_dwordx4 v[88:91], v3, s[34:35] offset:1024
	global_load_dwordx4 v[92:95], v3, s[34:35] offset:2048
	global_load_dwordx4 v[96:99], v3, s[34:35] offset:3072
	v_add_u32_e32 v3, 0x2000, v0
	global_load_dwordx4 v[100:103], v3, s[34:35]
	global_load_dwordx4 v[104:107], v3, s[34:35] offset:1024
	global_load_dwordx4 v[108:111], v3, s[34:35] offset:2048
	global_load_dwordx4 v[112:115], v3, s[34:35] offset:3072
	v_add_u32_e32 v3, 0x3000, v0
	global_load_dwordx4 v[116:119], v3, s[34:35]
	global_load_dwordx4 v[120:123], v3, s[34:35] offset:1024
	global_load_dwordx4 v[124:127], v3, s[34:35] offset:2048
	global_load_dwordx4 v[128:131], v3, s[34:35] offset:3072
	v_mov_b32_e32 v8, 0
	v_mov_b32_e32 v9, 0
	v_mov_b32_e32 v10, 0
	v_mov_b32_e32 v11, 0
	v_mov_b32_e32 v12, 0
	v_mov_b32_e32 v13, 0
	v_mov_b32_e32 v14, 0
	v_mov_b32_e32 v15, 0
	s_waitcnt vmcnt(16)
	v_lshlrev_b32_e32 v16, 16, v64
	v_and_b32_e32 v17, 0xffff0000, v64
	v_lshlrev_b32_e32 v18, 16, v65
	v_and_b32_e32 v19, 0xffff0000, v65
	v_lshlrev_b32_e32 v20, 16, v66
	v_and_b32_e32 v21, 0xffff0000, v66
	v_lshlrev_b32_e32 v22, 16, v67
	v_and_b32_e32 v23, 0xffff0000, v67
	v_pk_add_f32 v[8:9], v[8:9], v[16:17]
	v_pk_add_f32 v[10:11], v[10:11], v[18:19]
	v_pk_add_f32 v[12:13], v[12:13], v[20:21]
	v_pk_add_f32 v[14:15], v[14:15], v[22:23]
	v_add_u32_e32 v6, 1, v2
	v_min_u32_e32 v6, 2, v6
	v_cvt_f32_u32_e32 v6, v6
	v_rcp_f32_e32 v4, v6
	s_waitcnt vmcnt(15)
	v_lshlrev_b32_e32 v16, 16, v68
	v_and_b32_e32 v17, 0xffff0000, v68
	v_lshlrev_b32_e32 v18, 16, v69
	v_and_b32_e32 v19, 0xffff0000, v69
	v_lshlrev_b32_e32 v20, 16, v70
	v_and_b32_e32 v21, 0xffff0000, v70
	v_lshlrev_b32_e32 v22, 16, v71
	v_and_b32_e32 v23, 0xffff0000, v71
	v_pk_add_f32 v[8:9], v[8:9], v[16:17]
	v_pk_add_f32 v[10:11], v[10:11], v[18:19]
	v_pk_add_f32 v[12:13], v[12:13], v[20:21]
	v_pk_add_f32 v[14:15], v[14:15], v[22:23]
	v_pk_fma_f32 v[32:33], v[4:5], v[8:9], v[16:17] op_sel_hi:[0,1,1] neg_lo:[0,0,1] neg_hi:[0,0,1]
	v_pk_fma_f32 v[34:35], v[4:5], v[10:11], v[18:19] op_sel_hi:[0,1,1] neg_lo:[0,0,1] neg_hi:[0,0,1]
	v_pk_fma_f32 v[36:37], v[4:5], v[12:13], v[20:21] op_sel_hi:[0,1,1] neg_lo:[0,0,1] neg_hi:[0,0,1]
	v_pk_fma_f32 v[38:39], v[4:5], v[14:15], v[22:23] op_sel_hi:[0,1,1] neg_lo:[0,0,1] neg_hi:[0,0,1]
	v_lshlrev_b32_e32 v24, 16, v64
	v_and_b32_e32 v25, 0xffff0000, v64
	v_lshlrev_b32_e32 v26, 16, v65
	v_and_b32_e32 v27, 0xffff0000, v65
	v_lshlrev_b32_e32 v28, 16, v66
	v_and_b32_e32 v29, 0xffff0000, v66
	v_lshlrev_b32_e32 v30, 16, v67
	v_and_b32_e32 v31, 0xffff0000, v67
	v_cvt_pk_bf16_f32 v40, v32, v33
	v_cvt_pk_bf16_f32 v41, v34, v35
	v_cvt_pk_bf16_f32 v42, v36, v37
	v_cvt_pk_bf16_f32 v43, v38, v39
	v_pk_add_f32 v[8:9], v[8:9], v[24:25] neg_lo:[0,1] neg_hi:[0,1]
	v_pk_add_f32 v[10:11], v[10:11], v[26:27] neg_lo:[0,1] neg_hi:[0,1]
	v_pk_add_f32 v[12:13], v[12:13], v[28:29] neg_lo:[0,1] neg_hi:[0,1]
	v_pk_add_f32 v[14:15], v[14:15], v[30:31] neg_lo:[0,1] neg_hi:[0,1]
	global_store_dwordx4 v1, v[40:43], s[84:85]
	v_add_u32_e32 v6, 2, v2
	v_min_u32_e32 v6, 2, v6
	v_cvt_f32_u32_e32 v6, v6
	v_rcp_f32_e32 v4, v6
	s_waitcnt vmcnt(15)
	v_lshlrev_b32_e32 v16, 16, v72
	v_and_b32_e32 v17, 0xffff0000, v72
	v_lshlrev_b32_e32 v18, 16, v73
	v_and_b32_e32 v19, 0xffff0000, v73
	v_lshlrev_b32_e32 v20, 16, v74
	v_and_b32_e32 v21, 0xffff0000, v74
	v_lshlrev_b32_e32 v22, 16, v75
	v_and_b32_e32 v23, 0xffff0000, v75
	v_pk_add_f32 v[8:9], v[8:9], v[16:17]
	v_pk_add_f32 v[10:11], v[10:11], v[18:19]
	v_pk_add_f32 v[12:13], v[12:13], v[20:21]
	v_pk_add_f32 v[14:15], v[14:15], v[22:23]
	v_pk_fma_f32 v[32:33], v[4:5], v[8:9], v[16:17] op_sel_hi:[0,1,1] neg_lo:[0,0,1] neg_hi:[0,0,1]
	v_pk_fma_f32 v[34:35], v[4:5], v[10:11], v[18:19] op_sel_hi:[0,1,1] neg_lo:[0,0,1] neg_hi:[0,0,1]
	v_pk_fma_f32 v[36:37], v[4:5], v[12:13], v[20:21] op_sel_hi:[0,1,1] neg_lo:[0,0,1] neg_hi:[0,0,1]
	v_pk_fma_f32 v[38:39], v[4:5], v[14:15], v[22:23] op_sel_hi:[0,1,1] neg_lo:[0,0,1] neg_hi:[0,0,1]
	v_lshlrev_b32_e32 v24, 16, v68
	v_and_b32_e32 v25, 0xffff0000, v68
	v_lshlrev_b32_e32 v26, 16, v69
	v_and_b32_e32 v27, 0xffff0000, v69
	v_lshlrev_b32_e32 v28, 16, v70
	v_and_b32_e32 v29, 0xffff0000, v70
	v_lshlrev_b32_e32 v30, 16, v71
	v_and_b32_e32 v31, 0xffff0000, v71
	v_cvt_pk_bf16_f32 v44, v32, v33
	v_cvt_pk_bf16_f32 v45, v34, v35
	v_cvt_pk_bf16_f32 v46, v36, v37
	v_cvt_pk_bf16_f32 v47, v38, v39
	v_pk_add_f32 v[8:9], v[8:9], v[24:25] neg_lo:[0,1] neg_hi:[0,1]
	v_pk_add_f32 v[10:11], v[10:11], v[26:27] neg_lo:[0,1] neg_hi:[0,1]
	v_pk_add_f32 v[12:13], v[12:13], v[28:29] neg_lo:[0,1] neg_hi:[0,1]
	v_pk_add_f32 v[14:15], v[14:15], v[30:31] neg_lo:[0,1] neg_hi:[0,1]
	global_store_dwordx4 v1, v[44:47], s[84:85] offset:256
	v_add_u32_e32 v6, 3, v2
	v_min_u32_e32 v6, 2, v6
	v_cvt_f32_u32_e32 v6, v6
	v_rcp_f32_e32 v4, v6
	s_waitcnt vmcnt(15)
; __device__ __forceinline__ float bf_lo(unsigned w) { return __uint_as_float(w << 16); }
; __device__ __forceinline__ float bf_hi(unsigned w) { return __uint_as_float(w & 0xffff0000u); }
; __device__ __forceinline__ unsigned pk2(float lo, float hi) { return f2bf(lo) | (f2bf(hi) << 16); }
; template <int W> __device__ __forceinline__ v4u pool_window(const bf16* up, int t) {
;     ...
;     for (int j = 0; j < W; ++j) { const float wgt = (j <= t) ? 1.f : 0.f;
;         acc[0] += wgt * pg8::bf_lo(q[j].x); acc[1] += wgt * pg8::bf_hi(q[j].x); acc[2] += wgt * pg8::bf_lo(q[j].y); acc[3] += wgt * pg8::bf_hi(q[j].y);
;         acc[4] += wgt * pg8::bf_lo(q[j].z); acc[5] += wgt * pg8::bf_hi(q[j].z); acc[6] += wgt * pg8::bf_lo(q[j].w); acc[7] += wgt * pg8::bf_hi(q[j].w); }
;     const float inv = 1.0f / (float)((t + 1 < W) ? (t + 1) : W);
;     v4u o;
;     o.x = pk2(acc[0] * inv - pg8::bf_lo(q[0].x), acc[1] * inv - pg8::bf_hi(q[0].x)); o.y = pk2(acc[2] * inv - pg8::bf_lo(q[0].y), acc[3] * inv - pg8::bf_hi(q[0].y));
;     o.z = pk2(acc[4] * inv - pg8::bf_lo(q[0].z), acc[5] * inv - pg8::bf_hi(q[0].z)); o.w = pk2(acc[6] * inv - pg8::bf_lo(q[0].w), acc[7] * inv - pg8::bf_hi(q[0].w));
	v_lshlrev_b32_e32 v16, 16, v76
	v_and_b32_e32 v17, 0xffff0000, v76
	v_lshlrev_b32_e32 v18, 16, v77
	v_and_b32_e32 v19, 0xffff0000, v77
	v_lshlrev_b32_e32 v20, 16, v78
	v_and_b32_e32 v21, 0xffff0000, v78
	v_lshlrev_b32_e32 v22, 16, v79
	v_and_b32_e32 v23, 0xffff0000, v79
	v_pk_add_f32 v[8:9], v[8:9], v[16:17]
	v_pk_add_f32 v[10:11], v[10:11], v[18:19]
	v_pk_add_f32 v[12:13], v[12:13], v[20:21]
	v_pk_add_f32 v[14:15], v[14:15], v[22:23]
	v_pk_fma_f32 v[32:33], v[4:5], v[8:9], v[16:17] op_sel_hi:[0,1,1] neg_lo:[0,0,1] neg_hi:[0,0,1]
	v_pk_fma_f32 v[34:35], v[4:5], v[10:11], v[18:19] op_sel_hi:[0,1,1] neg_lo:[0,0,1] neg_hi:[0,0,1]
	v_pk_fma_f32 v[36:37], v[4:5], v[12:13], v[20:21] op_sel_hi:[0,1,1] neg_lo:[0,0,1] neg_hi:[0,0,1]
	v_pk_fma_f32 v[38:39], v[4:5], v[14:15], v[22:23] op_sel_hi:[0,1,1] neg_lo:[0,0,1] neg_hi:[0,0,1]
	v_lshlrev_b32_e32 v24, 16, v72
	v_and_b32_e32 v25, 0xffff0000, v72
	v_lshlrev_b32_e32 v26, 16, v73
	v_and_b32_e32 v27, 0xffff0000, v73
	v_lshlrev_b32_e32 v28, 16, v74
	v_and_b32_e32 v29, 0xffff0000, v74
	v_lshlrev_b32_e32 v30, 16, v75
	v_and_b32_e32 v31, 0xffff0000, v75
	v_cvt_pk_bf16_f32 v40, v32, v33
	v_cvt_pk_bf16_f32 v41, v34, v35
	v_cvt_pk_bf16_f32 v42, v36, v37
	v_cvt_pk_bf16_f32 v43, v38, v39
	v_pk_add_f32 v[8:9], v[8:9], v[24:25] neg_lo:[0,1] neg_hi:[0,1]
	v_pk_add_f32 v[10:11], v[10:11], v[26:27] neg_lo:[0,1] neg_hi:[0,1]
	v_pk_add_f32 v[12:13], v[12:13], v[28:29] neg_lo:[0,1] neg_hi:[0,1]
	v_pk_add_f32 v[14:15], v[14:15], v[30:31] neg_lo:[0,1] neg_hi:[0,1]
	global_store_dwordx4 v1, v[40:43], s[84:85] offset:512
	v_add_u32_e32 v6, 4, v2
	v_min_u32_e32 v6, 2, v6
	v_cvt_f32_u32_e32 v6, v6
	v_rcp_f32_e32 v4, v6
	s_waitcnt vmcnt(15)
	v_lshlrev_b32_e32 v16, 16, v80
	v_and_b32_e32 v17, 0xffff0000, v80
	v_lshlrev_b32_e32 v18, 16, v81
	v_and_b32_e32 v19, 0xffff0000, v81
	v_lshlrev_b32_e32 v20, 16, v82
	v_and_b32_e32 v21, 0xffff0000, v82
	v_lshlrev_b32_e32 v22, 16, v83
	v_and_b32_e32 v23, 0xffff0000, v83
	v_pk_add_f32 v[8:9], v[8:9], v[16:17]
	v_pk_add_f32 v[10:11], v[10:11], v[18:19]
	v_pk_add_f32 v[12:13], v[12:13], v[20:21]
	v_pk_add_f32 v[14:15], v[14:15], v[22:23]
	v_pk_fma_f32 v[32:33], v[4:5], v[8:9], v[16:17] op_sel_hi:[0,1,1] neg_lo:[0,0,1] neg_hi:[0,0,1]
	v_pk_fma_f32 v[34:35], v[4:5], v[10:11], v[18:19] op_sel_hi:[0,1,1] neg_lo:[0,0,1] neg_hi:[0,0,1]
	v_pk_fma_f32 v[36:37], v[4:5], v[12:13], v[20:21] op_sel_hi:[0,1,1] neg_lo:[0,0,1] neg_hi:[0,0,1]
	v_pk_fma_f32 v[38:39], v[4:5], v[14:15], v[22:23] op_sel_hi:[0,1,1] neg_lo:[0,0,1] neg_hi:[0,0,1]
	v_lshlrev_b32_e32 v24, 16, v76
	v_and_b32_e32 v25, 0xffff0000, v76
	v_lshlrev_b32_e32 v26, 16, v77
	v_and_b32_e32 v27, 0xffff0000, v77
	v_lshlrev_b32_e32 v28, 16, v78
	v_and_b32_e32 v29, 0xffff0000, v78
	v_lshlrev_b32_e32 v30, 16, v79
	v_and_b32_e32 v31, 0xffff0000, v79
	v_cvt_pk_bf16_f32 v44, v32, v33
	v_cvt_pk_bf16_f32 v45, v34, v35
	v_cvt_pk_bf16_f32 v46, v36, v37
	v_cvt_pk_bf16_f32 v47, v38, v39
	v_pk_add_f32 v[8:9], v[8:9], v[24:25] neg_lo:[0,1] neg_hi:[0,1]
	v_pk_add_f32 v[10:11], v[10:11], v[26:27] neg_lo:[0,1] neg_hi:[0,1]
	v_pk_add_f32 v[12:13], v[12:13], v[28:29] neg_lo:[0,1] neg_hi:[0,1]
	v_pk_add_f32 v[14:15], v[14:15], v[30:31] neg_lo:[0,1] neg_hi:[0,1]
	global_store_dwordx4 v1, v[44:47], s[84:85] offset:768
	v_add_u32_e32 v6, 5, v2
	v_min_u32_e32 v6, 2, v6
	v_cvt_f32_u32_e32 v6, v6
	v_rcp_f32_e32 v4, v6
	s_waitcnt vmcnt(15)
	v_lshlrev_b32_e32 v16, 16, v84
	v_and_b32_e32 v17, 0xffff0000, v84
	v_lshlrev_b32_e32 v18, 16, v85
	v_and_b32_e32 v19, 0xffff0000, v85
	v_lshlrev_b32_e32 v20, 16, v86
	v_and_b32_e32 v21, 0xffff0000, v86
	v_lshlrev_b32_e32 v22, 16, v87
	v_and_b32_e32 v23, 0xffff0000, v87
	v_pk_add_f32 v[8:9], v[8:9], v[16:17]
	v_pk_add_f32 v[10:11], v[10:11], v[18:19]
	v_pk_add_f32 v[12:13], v[12:13], v[20:21]
	v_pk_add_f32 v[14:15], v[14:15], v[22:23]
	v_pk_fma_f32 v[32:33], v[4:5], v[8:9], v[16:17] op_sel_hi:[0,1,1] neg_lo:[0,0,1] neg_hi:[0,0,1]
	v_pk_fma_f32 v[34:35], v[4:5], v[10:11], v[18:19] op_sel_hi:[0,1,1] neg_lo:[0,0,1] neg_hi:[0,0,1]
	v_pk_fma_f32 v[36:37], v[4:5], v[12:13], v[20:21] op_sel_hi:[0,1,1] neg_lo:[0,0,1] neg_hi:[0,0,1]
	v_pk_fma_f32 v[38:39], v[4:5], v[14:15], v[22:23] op_sel_hi:[0,1,1] neg_lo:[0,0,1] neg_hi:[0,0,1]
	v_lshlrev_b32_e32 v24, 16, v80
	v_and_b32_e32 v25, 0xffff0000, v80
	v_lshlrev_b32_e32 v26, 16, v81
	v_and_b32_e32 v27, 0xffff0000, v81
	v_lshlrev_b32_e32 v28, 16, v82
	v_and_b32_e32 v29, 0xffff0000, v82
	v_lshlrev_b32_e32 v30, 16, v83
	v_and_b32_e32 v31, 0xffff0000, v83
	v_cvt_pk_bf16_f32 v40, v32, v33
	v_cvt_pk_bf16_f32 v41, v34, v35
	v_cvt_pk_bf16_f32 v42, v36, v37
	v_cvt_pk_bf16_f32 v43, v38, v39
	v_pk_add_f32 v[8:9], v[8:9], v[24:25] neg_lo:[0,1] neg_hi:[0,1]
	v_pk_add_f32 v[10:11], v[10:11], v[26:27] neg_lo:[0,1] neg_hi:[0,1]
	v_pk_add_f32 v[12:13], v[12:13], v[28:29] neg_lo:[0,1] neg_hi:[0,1]
	v_pk_add_f32 v[14:15], v[14:15], v[30:31] neg_lo:[0,1] neg_hi:[0,1]
	global_store_dwordx4 v1, v[40:43], s[84:85] offset:1024
	v_add_u32_e32 v6, 6, v2
	v_min_u32_e32 v6, 2, v6
	v_cvt_f32_u32_e32 v6, v6
	v_rcp_f32_e32 v4, v6
	s_waitcnt vmcnt(15)
; __device__ __forceinline__ float bf_lo(unsigned w) { return __uint_as_float(w << 16); }
; __device__ __forceinline__ float bf_hi(unsigned w) { return __uint_as_float(w & 0xffff0000u); }
; __device__ __forceinline__ unsigned pk2(float lo, float hi) { return f2bf(lo) | (f2bf(hi) << 16); }
; template <int W> __device__ __forceinline__ v4u pool_window(const bf16* up, int t) {
;     ...
;     for (int j = 0; j < W; ++j) { const float wgt = (j <= t) ? 1.f : 0.f;
;         acc[0] += wgt * pg8::bf_lo(q[j].x); acc[1] += wgt * pg8::bf_hi(q[j].x); acc[2] += wgt * pg8::bf_lo(q[j].y); acc[3] += wgt * pg8::bf_hi(q[j].y);
;         acc[4] += wgt * pg8::bf_lo(q[j].z); acc[5] += wgt * pg8::bf_hi(q[j].z); acc[6] += wgt * pg8::bf_lo(q[j].w); acc[7] += wgt * pg8::bf_hi(q[j].w); }
;     const float inv = 1.0f / (float)((t + 1 < W) ? (t + 1) : W);
;     v4u o;
;     o.x = pk2(acc[0] * inv - pg8::bf_lo(q[0].x), acc[1] * inv - pg8::bf_hi(q[0].x)); o.y = pk2(acc[2] * inv - pg8::bf_lo(q[0].y), acc[3] * inv - pg8::bf_hi(q[0].y));
;     o.z = pk2(acc[4] * inv - pg8::bf_lo(q[0].z), acc[5] * inv - pg8::bf_hi(q[0].z)); o.w = pk2(acc[6] * inv - pg8::bf_lo(q[0].w), acc[7] * inv - pg8::bf_hi(q[0].w));
	v_lshlrev_b32_e32 v16, 16, v88
	v_and_b32_e32 v17, 0xffff0000, v88
	v_lshlrev_b32_e32 v18, 16, v89
	v_and_b32_e32 v19, 0xffff0000, v89
	v_lshlrev_b32_e32 v20, 16, v90
	v_and_b32_e32 v21, 0xffff0000, v90
	v_lshlrev_b32_e32 v22, 16, v91
	v_and_b32_e32 v23, 0xffff0000, v91
	v_pk_add_f32 v[8:9], v[8:9], v[16:17]
	v_pk_add_f32 v[10:11], v[10:11], v[18:19]
	v_pk_add_f32 v[12:13], v[12:13], v[20:21]
	v_pk_add_f32 v[14:15], v[14:15], v[22:23]
	v_pk_fma_f32 v[32:33], v[4:5], v[8:9], v[16:17] op_sel_hi:[0,1,1] neg_lo:[0,0,1] neg_hi:[0,0,1]
	v_pk_fma_f32 v[34:35], v[4:5], v[10:11], v[18:19] op_sel_hi:[0,1,1] neg_lo:[0,0,1] neg_hi:[0,0,1]
	v_pk_fma_f32 v[36:37], v[4:5], v[12:13], v[20:21] op_sel_hi:[0,1,1] neg_lo:[0,0,1] neg_hi:[0,0,1]
	v_pk_fma_f32 v[38:39], v[4:5], v[14:15], v[22:23] op_sel_hi:[0,1,1] neg_lo:[0,0,1] neg_hi:[0,0,1]
	v_lshlrev_b32_e32 v24, 16, v84
	v_and_b32_e32 v25, 0xffff0000, v84
	v_lshlrev_b32_e32 v26, 16, v85
	v_and_b32_e32 v27, 0xffff0000, v85
	v_lshlrev_b32_e32 v28, 16, v86
	v_and_b32_e32 v29, 0xffff0000, v86
	v_lshlrev_b32_e32 v30, 16, v87
	v_and_b32_e32 v31, 0xffff0000, v87
	v_cvt_pk_bf16_f32 v44, v32, v33
	v_cvt_pk_bf16_f32 v45, v34, v35
	v_cvt_pk_bf16_f32 v46, v36, v37
	v_cvt_pk_bf16_f32 v47, v38, v39
	v_pk_add_f32 v[8:9], v[8:9], v[24:25] neg_lo:[0,1] neg_hi:[0,1]
	v_pk_add_f32 v[10:11], v[10:11], v[26:27] neg_lo:[0,1] neg_hi:[0,1]
	v_pk_add_f32 v[12:13], v[12:13], v[28:29] neg_lo:[0,1] neg_hi:[0,1]
	v_pk_add_f32 v[14:15], v[14:15], v[30:31] neg_lo:[0,1] neg_hi:[0,1]
	global_store_dwordx4 v1, v[44:47], s[84:85] offset:1280
	v_add_u32_e32 v6, 7, v2
	v_min_u32_e32 v6, 2, v6
	v_cvt_f32_u32_e32 v6, v6
	v_rcp_f32_e32 v4, v6
	s_waitcnt vmcnt(15)
	v_lshlrev_b32_e32 v16, 16, v92
	v_and_b32_e32 v17, 0xffff0000, v92
	v_lshlrev_b32_e32 v18, 16, v93
	v_and_b32_e32 v19, 0xffff0000, v93
	v_lshlrev_b32_e32 v20, 16, v94
	v_and_b32_e32 v21, 0xffff0000, v94
	v_lshlrev_b32_e32 v22, 16, v95
	v_and_b32_e32 v23, 0xffff0000, v95
	v_pk_add_f32 v[8:9], v[8:9], v[16:17]
	v_pk_add_f32 v[10:11], v[10:11], v[18:19]
	v_pk_add_f32 v[12:13], v[12:13], v[20:21]
	v_pk_add_f32 v[14:15], v[14:15], v[22:23]
	v_pk_fma_f32 v[32:33], v[4:5], v[8:9], v[16:17] op_sel_hi:[0,1,1] neg_lo:[0,0,1] neg_hi:[0,0,1]
	v_pk_fma_f32 v[34:35], v[4:5], v[10:11], v[18:19] op_sel_hi:[0,1,1] neg_lo:[0,0,1] neg_hi:[0,0,1]
	v_pk_fma_f32 v[36:37], v[4:5], v[12:13], v[20:21] op_sel_hi:[0,1,1] neg_lo:[0,0,1] neg_hi:[0,0,1]
	v_pk_fma_f32 v[38:39], v[4:5], v[14:15], v[22:23] op_sel_hi:[0,1,1] neg_lo:[0,0,1] neg_hi:[0,0,1]
	v_lshlrev_b32_e32 v24, 16, v88
	v_and_b32_e32 v25, 0xffff0000, v88
	v_lshlrev_b32_e32 v26, 16, v89
	v_and_b32_e32 v27, 0xffff0000, v89
	v_lshlrev_b32_e32 v28, 16, v90
	v_and_b32_e32 v29, 0xffff0000, v90
	v_lshlrev_b32_e32 v30, 16, v91
	v_and_b32_e32 v31, 0xffff0000, v91
	v_cvt_pk_bf16_f32 v40, v32, v33
	v_cvt_pk_bf16_f32 v41, v34, v35
	v_cvt_pk_bf16_f32 v42, v36, v37
	v_cvt_pk_bf16_f32 v43, v38, v39
	v_pk_add_f32 v[8:9], v[8:9], v[24:25] neg_lo:[0,1] neg_hi:[0,1]
	v_pk_add_f32 v[10:11], v[10:11], v[26:27] neg_lo:[0,1] neg_hi:[0,1]
	v_pk_add_f32 v[12:13], v[12:13], v[28:29] neg_lo:[0,1] neg_hi:[0,1]
	v_pk_add_f32 v[14:15], v[14:15], v[30:31] neg_lo:[0,1] neg_hi:[0,1]
	global_store_dwordx4 v1, v[40:43], s[84:85] offset:1536
	v_add_u32_e32 v6, 8, v2
	v_min_u32_e32 v6, 2, v6
	v_cvt_f32_u32_e32 v6, v6
	v_rcp_f32_e32 v4, v6
	s_waitcnt vmcnt(15)
	v_lshlrev_b32_e32 v16, 16, v96
	v_and_b32_e32 v17, 0xffff0000, v96
	v_lshlrev_b32_e32 v18, 16, v97
	v_and_b32_e32 v19, 0xffff0000, v97
	v_lshlrev_b32_e32 v20, 16, v98
	v_and_b32_e32 v21, 0xffff0000, v98
	v_lshlrev_b32_e32 v22, 16, v99
	v_and_b32_e32 v23, 0xffff0000, v99
	v_pk_add_f32 v[8:9], v[8:9], v[16:17]
	v_pk_add_f32 v[10:11], v[10:11], v[18:19]
	v_pk_add_f32 v[12:13], v[12:13], v[20:21]
	v_pk_add_f32 v[14:15], v[14:15], v[22:23]
	v_pk_fma_f32 v[32:33], v[4:5], v[8:9], v[16:17] op_sel_hi:[0,1,1] neg_lo:[0,0,1] neg_hi:[0,0,1]
	v_pk_fma_f32 v[34:35], v[4:5], v[10:11], v[18:19] op_sel_hi:[0,1,1] neg_lo:[0,0,1] neg_hi:[0,0,1]
	v_pk_fma_f32 v[36:37], v[4:5], v[12:13], v[20:21] op_sel_hi:[0,1,1] neg_lo:[0,0,1] neg_hi:[0,0,1]
	v_pk_fma_f32 v[38:39], v[4:5], v[14:15], v[22:23] op_sel_hi:[0,1,1] neg_lo:[0,0,1] neg_hi:[0,0,1]
	v_lshlrev_b32_e32 v24, 16, v92
	v_and_b32_e32 v25, 0xffff0000, v92
	v_lshlrev_b32_e32 v26, 16, v93
	v_and_b32_e32 v27, 0xffff0000, v93
	v_lshlrev_b32_e32 v28, 16, v94
	v_and_b32_e32 v29, 0xffff0000, v94
	v_lshlrev_b32_e32 v30, 16, v95
	v_and_b32_e32 v31, 0xffff0000, v95
	v_cvt_pk_bf16_f32 v44, v32, v33
	v_cvt_pk_bf16_f32 v45, v34, v35
	v_cvt_pk_bf16_f32 v46, v36, v37
	v_cvt_pk_bf16_f32 v47, v38, v39
	v_pk_add_f32 v[8:9], v[8:9], v[24:25] neg_lo:[0,1] neg_hi:[0,1]
	v_pk_add_f32 v[10:11], v[10:11], v[26:27] neg_lo:[0,1] neg_hi:[0,1]
	v_pk_add_f32 v[12:13], v[12:13], v[28:29] neg_lo:[0,1] neg_hi:[0,1]
	v_pk_add_f32 v[14:15], v[14:15], v[30:31] neg_lo:[0,1] neg_hi:[0,1]
	global_store_dwordx4 v1, v[44:47], s[84:85] offset:1792
	v_add_u32_e32 v6, 9, v2
	v_min_u32_e32 v6, 2, v6
	v_cvt_f32_u32_e32 v6, v6
	v_rcp_f32_e32 v4, v6
	s_waitcnt vmcnt(15)
; __device__ __forceinline__ float bf_lo(unsigned w) { return __uint_as_float(w << 16); }
; __device__ __forceinline__ float bf_hi(unsigned w) { return __uint_as_float(w & 0xffff0000u); }
; __device__ __forceinline__ unsigned pk2(float lo, float hi) { return f2bf(lo) | (f2bf(hi) << 16); }
; template <int W> __device__ __forceinline__ v4u pool_window(const bf16* up, int t) {
;     ...
;     for (int j = 0; j < W; ++j) { const float wgt = (j <= t) ? 1.f : 0.f;
;         acc[0] += wgt * pg8::bf_lo(q[j].x); acc[1] += wgt * pg8::bf_hi(q[j].x); acc[2] += wgt * pg8::bf_lo(q[j].y); acc[3] += wgt * pg8::bf_hi(q[j].y);
;         acc[4] += wgt * pg8::bf_lo(q[j].z); acc[5] += wgt * pg8::bf_hi(q[j].z); acc[6] += wgt * pg8::bf_lo(q[j].w); acc[7] += wgt * pg8::bf_hi(q[j].w); }
;     const float inv = 1.0f / (float)((t + 1 < W) ? (t + 1) : W);
;     v4u o;
;     o.x = pk2(acc[0] * inv - pg8::bf_lo(q[0].x), acc[1] * inv - pg8::bf_hi(q[0].x)); o.y = pk2(acc[2] * inv - pg8::bf_lo(q[0].y), acc[3] * inv - pg8::bf_hi(q[0].y));
;     o.z = pk2(acc[4] * inv - pg8::bf_lo(q[0].z), acc[5] * inv - pg8::bf_hi(q[0].z)); o.w = pk2(acc[6] * inv - pg8::bf_lo(q[0].w), acc[7] * inv - pg8::bf_hi(q[0].w));
	v_lshlrev_b32_e32 v16, 16, v100
	v_and_b32_e32 v17, 0xffff0000, v100
	v_lshlrev_b32_e32 v18, 16, v101
	v_and_b32_e32 v19, 0xffff0000, v101
	v_lshlrev_b32_e32 v20, 16, v102
	v_and_b32_e32 v21, 0xffff0000, v102
	v_lshlrev_b32_e32 v22, 16, v103
	v_and_b32_e32 v23, 0xffff0000, v103
	v_pk_add_f32 v[8:9], v[8:9], v[16:17]
	v_pk_add_f32 v[10:11], v[10:11], v[18:19]
	v_pk_add_f32 v[12:13], v[12:13], v[20:21]
	v_pk_add_f32 v[14:15], v[14:15], v[22:23]
	v_pk_fma_f32 v[32:33], v[4:5], v[8:9], v[16:17] op_sel_hi:[0,1,1] neg_lo:[0,0,1] neg_hi:[0,0,1]
	v_pk_fma_f32 v[34:35], v[4:5], v[10:11], v[18:19] op_sel_hi:[0,1,1] neg_lo:[0,0,1] neg_hi:[0,0,1]
	v_pk_fma_f32 v[36:37], v[4:5], v[12:13], v[20:21] op_sel_hi:[0,1,1] neg_lo:[0,0,1] neg_hi:[0,0,1]
	v_pk_fma_f32 v[38:39], v[4:5], v[14:15], v[22:23] op_sel_hi:[0,1,1] neg_lo:[0,0,1] neg_hi:[0,0,1]
	v_lshlrev_b32_e32 v24, 16, v96
	v_and_b32_e32 v25, 0xffff0000, v96
	v_lshlrev_b32_e32 v26, 16, v97
	v_and_b32_e32 v27, 0xffff0000, v97
	v_lshlrev_b32_e32 v28, 16, v98
	v_and_b32_e32 v29, 0xffff0000, v98
	v_lshlrev_b32_e32 v30, 16, v99
	v_and_b32_e32 v31, 0xffff0000, v99
	v_cvt_pk_bf16_f32 v40, v32, v33
	v_cvt_pk_bf16_f32 v41, v34, v35
	v_cvt_pk_bf16_f32 v42, v36, v37
	v_cvt_pk_bf16_f32 v43, v38, v39
	v_pk_add_f32 v[8:9], v[8:9], v[24:25] neg_lo:[0,1] neg_hi:[0,1]
	v_pk_add_f32 v[10:11], v[10:11], v[26:27] neg_lo:[0,1] neg_hi:[0,1]
	v_pk_add_f32 v[12:13], v[12:13], v[28:29] neg_lo:[0,1] neg_hi:[0,1]
	v_pk_add_f32 v[14:15], v[14:15], v[30:31] neg_lo:[0,1] neg_hi:[0,1]
	global_store_dwordx4 v1, v[40:43], s[84:85] offset:2048
	v_add_u32_e32 v6, 10, v2
	v_min_u32_e32 v6, 2, v6
	v_cvt_f32_u32_e32 v6, v6
	v_rcp_f32_e32 v4, v6
	s_waitcnt vmcnt(15)
	v_lshlrev_b32_e32 v16, 16, v104
	v_and_b32_e32 v17, 0xffff0000, v104
	v_lshlrev_b32_e32 v18, 16, v105
	v_and_b32_e32 v19, 0xffff0000, v105
	v_lshlrev_b32_e32 v20, 16, v106
	v_and_b32_e32 v21, 0xffff0000, v106
	v_lshlrev_b32_e32 v22, 16, v107
	v_and_b32_e32 v23, 0xffff0000, v107
	v_pk_add_f32 v[8:9], v[8:9], v[16:17]
	v_pk_add_f32 v[10:11], v[10:11], v[18:19]
	v_pk_add_f32 v[12:13], v[12:13], v[20:21]
	v_pk_add_f32 v[14:15], v[14:15], v[22:23]
	v_pk_fma_f32 v[32:33], v[4:5], v[8:9], v[16:17] op_sel_hi:[0,1,1] neg_lo:[0,0,1] neg_hi:[0,0,1]
	v_pk_fma_f32 v[34:35], v[4:5], v[10:11], v[18:19] op_sel_hi:[0,1,1] neg_lo:[0,0,1] neg_hi:[0,0,1]
	v_pk_fma_f32 v[36:37], v[4:5], v[12:13], v[20:21] op_sel_hi:[0,1,1] neg_lo:[0,0,1] neg_hi:[0,0,1]
	v_pk_fma_f32 v[38:39], v[4:5], v[14:15], v[22:23] op_sel_hi:[0,1,1] neg_lo:[0,0,1] neg_hi:[0,0,1]
	v_lshlrev_b32_e32 v24, 16, v100
	v_and_b32_e32 v25, 0xffff0000, v100
	v_lshlrev_b32_e32 v26, 16, v101
	v_and_b32_e32 v27, 0xffff0000, v101
	v_lshlrev_b32_e32 v28, 16, v102
	v_and_b32_e32 v29, 0xffff0000, v102
	v_lshlrev_b32_e32 v30, 16, v103
	v_and_b32_e32 v31, 0xffff0000, v103
	v_cvt_pk_bf16_f32 v44, v32, v33
	v_cvt_pk_bf16_f32 v45, v34, v35
	v_cvt_pk_bf16_f32 v46, v36, v37
	v_cvt_pk_bf16_f32 v47, v38, v39
	v_pk_add_f32 v[8:9], v[8:9], v[24:25] neg_lo:[0,1] neg_hi:[0,1]
	v_pk_add_f32 v[10:11], v[10:11], v[26:27] neg_lo:[0,1] neg_hi:[0,1]
	v_pk_add_f32 v[12:13], v[12:13], v[28:29] neg_lo:[0,1] neg_hi:[0,1]
	v_pk_add_f32 v[14:15], v[14:15], v[30:31] neg_lo:[0,1] neg_hi:[0,1]
	global_store_dwordx4 v1, v[44:47], s[84:85] offset:2304
	v_add_u32_e32 v6, 11, v2
	v_min_u32_e32 v6, 2, v6
	v_cvt_f32_u32_e32 v6, v6
	v_rcp_f32_e32 v4, v6
	s_waitcnt vmcnt(15)
	v_lshlrev_b32_e32 v16, 16, v108
	v_and_b32_e32 v17, 0xffff0000, v108
	v_lshlrev_b32_e32 v18, 16, v109
	v_and_b32_e32 v19, 0xffff0000, v109
	v_lshlrev_b32_e32 v20, 16, v110
	v_and_b32_e32 v21, 0xffff0000, v110
	v_lshlrev_b32_e32 v22, 16, v111
	v_and_b32_e32 v23, 0xffff0000, v111
	v_pk_add_f32 v[8:9], v[8:9], v[16:17]
	v_pk_add_f32 v[10:11], v[10:11], v[18:19]
	v_pk_add_f32 v[12:13], v[12:13], v[20:21]
	v_pk_add_f32 v[14:15], v[14:15], v[22:23]
	v_pk_fma_f32 v[32:33], v[4:5], v[8:9], v[16:17] op_sel_hi:[0,1,1] neg_lo:[0,0,1] neg_hi:[0,0,1]
	v_pk_fma_f32 v[34:35], v[4:5], v[10:11], v[18:19] op_sel_hi:[0,1,1] neg_lo:[0,0,1] neg_hi:[0,0,1]
	v_pk_fma_f32 v[36:37], v[4:5], v[12:13], v[20:21] op_sel_hi:[0,1,1] neg_lo:[0,0,1] neg_hi:[0,0,1]
	v_pk_fma_f32 v[38:39], v[4:5], v[14:15], v[22:23] op_sel_hi:[0,1,1] neg_lo:[0,0,1] neg_hi:[0,0,1]
	v_lshlrev_b32_e32 v24, 16, v104
	v_and_b32_e32 v25, 0xffff0000, v104
	v_lshlrev_b32_e32 v26, 16, v105
	v_and_b32_e32 v27, 0xffff0000, v105
	v_lshlrev_b32_e32 v28, 16, v106
	v_and_b32_e32 v29, 0xffff0000, v106
	v_lshlrev_b32_e32 v30, 16, v107
	v_and_b32_e32 v31, 0xffff0000, v107
	v_cvt_pk_bf16_f32 v40, v32, v33
	v_cvt_pk_bf16_f32 v41, v34, v35
	v_cvt_pk_bf16_f32 v42, v36, v37
	v_cvt_pk_bf16_f32 v43, v38, v39
	v_pk_add_f32 v[8:9], v[8:9], v[24:25] neg_lo:[0,1] neg_hi:[0,1]
	v_pk_add_f32 v[10:11], v[10:11], v[26:27] neg_lo:[0,1] neg_hi:[0,1]
	v_pk_add_f32 v[12:13], v[12:13], v[28:29] neg_lo:[0,1] neg_hi:[0,1]
	v_pk_add_f32 v[14:15], v[14:15], v[30:31] neg_lo:[0,1] neg_hi:[0,1]
	global_store_dwordx4 v1, v[40:43], s[84:85] offset:2560
	v_add_u32_e32 v6, 12, v2
	v_min_u32_e32 v6, 2, v6
	v_cvt_f32_u32_e32 v6, v6
	v_rcp_f32_e32 v4, v6
	s_waitcnt vmcnt(15)
; __device__ __forceinline__ float bf_lo(unsigned w) { return __uint_as_float(w << 16); }
; __device__ __forceinline__ float bf_hi(unsigned w) { return __uint_as_float(w & 0xffff0000u); }
; __device__ __forceinline__ unsigned pk2(float lo, float hi) { return f2bf(lo) | (f2bf(hi) << 16); }
; template <int W> __device__ __forceinline__ v4u pool_window(const bf16* up, int t) {
;     ...
;     for (int j = 0; j < W; ++j) { const float wgt = (j <= t) ? 1.f : 0.f;
;         acc[0] += wgt * pg8::bf_lo(q[j].x); acc[1] += wgt * pg8::bf_hi(q[j].x); acc[2] += wgt * pg8::bf_lo(q[j].y); acc[3] += wgt * pg8::bf_hi(q[j].y);
;         acc[4] += wgt * pg8::bf_lo(q[j].z); acc[5] += wgt * pg8::bf_hi(q[j].z); acc[6] += wgt * pg8::bf_lo(q[j].w); acc[7] += wgt * pg8::bf_hi(q[j].w); }
;     const float inv = 1.0f / (float)((t + 1 < W) ? (t + 1) : W);
;     v4u o;
;     o.x = pk2(acc[0] * inv - pg8::bf_lo(q[0].x), acc[1] * inv - pg8::bf_hi(q[0].x)); o.y = pk2(acc[2] * inv - pg8::bf_lo(q[0].y), acc[3] * inv - pg8::bf_hi(q[0].y));
;     o.z = pk2(acc[4] * inv - pg8::bf_lo(q[0].z), acc[5] * inv - pg8::bf_hi(q[0].z)); o.w = pk2(acc[6] * inv - pg8::bf_lo(q[0].w), acc[7] * inv - pg8::bf_hi(q[0].w));
	v_lshlrev_b32_e32 v16, 16, v112
	v_and_b32_e32 v17, 0xffff0000, v112
	v_lshlrev_b32_e32 v18, 16, v113
	v_and_b32_e32 v19, 0xffff0000, v113
	v_lshlrev_b32_e32 v20, 16, v114
	v_and_b32_e32 v21, 0xffff0000, v114
	v_lshlrev_b32_e32 v22, 16, v115
	v_and_b32_e32 v23, 0xffff0000, v115
	v_pk_add_f32 v[8:9], v[8:9], v[16:17]
	v_pk_add_f32 v[10:11], v[10:11], v[18:19]
	v_pk_add_f32 v[12:13], v[12:13], v[20:21]
	v_pk_add_f32 v[14:15], v[14:15], v[22:23]
	v_pk_fma_f32 v[32:33], v[4:5], v[8:9], v[16:17] op_sel_hi:[0,1,1] neg_lo:[0,0,1] neg_hi:[0,0,1]
	v_pk_fma_f32 v[34:35], v[4:5], v[10:11], v[18:19] op_sel_hi:[0,1,1] neg_lo:[0,0,1] neg_hi:[0,0,1]
	v_pk_fma_f32 v[36:37], v[4:5], v[12:13], v[20:21] op_sel_hi:[0,1,1] neg_lo:[0,0,1] neg_hi:[0,0,1]
	v_pk_fma_f32 v[38:39], v[4:5], v[14:15], v[22:23] op_sel_hi:[0,1,1] neg_lo:[0,0,1] neg_hi:[0,0,1]
	v_lshlrev_b32_e32 v24, 16, v108
	v_and_b32_e32 v25, 0xffff0000, v108
	v_lshlrev_b32_e32 v26, 16, v109
	v_and_b32_e32 v27, 0xffff0000, v109
	v_lshlrev_b32_e32 v28, 16, v110
	v_and_b32_e32 v29, 0xffff0000, v110
	v_lshlrev_b32_e32 v30, 16, v111
	v_and_b32_e32 v31, 0xffff0000, v111
	v_cvt_pk_bf16_f32 v44, v32, v33
	v_cvt_pk_bf16_f32 v45, v34, v35
	v_cvt_pk_bf16_f32 v46, v36, v37
	v_cvt_pk_bf16_f32 v47, v38, v39
	v_pk_add_f32 v[8:9], v[8:9], v[24:25] neg_lo:[0,1] neg_hi:[0,1]
	v_pk_add_f32 v[10:11], v[10:11], v[26:27] neg_lo:[0,1] neg_hi:[0,1]
	v_pk_add_f32 v[12:13], v[12:13], v[28:29] neg_lo:[0,1] neg_hi:[0,1]
	v_pk_add_f32 v[14:15], v[14:15], v[30:31] neg_lo:[0,1] neg_hi:[0,1]
	global_store_dwordx4 v1, v[44:47], s[84:85] offset:2816
	v_add_u32_e32 v6, 13, v2
	v_min_u32_e32 v6, 2, v6
	v_cvt_f32_u32_e32 v6, v6
	v_rcp_f32_e32 v4, v6
	s_waitcnt vmcnt(15)
	v_lshlrev_b32_e32 v16, 16, v116
	v_and_b32_e32 v17, 0xffff0000, v116
	v_lshlrev_b32_e32 v18, 16, v117
	v_and_b32_e32 v19, 0xffff0000, v117
	v_lshlrev_b32_e32 v20, 16, v118
	v_and_b32_e32 v21, 0xffff0000, v118
	v_lshlrev_b32_e32 v22, 16, v119
	v_and_b32_e32 v23, 0xffff0000, v119
	v_pk_add_f32 v[8:9], v[8:9], v[16:17]
	v_pk_add_f32 v[10:11], v[10:11], v[18:19]
	v_pk_add_f32 v[12:13], v[12:13], v[20:21]
	v_pk_add_f32 v[14:15], v[14:15], v[22:23]
	v_pk_fma_f32 v[32:33], v[4:5], v[8:9], v[16:17] op_sel_hi:[0,1,1] neg_lo:[0,0,1] neg_hi:[0,0,1]
	v_pk_fma_f32 v[34:35], v[4:5], v[10:11], v[18:19] op_sel_hi:[0,1,1] neg_lo:[0,0,1] neg_hi:[0,0,1]
	v_pk_fma_f32 v[36:37], v[4:5], v[12:13], v[20:21] op_sel_hi:[0,1,1] neg_lo:[0,0,1] neg_hi:[0,0,1]
	v_pk_fma_f32 v[38:39], v[4:5], v[14:15], v[22:23] op_sel_hi:[0,1,1] neg_lo:[0,0,1] neg_hi:[0,0,1]
	v_lshlrev_b32_e32 v24, 16, v112
	v_and_b32_e32 v25, 0xffff0000, v112
	v_lshlrev_b32_e32 v26, 16, v113
	v_and_b32_e32 v27, 0xffff0000, v113
	v_lshlrev_b32_e32 v28, 16, v114
	v_and_b32_e32 v29, 0xffff0000, v114
	v_lshlrev_b32_e32 v30, 16, v115
	v_and_b32_e32 v31, 0xffff0000, v115
	v_cvt_pk_bf16_f32 v40, v32, v33
	v_cvt_pk_bf16_f32 v41, v34, v35
	v_cvt_pk_bf16_f32 v42, v36, v37
	v_cvt_pk_bf16_f32 v43, v38, v39
	v_pk_add_f32 v[8:9], v[8:9], v[24:25] neg_lo:[0,1] neg_hi:[0,1]
	v_pk_add_f32 v[10:11], v[10:11], v[26:27] neg_lo:[0,1] neg_hi:[0,1]
	v_pk_add_f32 v[12:13], v[12:13], v[28:29] neg_lo:[0,1] neg_hi:[0,1]
	v_pk_add_f32 v[14:15], v[14:15], v[30:31] neg_lo:[0,1] neg_hi:[0,1]
	global_store_dwordx4 v1, v[40:43], s[84:85] offset:3072
	v_add_u32_e32 v6, 14, v2
	v_min_u32_e32 v6, 2, v6
	v_cvt_f32_u32_e32 v6, v6
	v_rcp_f32_e32 v4, v6
	s_waitcnt vmcnt(15)
	v_lshlrev_b32_e32 v16, 16, v120
	v_and_b32_e32 v17, 0xffff0000, v120
	v_lshlrev_b32_e32 v18, 16, v121
	v_and_b32_e32 v19, 0xffff0000, v121
	v_lshlrev_b32_e32 v20, 16, v122
	v_and_b32_e32 v21, 0xffff0000, v122
	v_lshlrev_b32_e32 v22, 16, v123
	v_and_b32_e32 v23, 0xffff0000, v123
	v_pk_add_f32 v[8:9], v[8:9], v[16:17]
	v_pk_add_f32 v[10:11], v[10:11], v[18:19]
	v_pk_add_f32 v[12:13], v[12:13], v[20:21]
	v_pk_add_f32 v[14:15], v[14:15], v[22:23]
	v_pk_fma_f32 v[32:33], v[4:5], v[8:9], v[16:17] op_sel_hi:[0,1,1] neg_lo:[0,0,1] neg_hi:[0,0,1]
	v_pk_fma_f32 v[34:35], v[4:5], v[10:11], v[18:19] op_sel_hi:[0,1,1] neg_lo:[0,0,1] neg_hi:[0,0,1]
	v_pk_fma_f32 v[36:37], v[4:5], v[12:13], v[20:21] op_sel_hi:[0,1,1] neg_lo:[0,0,1] neg_hi:[0,0,1]
	v_pk_fma_f32 v[38:39], v[4:5], v[14:15], v[22:23] op_sel_hi:[0,1,1] neg_lo:[0,0,1] neg_hi:[0,0,1]
	v_lshlrev_b32_e32 v24, 16, v116
	v_and_b32_e32 v25, 0xffff0000, v116
	v_lshlrev_b32_e32 v26, 16, v117
	v_and_b32_e32 v27, 0xffff0000, v117
	v_lshlrev_b32_e32 v28, 16, v118
	v_and_b32_e32 v29, 0xffff0000, v118
	v_lshlrev_b32_e32 v30, 16, v119
	v_and_b32_e32 v31, 0xffff0000, v119
	v_cvt_pk_bf16_f32 v44, v32, v33
	v_cvt_pk_bf16_f32 v45, v34, v35
	v_cvt_pk_bf16_f32 v46, v36, v37
	v_cvt_pk_bf16_f32 v47, v38, v39
	v_pk_add_f32 v[8:9], v[8:9], v[24:25] neg_lo:[0,1] neg_hi:[0,1]
	v_pk_add_f32 v[10:11], v[10:11], v[26:27] neg_lo:[0,1] neg_hi:[0,1]
	v_pk_add_f32 v[12:13], v[12:13], v[28:29] neg_lo:[0,1] neg_hi:[0,1]
	v_pk_add_f32 v[14:15], v[14:15], v[30:31] neg_lo:[0,1] neg_hi:[0,1]
	global_store_dwordx4 v1, v[44:47], s[84:85] offset:3328
	v_add_u32_e32 v6, 15, v2
	v_min_u32_e32 v6, 2, v6
	v_cvt_f32_u32_e32 v6, v6
	v_rcp_f32_e32 v4, v6
	s_waitcnt vmcnt(15)
; __device__ __forceinline__ float bf_lo(unsigned w) { return __uint_as_float(w << 16); }
; __device__ __forceinline__ float bf_hi(unsigned w) { return __uint_as_float(w & 0xffff0000u); }
; __device__ __forceinline__ unsigned pk2(float lo, float hi) { return f2bf(lo) | (f2bf(hi) << 16); }
; template <int W> __device__ __forceinline__ v4u pool_window(const bf16* up, int t) {
;     ...
;     for (int j = 0; j < W; ++j) { const float wgt = (j <= t) ? 1.f : 0.f;
;         acc[0] += wgt * pg8::bf_lo(q[j].x); acc[1] += wgt * pg8::bf_hi(q[j].x); acc[2] += wgt * pg8::bf_lo(q[j].y); acc[3] += wgt * pg8::bf_hi(q[j].y);
;         acc[4] += wgt * pg8::bf_lo(q[j].z); acc[5] += wgt * pg8::bf_hi(q[j].z); acc[6] += wgt * pg8::bf_lo(q[j].w); acc[7] += wgt * pg8::bf_hi(q[j].w); }
;     const float inv = 1.0f / (float)((t + 1 < W) ? (t + 1) : W);
;     v4u o;
;     o.x = pk2(acc[0] * inv - pg8::bf_lo(q[0].x), acc[1] * inv - pg8::bf_hi(q[0].x)); o.y = pk2(acc[2] * inv - pg8::bf_lo(q[0].y), acc[3] * inv - pg8::bf_hi(q[0].y));
;     o.z = pk2(acc[4] * inv - pg8::bf_lo(q[0].z), acc[5] * inv - pg8::bf_hi(q[0].z)); o.w = pk2(acc[6] * inv - pg8::bf_lo(q[0].w), acc[7] * inv - pg8::bf_hi(q[0].w));
; __global__ void __launch_bounds__(NWAVES * 64, 2) hybrid_fwd(Args a) {
;     ...
;         const float sa = wave_sum(a.lq1[lane] * a.lk1[lane]), sb = wave_sum(a.lq2[lane] * a.lk2[lane]);
;         const float lam = expf(sa) - expf(sb) + 0.2f;
;         for (int pu = vcu; pu < BATCH * NH * 8; pu += G) {
	v_lshlrev_b32_e32 v16, 16, v124
	v_and_b32_e32 v17, 0xffff0000, v124
	v_lshlrev_b32_e32 v18, 16, v125
	v_and_b32_e32 v19, 0xffff0000, v125
	v_lshlrev_b32_e32 v20, 16, v126
	v_and_b32_e32 v21, 0xffff0000, v126
	v_lshlrev_b32_e32 v22, 16, v127
	v_and_b32_e32 v23, 0xffff0000, v127
	v_pk_add_f32 v[8:9], v[8:9], v[16:17]
	v_pk_add_f32 v[10:11], v[10:11], v[18:19]
	v_pk_add_f32 v[12:13], v[12:13], v[20:21]
	v_pk_add_f32 v[14:15], v[14:15], v[22:23]
	v_pk_fma_f32 v[32:33], v[4:5], v[8:9], v[16:17] op_sel_hi:[0,1,1] neg_lo:[0,0,1] neg_hi:[0,0,1]
	v_pk_fma_f32 v[34:35], v[4:5], v[10:11], v[18:19] op_sel_hi:[0,1,1] neg_lo:[0,0,1] neg_hi:[0,0,1]
	v_pk_fma_f32 v[36:37], v[4:5], v[12:13], v[20:21] op_sel_hi:[0,1,1] neg_lo:[0,0,1] neg_hi:[0,0,1]
	v_pk_fma_f32 v[38:39], v[4:5], v[14:15], v[22:23] op_sel_hi:[0,1,1] neg_lo:[0,0,1] neg_hi:[0,0,1]
	v_lshlrev_b32_e32 v24, 16, v120
	v_and_b32_e32 v25, 0xffff0000, v120
	v_lshlrev_b32_e32 v26, 16, v121
	v_and_b32_e32 v27, 0xffff0000, v121
	v_lshlrev_b32_e32 v28, 16, v122
	v_and_b32_e32 v29, 0xffff0000, v122
	v_lshlrev_b32_e32 v30, 16, v123
	v_and_b32_e32 v31, 0xffff0000, v123
	v_cvt_pk_bf16_f32 v40, v32, v33
	v_cvt_pk_bf16_f32 v41, v34, v35
	v_cvt_pk_bf16_f32 v42, v36, v37
	v_cvt_pk_bf16_f32 v43, v38, v39
	v_pk_add_f32 v[8:9], v[8:9], v[24:25] neg_lo:[0,1] neg_hi:[0,1]
	v_pk_add_f32 v[10:11], v[10:11], v[26:27] neg_lo:[0,1] neg_hi:[0,1]
	v_pk_add_f32 v[12:13], v[12:13], v[28:29] neg_lo:[0,1] neg_hi:[0,1]
	v_pk_add_f32 v[14:15], v[14:15], v[30:31] neg_lo:[0,1] neg_hi:[0,1]
	global_store_dwordx4 v1, v[40:43], s[84:85] offset:3584
	v_add_u32_e32 v6, 16, v2
	v_min_u32_e32 v6, 2, v6
	v_cvt_f32_u32_e32 v6, v6
	v_rcp_f32_e32 v4, v6
	s_waitcnt vmcnt(15)
	v_lshlrev_b32_e32 v16, 16, v128
	v_and_b32_e32 v17, 0xffff0000, v128
	v_lshlrev_b32_e32 v18, 16, v129
	v_and_b32_e32 v19, 0xffff0000, v129
	v_lshlrev_b32_e32 v20, 16, v130
	v_and_b32_e32 v21, 0xffff0000, v130
	v_lshlrev_b32_e32 v22, 16, v131
	v_and_b32_e32 v23, 0xffff0000, v131
	v_pk_add_f32 v[8:9], v[8:9], v[16:17]
	v_pk_add_f32 v[10:11], v[10:11], v[18:19]
	v_pk_add_f32 v[12:13], v[12:13], v[20:21]
	v_pk_add_f32 v[14:15], v[14:15], v[22:23]
	v_pk_fma_f32 v[32:33], v[4:5], v[8:9], v[16:17] op_sel_hi:[0,1,1] neg_lo:[0,0,1] neg_hi:[0,0,1]
	v_pk_fma_f32 v[34:35], v[4:5], v[10:11], v[18:19] op_sel_hi:[0,1,1] neg_lo:[0,0,1] neg_hi:[0,0,1]
	v_pk_fma_f32 v[36:37], v[4:5], v[12:13], v[20:21] op_sel_hi:[0,1,1] neg_lo:[0,0,1] neg_hi:[0,0,1]
	v_pk_fma_f32 v[38:39], v[4:5], v[14:15], v[22:23] op_sel_hi:[0,1,1] neg_lo:[0,0,1] neg_hi:[0,0,1]
	v_cvt_pk_bf16_f32 v44, v32, v33
	v_cvt_pk_bf16_f32 v45, v34, v35
	v_cvt_pk_bf16_f32 v46, v36, v37
	v_cvt_pk_bf16_f32 v47, v38, v39
	global_store_dwordx4 v1, v[44:47], s[84:85] offset:3840
	v_add_u32_e32 v0, 0x4000, v0
	v_add_u32_e32 v1, 0x1000, v1
	v_add_u32_e32 v2, 16, v2
	s_add_i32 s4, s4, 1
	s_cmp_lt_u32 s4, 2
	s_cbranch_scc1 .Lpool_pass_w2
	s_branch .Lpool_done
.Lpool_done:
.LBB0_280:
	s_nop 0
	v_lshlrev_b32_e32 v0, 2, v50
	global_load_dword v1, v0, s[64:65]
	global_load_dword v2, v0, s[66:67]
	global_load_dword v3, v0, s[68:69]
	s_nop 0
	global_load_dword v0, v0, s[70:71]
	v_writelane_b32 v255, s94, 8
	s_cmpk_gt_i32 s78, 0x3ff
	s_waitcnt vmcnt(2)
	v_mul_f32_e32 v4, v1, v2
	ds_swizzle_b32 v4, v4 offset:swizzle(SWAP,1)
	s_waitcnt vmcnt(0)
	v_mul_f32_e32 v5, v3, v0
	ds_swizzle_b32 v5, v5 offset:swizzle(SWAP,1)
	v_writelane_b32 v255, s95, 9
	v_writelane_b32 v255, s92, 10
	s_waitcnt lgkmcnt(1)
	v_fmac_f32_e32 v4, v1, v2
	s_waitcnt lgkmcnt(0)
	v_fmac_f32_e32 v5, v3, v0
	ds_swizzle_b32 v0, v4 offset:swizzle(SWAP,2)
	ds_swizzle_b32 v1, v5 offset:swizzle(SWAP,2)
	v_writelane_b32 v255, s93, 11
	v_writelane_b32 v255, s90, 12
	s_waitcnt lgkmcnt(1)
	v_add_f32_e32 v0, v4, v0
	s_waitcnt lgkmcnt(0)
	v_add_f32_e32 v1, v5, v1
	ds_swizzle_b32 v2, v0 offset:swizzle(SWAP,4)
	ds_swizzle_b32 v3, v1 offset:swizzle(SWAP,4)
	v_writelane_b32 v255, s91, 13
	v_writelane_b32 v255, s80, 14
	s_waitcnt lgkmcnt(1)
	v_add_f32_e32 v0, v0, v2
	s_waitcnt lgkmcnt(0)
	v_add_f32_e32 v1, v1, v3
	ds_swizzle_b32 v2, v0 offset:swizzle(SWAP,8)
	ds_swizzle_b32 v3, v1 offset:swizzle(SWAP,8)
	v_writelane_b32 v255, s81, 15
	v_writelane_b32 v255, s78, 16
	s_waitcnt lgkmcnt(1)
	v_add_f32_e32 v0, v0, v2
	s_waitcnt lgkmcnt(0)
	v_add_f32_e32 v1, v1, v3
	ds_swizzle_b32 v2, v0 offset:swizzle(SWAP,16)
	ds_swizzle_b32 v3, v1 offset:swizzle(SWAP,16)
	s_waitcnt lgkmcnt(1)
	v_add_f32_e32 v2, v0, v2
	s_waitcnt lgkmcnt(0)
	v_add_f32_e32 v0, v1, v3
	v_mov_b32_e32 v3, v2
	v_mov_b32_e32 v1, v0
	s_nop 0
	v_permlane32_swap_b32_e32 v2, v3
	v_permlane32_swap_b32_e32 v0, v1
	s_cbranch_scc1 .LBB0_354
	v_add_f32_e32 v2, v2, v3
	s_mov_b32 s0, 0x3fb8aa3b
	v_mul_f32_e32 v3, 0x3fb8aa3b, v2
	v_fma_f32 v4, v2, s0, -v3
	v_rndne_f32_e32 v5, v3
	v_fmac_f32_e32 v4, 0x32a5705f, v2
	v_sub_f32_e32 v3, v3, v5
	v_add_f32_e32 v3, v3, v4
	v_exp_f32_e32 v3, v3
	v_cvt_i32_f32_e32 v4, v5
	v_add_f32_e32 v0, v0, v1
	s_mov_b32 s1, 0xc2ce8ed0
	v_cmp_ngt_f32_e32 vcc, s1, v2
	v_ldexp_f32 v1, v3, v4
	v_mul_f32_e32 v3, 0x3fb8aa3b, v0
	v_fma_f32 v4, v0, s0, -v3
	v_rndne_f32_e32 v5, v3
	v_fmac_f32_e32 v4, 0x32a5705f, v0
	v_sub_f32_e32 v3, v3, v5
	v_add_f32_e32 v3, v3, v4
	v_exp_f32_e32 v3, v3
	v_cvt_i32_f32_e32 v4, v5
	s_mov_b32 s2, 0x42b17218
	v_cndmask_b32_e32 v1, 0, v1, vcc
	v_mov_b32_e32 v5, 0x7f800000
	v_cmp_nlt_f32_e32 vcc, s2, v2
	v_ldexp_f32 v2, v3, v4
	s_movk_i32 s97, 0xf0
	v_cndmask_b32_e32 v1, v5, v1, vcc
	v_cmp_ngt_f32_e32 vcc, s1, v0
	s_movk_i32 s98, 0x80
	s_add_i32 s99, 0, 0x11000
	v_cndmask_b32_e32 v2, 0, v2, vcc
	v_cmp_nlt_f32_e32 vcc, s2, v0
	s_mov_b32 s31, 0xff800000
	s_mov_b32 s58, 0x47800000
	v_cndmask_b32_e32 v0, v5, v2, vcc
	v_sub_f32_e32 v0, v1, v0
	v_add_f32_e32 v193, 0x3e4ccccd, v0
	v_mov_b32_e32 v1, 0
	v_mov_b32_e32 v194, 0x358637bd
	v_mov_b32_e32 v17, 0xff800000
	v_readlane_b32 s59, v255, 16
	s_branch .LBB0_283
